# cross-row wave reductions (xor 16 / xor 32) in the in-projection and residual epilogues done with v_permlane16_swap / v_permlane32_swap instead of ds_bpermute LDS round trips (bit-identical sums)
# speedup vs baseline: 1.0200x; 1.0200x over previous
; __device__ __forceinline__ unsigned cvt_pk_bf16(float lo, float hi) { unsigned r; asm volatile("v_cvt_pk_bf16_f32 %0, %1, %2" : "=v"(r) : "v"(lo), "v"(hi)); return r; }
; __device__ __forceinline__ float gelu_t(float x) { const float z = 1.5957691216f * (x + 0.044715f * x * x * x); return x * sigm(z); }
; #define EPI_FOR_ROWS() _Pragma("unroll") for (int ai = 0; ai < 2; ++ai) _Pragma("unroll") for (int m = 0; m < 4; ++m)
; __device__ __forceinline__ float row_rstd(const float* ssq, int row, int fq) {
;     const f32x4 q = *(const f32x4*)(ssq + (size_t)row * 16 + 4 * fq); float s = (q[0] + q[1]) + (q[2] + q[3]);
;     s += __shfl_xor(s, 16); s += __shfl_xor(s, 32); return rsqrtf(s * (1.0f / 1024.0f) + EPS);
; }
;     __device__ __forceinline__ void operator()(const f32x4 (&acc)[2][2][4][2], const Unit& u, int wr, int wc, int fr, int fq) const {
;         EPI_ROWCOL();
;         EPI_FOR_ROWS() {
;             const int row = row0 + ai * 128 + m * 16; const float rs = row_rstd(ssq, row, fq);
; #pragma unroll
;             for (int bj = 0; bj < 2; ++bj) { const int col = col0 + bj * 128; f32x4 v0 = acc[ai][bj][m][0] * rs, v1 = acc[ai][bj][m][1] * rs;
;                 if (u.pn >= 2) {
; #pragma unroll
;                     for (int e = 0; e < 4; ++e) { v0[e] = gelu_t(v0[e]); v1[e] = gelu_t(v1[e]); } }
;                 u32x4 w; w.x = cvt_pk_bf16(v0[0], v0[1]); w.y = cvt_pk_bf16(v0[2], v0[3]); w.z = cvt_pk_bf16(v1[0], v1[1]); w.w = cvt_pk_bf16(v1[2], v1[3]);
;                 *(u32x4*)(proj + (size_t)row * 1536 + col) = w; }
.LBB0_236:
	v_lshl_add_u32 v130, s57, 8, v140
	v_ashrrev_i32_e32 v131, 31, v130
	v_lshlrev_b64 v[132:133], 6, v[130:131]
	v_lshl_add_u64 v[132:133], v[128:129], 0, v[132:133]
	global_load_dwordx4 v[154:157], v[132:133], off
	global_load_dwordx4 v[166:169], v[132:133], off offset:1024
	global_load_dwordx4 v[178:181], v[132:133], off offset:2048
	global_load_dwordx4 v[182:185], v[132:133], off offset:3072
	v_mov_b32_e32 v188, 0x2000
	v_mov_b32_e32 v189, 0
	v_lshl_add_u64 v[186:187], v[132:133], 0, v[188:189]
	global_load_dwordx4 v[186:189], v[186:187], off
	v_mov_b32_e32 v192, 0x2400
	v_mov_b32_e32 v193, 0
	v_lshl_add_u64 v[190:191], v[132:133], 0, v[192:193]
	global_load_dwordx4 v[190:193], v[190:191], off
	v_mov_b32_e32 v196, 0x2800
	v_mov_b32_e32 v197, 0
	v_lshl_add_u64 v[194:195], v[132:133], 0, v[196:197]
	global_load_dwordx4 v[194:197], v[194:195], off
	v_mov_b32_e32 v200, 0x2c00
	v_mov_b32_e32 v201, 0
	v_lshl_add_u64 v[198:199], v[132:133], 0, v[200:201]
	global_load_dwordx4 v[198:201], v[198:199], off
	s_waitcnt vmcnt(0)
	v_mov_b32_e32 v132, v154
	v_mov_b32_e32 v133, v155
	v_mov_b32_e32 v134, v156
	v_mov_b32_e32 v135, v157
	v_and_b32_e32 v147, 64, v207
	v_xor_b32_e32 v131, 16, v207
	v_add_u32_e32 v147, 64, v147
	v_cmp_lt_i32_e32 vcc, v131, v147
	s_cmp_gt_i32 s56, 1
	v_readlane_b32 s60, v252, 25
	v_cndmask_b32_e32 v131, v207, v131, vcc
	v_lshlrev_b32_e32 v131, 2, v131
	v_readlane_b32 s62, v252, 27
	v_readlane_b32 s58, v252, 21
	s_cselect_b64 s[4:5], -1, 0
	s_cmp_lt_i32 s56, 2
	v_readlane_b32 s61, v252, 26
	v_readlane_b32 s63, v252, 28
	v_readlane_b32 s59, v252, 22
	v_mov_b32_e32 v148, v133
	v_mov_b32_e32 v149, v134
	v_mov_b32_e32 v133, v135
	v_pk_add_f32 v[132:133], v[148:149], v[132:133]
	v_xor_b32_e32 v134, 32, v207
	v_add_f32_e32 v132, v132, v133
	v_mov_b32_e32 v133, v132
	v_mov_b32_e32 v158, v132
	s_nop 1
	v_permlane16_swap_b32_e32 v133, v158
	v_cmp_lt_i32_e32 vcc, v134, v147
	s_waitcnt lgkmcnt(0)
	v_add_f32_e32 v132, v133, v158
	v_cndmask_b32_e32 v134, v207, v134, vcc
	v_lshlrev_b32_e32 v147, 2, v134
	v_mov_b32_e32 v133, v132
	v_mov_b32_e32 v158, v132
	s_nop 1
	v_permlane32_swap_b32_e32 v133, v158
	s_waitcnt lgkmcnt(0)
	v_add_f32_e32 v132, v133, v158
	v_fmamk_f32 v132, v132, 0x3a800000, v208
	v_mul_f32_e32 v133, 0x4b800000, v132
	v_cmp_gt_f32_e32 vcc, s44, v132
	s_nop 1
	v_cndmask_b32_e32 v132, v132, v133, vcc
	v_rsq_f32_e32 v132, v132
	s_nop 0
	v_mul_f32_e32 v133, 0x45800000, v132
	v_cndmask_b32_e32 v132, v132, v133, vcc
	v_pk_mul_f32 v[126:127], v[126:127], v[132:133] op_sel_hi:[1,0]
	v_pk_mul_f32 v[124:125], v[124:125], v[132:133] op_sel_hi:[1,0]
	v_pk_mul_f32 v[122:123], v[122:123], v[132:133] op_sel_hi:[1,0]
	v_pk_mul_f32 v[134:135], v[120:121], v[132:133] op_sel_hi:[1,0]
	s_cbranch_scc1 .LBB0_238
	v_mul_f32_e32 v121, 0x3d372713, v134
	v_mul_f32_e32 v121, v134, v121
	v_fma_f32 v121, v134, v121, v134
	v_mul_f32_e32 v121, 0x3fcc422a, v121
	v_mul_f32_e32 v121, 0xbfb8aa3b, v121
	v_exp_f32_e32 v121, v121
	v_mov_b32_e32 v133, v125
	v_mov_b32_e32 v149, v135
	v_mul_f32_e32 v120, 0x3d372713, v124
	v_add_f32_e32 v121, 1.0, v121
	v_rcp_f32_e32 v148, v121
	v_mul_f32_e32 v121, 0x3d372713, v125
	v_mul_f32_e32 v121, v125, v121
	v_fmac_f32_e32 v133, v133, v121
	v_mul_f32_e32 v121, 0x3fcc422a, v133
	v_mul_f32_e32 v133, 0x3d372713, v135
	v_mul_f32_e32 v133, v135, v133
	v_fmac_f32_e32 v149, v149, v133
	v_mul_f32_e32 v133, 0x3fcc422a, v149
	v_mul_f32_e32 v133, 0xbfb8aa3b, v133
	v_exp_f32_e32 v133, v133
	v_mul_f32_e32 v120, v124, v120
	v_fma_f32 v120, v124, v120, v124
	v_mul_f32_e32 v120, 0x3fcc422a, v120
	v_add_f32_e32 v133, 1.0, v133
	v_rcp_f32_e32 v149, v133
	v_mul_f32_e32 v133, 0x3d372713, v126
	v_mul_f32_e32 v133, v126, v133
	v_fma_f32 v133, v126, v133, v126
	v_mul_f32_e32 v133, 0x3fcc422a, v133
	v_mul_f32_e32 v133, 0xbfb8aa3b, v133
	v_exp_f32_e32 v133, v133
	v_mul_f32_e32 v120, 0xbfb8aa3b, v120
	v_mul_f32_e32 v121, 0xbfb8aa3b, v121
	v_exp_f32_e32 v120, v120
	v_add_f32_e32 v133, 1.0, v133
	v_rcp_f32_e32 v150, v133
	v_mul_f32_e32 v133, 0x3d372713, v122
	v_exp_f32_e32 v121, v121
	v_mul_f32_e32 v133, v122, v133
	v_fma_f32 v133, v122, v133, v122
	v_mul_f32_e32 v133, 0x3fcc422a, v133
	v_mul_f32_e32 v133, 0xbfb8aa3b, v133
	v_add_f32_e32 v120, 1.0, v120
	v_add_f32_e32 v121, 1.0, v121
	v_exp_f32_e32 v133, v133
	v_rcp_f32_e32 v120, v120
	v_rcp_f32_e32 v121, v121
	v_pk_mul_f32 v[134:135], v[134:135], v[148:149]
	v_add_f32_e32 v133, 1.0, v133
	v_rcp_f32_e32 v152, v133
	v_mul_f32_e32 v133, 0x3d372713, v127
	v_pk_mul_f32 v[124:125], v[124:125], v[120:121]
	v_mul_f32_e32 v120, 0x3d372713, v123
	v_mul_f32_e32 v133, v127, v133
	v_mul_f32_e32 v120, v123, v120
	v_fma_f32 v133, v127, v133, v127
	v_fma_f32 v120, v123, v120, v123
	v_mul_f32_e32 v133, 0x3fcc422a, v133
	v_mul_f32_e32 v120, 0x3fcc422a, v120
	v_mul_f32_e32 v133, 0xbfb8aa3b, v133
	v_mul_f32_e32 v120, 0xbfb8aa3b, v120
	v_exp_f32_e32 v133, v133
	v_exp_f32_e32 v120, v120
	v_add_f32_e32 v133, 1.0, v133
	v_add_f32_e32 v120, 1.0, v120
	v_rcp_f32_e32 v151, v133
	v_rcp_f32_e32 v153, v120
	v_pk_mul_f32 v[126:127], v[126:127], v[150:151]
	v_pk_mul_f32 v[122:123], v[122:123], v[152:153]

; __device__ __forceinline__ unsigned cvt_pk_bf16(float lo, float hi) { unsigned r; asm volatile("v_cvt_pk_bf16_f32 %0, %1, %2" : "=v"(r) : "v"(lo), "v"(hi)); return r; }
; __device__ __forceinline__ float gelu_t(float x) { const float z = 1.5957691216f * (x + 0.044715f * x * x * x); return x * sigm(z); }
; #define EPI_FOR_ROWS() _Pragma("unroll") for (int ai = 0; ai < 2; ++ai) _Pragma("unroll") for (int m = 0; m < 4; ++m)
; __device__ __forceinline__ float row_rstd(const float* ssq, int row, int fq) {
;     const f32x4 q = *(const f32x4*)(ssq + (size_t)row * 16 + 4 * fq); float s = (q[0] + q[1]) + (q[2] + q[3]);
;     s += __shfl_xor(s, 16); s += __shfl_xor(s, 32); return rsqrtf(s * (1.0f / 1024.0f) + EPS);
; }
;     __device__ __forceinline__ void operator()(const f32x4 (&acc)[2][2][4][2], const Unit& u, int wr, int wc, int fr, int fq) const {
;         EPI_ROWCOL();
;         EPI_FOR_ROWS() {
;             const int row = row0 + ai * 128 + m * 16; const float rs = row_rstd(ssq, row, fq);
; #pragma unroll
;             for (int bj = 0; bj < 2; ++bj) { const int col = col0 + bj * 128; f32x4 v0 = acc[ai][bj][m][0] * rs, v1 = acc[ai][bj][m][1] * rs;
;                 if (u.pn >= 2) {
; #pragma unroll
;                     for (int e = 0; e < 4; ++e) { v0[e] = gelu_t(v0[e]); v1[e] = gelu_t(v1[e]); } }
;                 u32x4 w; w.x = cvt_pk_bf16(v0[0], v0[1]); w.y = cvt_pk_bf16(v0[2], v0[3]); w.z = cvt_pk_bf16(v1[0], v1[1]); w.w = cvt_pk_bf16(v1[2], v1[3]);
;                 *(u32x4*)(proj + (size_t)row * 1536 + col) = w; }
.LBB0_240:
	v_cvt_pk_bf16_f32 v116, v116, v117
	v_cvt_pk_bf16_f32 v117, v118, v119
	v_cvt_pk_bf16_f32 v118, v112, v113
	v_or_b32_e32 v112, 16, v130
	v_ashrrev_i32_e32 v113, 31, v112
	v_cvt_pk_bf16_f32 v119, v114, v115
	v_lshlrev_b64 v[114:115], 6, v[112:113]
	global_store_dwordx4 v[122:123], v[116:119], off offset:256
	v_lshl_add_u64 v[114:115], v[128:129], 0, v[114:115]
	v_mov_b32_e32 v114, v166
	v_mov_b32_e32 v115, v167
	v_mov_b32_e32 v116, v168
	v_mov_b32_e32 v117, v169
	s_and_b64 vcc, exec, s[8:9]
	v_mov_b32_e32 v118, v115
	v_mov_b32_e32 v119, v116
	v_mov_b32_e32 v115, v117
	v_pk_add_f32 v[114:115], v[118:119], v[114:115]
	s_nop 0
	v_add_f32_e32 v113, v114, v115
	v_mov_b32_e32 v114, v113
	v_mov_b32_e32 v158, v113
	s_nop 1
	v_permlane16_swap_b32_e32 v114, v158
	s_waitcnt lgkmcnt(0)
	v_add_f32_e32 v113, v114, v158
	v_mov_b32_e32 v114, v113
	v_mov_b32_e32 v158, v113
	s_nop 1
	v_permlane32_swap_b32_e32 v114, v158
	s_waitcnt lgkmcnt(0)
	v_add_f32_e32 v113, v114, v158
	v_fmamk_f32 v113, v113, 0x3a800000, v208
	v_mul_f32_e32 v114, 0x4b800000, v113
	v_cmp_gt_f32_e64 s[10:11], s44, v113
	s_nop 1
	v_cndmask_b32_e64 v113, v113, v114, s[10:11]
	v_rsq_f32_e32 v113, v113
	s_nop 0
	v_mul_f32_e32 v114, 0x45800000, v113
	v_cndmask_b32_e64 v114, v113, v114, s[10:11]
	v_pk_mul_f32 v[110:111], v[110:111], v[114:115] op_sel_hi:[1,0]
	v_pk_mul_f32 v[108:109], v[108:109], v[114:115] op_sel_hi:[1,0]
	v_pk_mul_f32 v[106:107], v[106:107], v[114:115] op_sel_hi:[1,0]
	v_pk_mul_f32 v[104:105], v[104:105], v[114:115] op_sel_hi:[1,0]
	s_cbranch_vccnz .LBB0_242
	v_mul_f32_e32 v113, 0x3d372713, v108
	v_mul_f32_e32 v113, v108, v113
	v_fma_f32 v113, v108, v113, v108
	v_mul_f32_e32 v113, 0x3fcc422a, v113
	v_mul_f32_e32 v113, 0xbfb8aa3b, v113
	v_exp_f32_e32 v113, v113
	v_mov_b32_e32 v115, v109
	v_add_f32_e32 v113, 1.0, v113
	v_rcp_f32_e32 v116, v113
	v_mul_f32_e32 v113, 0x3d372713, v104
	v_mul_f32_e32 v113, v104, v113
	v_fma_f32 v113, v104, v113, v104
	v_mul_f32_e32 v113, 0x3fcc422a, v113
	v_mul_f32_e32 v113, 0xbfb8aa3b, v113
	v_exp_f32_e32 v113, v113
	s_nop 0
	v_add_f32_e32 v113, 1.0, v113
	v_rcp_f32_e32 v118, v113
	v_mul_f32_e32 v113, 0x3d372713, v109
	v_mul_f32_e32 v113, v109, v113
	v_fmac_f32_e32 v115, v115, v113
	v_mul_f32_e32 v113, 0x3fcc422a, v115
	v_mul_f32_e32 v113, 0xbfb8aa3b, v113
	v_exp_f32_e32 v113, v113
	v_mov_b32_e32 v115, v105
	v_add_f32_e32 v113, 1.0, v113
	v_rcp_f32_e32 v117, v113
	v_mul_f32_e32 v113, 0x3d372713, v105
	v_mul_f32_e32 v113, v105, v113
	v_fmac_f32_e32 v115, v115, v113
	v_mul_f32_e32 v113, 0x3fcc422a, v115
	v_mul_f32_e32 v113, 0xbfb8aa3b, v113
	v_exp_f32_e32 v113, v113
	v_pk_mul_f32 v[108:109], v[108:109], v[116:117]
	v_add_f32_e32 v113, 1.0, v113
	v_rcp_f32_e32 v119, v113
	v_mul_f32_e32 v113, 0x3d372713, v110
	v_mul_f32_e32 v113, v110, v113
	v_fma_f32 v113, v110, v113, v110
	v_mul_f32_e32 v113, 0x3fcc422a, v113
	v_mul_f32_e32 v113, 0xbfb8aa3b, v113
	v_exp_f32_e32 v113, v113
	v_pk_mul_f32 v[104:105], v[104:105], v[118:119]
	v_add_f32_e32 v113, 1.0, v113
	v_rcp_f32_e32 v122, v113
	v_mul_f32_e32 v113, 0x3d372713, v106
	v_mul_f32_e32 v113, v106, v113
	v_fma_f32 v113, v106, v113, v106
	v_mul_f32_e32 v113, 0x3fcc422a, v113
	v_mul_f32_e32 v113, 0xbfb8aa3b, v113
	v_exp_f32_e32 v113, v113
	s_nop 0
	v_add_f32_e32 v113, 1.0, v113
	v_rcp_f32_e32 v124, v113
	v_mul_f32_e32 v113, 0x3d372713, v111
	v_mul_f32_e32 v113, v111, v113
	v_fma_f32 v113, v111, v113, v111
	v_mul_f32_e32 v113, 0x3fcc422a, v113
	v_mul_f32_e32 v113, 0xbfb8aa3b, v113
	v_exp_f32_e32 v113, v113
	s_nop 0
	v_add_f32_e32 v113, 1.0, v113
	v_rcp_f32_e32 v123, v113
	v_mul_f32_e32 v113, 0x3d372713, v107
	v_mul_f32_e32 v113, v107, v113
	v_fma_f32 v113, v107, v113, v107
	v_mul_f32_e32 v113, 0x3fcc422a, v113
	v_mul_f32_e32 v113, 0xbfb8aa3b, v113
	v_exp_f32_e32 v113, v113
	v_pk_mul_f32 v[110:111], v[110:111], v[122:123]
	v_add_f32_e32 v113, 1.0, v113
	v_rcp_f32_e32 v125, v113
	s_nop 0
	v_pk_mul_f32 v[106:107], v[106:107], v[124:125]

; __device__ __forceinline__ unsigned cvt_pk_bf16(float lo, float hi) { unsigned r; asm volatile("v_cvt_pk_bf16_f32 %0, %1, %2" : "=v"(r) : "v"(lo), "v"(hi)); return r; }
; __device__ __forceinline__ float gelu_t(float x) { const float z = 1.5957691216f * (x + 0.044715f * x * x * x); return x * sigm(z); }
; #define EPI_FOR_ROWS() _Pragma("unroll") for (int ai = 0; ai < 2; ++ai) _Pragma("unroll") for (int m = 0; m < 4; ++m)
; __device__ __forceinline__ float row_rstd(const float* ssq, int row, int fq) {
;     const f32x4 q = *(const f32x4*)(ssq + (size_t)row * 16 + 4 * fq); float s = (q[0] + q[1]) + (q[2] + q[3]);
;     s += __shfl_xor(s, 16); s += __shfl_xor(s, 32); return rsqrtf(s * (1.0f / 1024.0f) + EPS);
; }
;     __device__ __forceinline__ void operator()(const f32x4 (&acc)[2][2][4][2], const Unit& u, int wr, int wc, int fr, int fq) const {
;         EPI_ROWCOL();
;         EPI_FOR_ROWS() {
;             const int row = row0 + ai * 128 + m * 16; const float rs = row_rstd(ssq, row, fq);
; #pragma unroll
;             for (int bj = 0; bj < 2; ++bj) { const int col = col0 + bj * 128; f32x4 v0 = acc[ai][bj][m][0] * rs, v1 = acc[ai][bj][m][1] * rs;
;                 if (u.pn >= 2) {
; #pragma unroll
;                     for (int e = 0; e < 4; ++e) { v0[e] = gelu_t(v0[e]); v1[e] = gelu_t(v1[e]); } }
;                 u32x4 w; w.x = cvt_pk_bf16(v0[0], v0[1]); w.y = cvt_pk_bf16(v0[2], v0[3]); w.z = cvt_pk_bf16(v1[0], v1[1]); w.w = cvt_pk_bf16(v1[2], v1[3]);
;                 *(u32x4*)(proj + (size_t)row * 1536 + col) = w; }
.LBB0_244:
	v_cvt_pk_bf16_f32 v100, v100, v101
	v_cvt_pk_bf16_f32 v101, v102, v103
	v_cvt_pk_bf16_f32 v102, v96, v97
	v_or_b32_e32 v96, 32, v130
	v_ashrrev_i32_e32 v97, 31, v96
	v_cvt_pk_bf16_f32 v103, v98, v99
	v_lshlrev_b64 v[98:99], 6, v[96:97]
	global_store_dwordx4 v[104:105], v[100:103], off offset:256
	v_lshl_add_u64 v[98:99], v[128:129], 0, v[98:99]
	v_mov_b32_e32 v98, v178
	v_mov_b32_e32 v99, v179
	v_mov_b32_e32 v100, v180
	v_mov_b32_e32 v101, v181
	s_and_b64 vcc, exec, s[8:9]
	v_mov_b32_e32 v102, v99
	v_mov_b32_e32 v103, v100
	v_mov_b32_e32 v99, v101
	v_pk_add_f32 v[98:99], v[102:103], v[98:99]
	s_nop 0
	v_add_f32_e32 v97, v98, v99
	v_mov_b32_e32 v98, v97
	v_mov_b32_e32 v158, v97
	s_nop 1
	v_permlane16_swap_b32_e32 v98, v158
	s_waitcnt lgkmcnt(0)
	v_add_f32_e32 v97, v98, v158
	v_mov_b32_e32 v98, v97
	v_mov_b32_e32 v158, v97
	s_nop 1
	v_permlane32_swap_b32_e32 v98, v158
	s_waitcnt lgkmcnt(0)
	v_add_f32_e32 v97, v98, v158
	v_fmamk_f32 v97, v97, 0x3a800000, v208
	v_mul_f32_e32 v98, 0x4b800000, v97
	v_cmp_gt_f32_e64 s[10:11], s44, v97
	s_nop 1
	v_cndmask_b32_e64 v97, v97, v98, s[10:11]
	v_rsq_f32_e32 v97, v97
	s_nop 0
	v_mul_f32_e32 v98, 0x45800000, v97
	v_cndmask_b32_e64 v98, v97, v98, s[10:11]
	v_pk_mul_f32 v[94:95], v[94:95], v[98:99] op_sel_hi:[1,0]
	v_pk_mul_f32 v[92:93], v[92:93], v[98:99] op_sel_hi:[1,0]
	v_pk_mul_f32 v[90:91], v[90:91], v[98:99] op_sel_hi:[1,0]
	v_pk_mul_f32 v[88:89], v[88:89], v[98:99] op_sel_hi:[1,0]
	s_cbranch_vccnz .LBB0_246
	v_mul_f32_e32 v97, 0x3d372713, v92
	v_mul_f32_e32 v97, v92, v97
	v_fma_f32 v97, v92, v97, v92
	v_mul_f32_e32 v97, 0x3fcc422a, v97
	v_mul_f32_e32 v97, 0xbfb8aa3b, v97
	v_exp_f32_e32 v97, v97
	v_mov_b32_e32 v99, v93
	v_add_f32_e32 v97, 1.0, v97
	v_rcp_f32_e32 v100, v97
	v_mul_f32_e32 v97, 0x3d372713, v88
	v_mul_f32_e32 v97, v88, v97
	v_fma_f32 v97, v88, v97, v88
	v_mul_f32_e32 v97, 0x3fcc422a, v97
	v_mul_f32_e32 v97, 0xbfb8aa3b, v97
	v_exp_f32_e32 v97, v97
	s_nop 0
	v_add_f32_e32 v97, 1.0, v97
	v_rcp_f32_e32 v102, v97
	v_mul_f32_e32 v97, 0x3d372713, v93
	v_mul_f32_e32 v97, v93, v97
	v_fmac_f32_e32 v99, v99, v97
	v_mul_f32_e32 v97, 0x3fcc422a, v99
	v_mul_f32_e32 v97, 0xbfb8aa3b, v97
	v_exp_f32_e32 v97, v97
	v_mov_b32_e32 v99, v89
	v_add_f32_e32 v97, 1.0, v97
	v_rcp_f32_e32 v101, v97
	v_mul_f32_e32 v97, 0x3d372713, v89
	v_mul_f32_e32 v97, v89, v97
	v_fmac_f32_e32 v99, v99, v97
	v_mul_f32_e32 v97, 0x3fcc422a, v99
	v_mul_f32_e32 v97, 0xbfb8aa3b, v97
	v_exp_f32_e32 v97, v97
	v_pk_mul_f32 v[92:93], v[92:93], v[100:101]
	v_add_f32_e32 v97, 1.0, v97
	v_rcp_f32_e32 v103, v97
	v_mul_f32_e32 v97, 0x3d372713, v94
	v_mul_f32_e32 v97, v94, v97
	v_fma_f32 v97, v94, v97, v94
	v_mul_f32_e32 v97, 0x3fcc422a, v97
	v_mul_f32_e32 v97, 0xbfb8aa3b, v97
	v_exp_f32_e32 v97, v97
	v_pk_mul_f32 v[88:89], v[88:89], v[102:103]
	v_add_f32_e32 v97, 1.0, v97
	v_rcp_f32_e32 v104, v97
	v_mul_f32_e32 v97, 0x3d372713, v90
	v_mul_f32_e32 v97, v90, v97
	v_fma_f32 v97, v90, v97, v90
	v_mul_f32_e32 v97, 0x3fcc422a, v97
	v_mul_f32_e32 v97, 0xbfb8aa3b, v97
	v_exp_f32_e32 v97, v97
	s_nop 0
	v_add_f32_e32 v97, 1.0, v97
	v_rcp_f32_e32 v106, v97
	v_mul_f32_e32 v97, 0x3d372713, v95
	v_mul_f32_e32 v97, v95, v97
	v_fma_f32 v97, v95, v97, v95
	v_mul_f32_e32 v97, 0x3fcc422a, v97
	v_mul_f32_e32 v97, 0xbfb8aa3b, v97
	v_exp_f32_e32 v97, v97
	s_nop 0
	v_add_f32_e32 v97, 1.0, v97
	v_rcp_f32_e32 v105, v97
	v_mul_f32_e32 v97, 0x3d372713, v91
	v_mul_f32_e32 v97, v91, v97
	v_fma_f32 v97, v91, v97, v91
	v_mul_f32_e32 v97, 0x3fcc422a, v97
	v_mul_f32_e32 v97, 0xbfb8aa3b, v97
	v_exp_f32_e32 v97, v97
	v_pk_mul_f32 v[94:95], v[94:95], v[104:105]
	v_add_f32_e32 v97, 1.0, v97
	v_rcp_f32_e32 v107, v97
	s_nop 0
	v_pk_mul_f32 v[90:91], v[90:91], v[106:107]

; __device__ __forceinline__ unsigned cvt_pk_bf16(float lo, float hi) { unsigned r; asm volatile("v_cvt_pk_bf16_f32 %0, %1, %2" : "=v"(r) : "v"(lo), "v"(hi)); return r; }
; __device__ __forceinline__ float gelu_t(float x) { const float z = 1.5957691216f * (x + 0.044715f * x * x * x); return x * sigm(z); }
; #define EPI_FOR_ROWS() _Pragma("unroll") for (int ai = 0; ai < 2; ++ai) _Pragma("unroll") for (int m = 0; m < 4; ++m)
; __device__ __forceinline__ float row_rstd(const float* ssq, int row, int fq) {
;     const f32x4 q = *(const f32x4*)(ssq + (size_t)row * 16 + 4 * fq); float s = (q[0] + q[1]) + (q[2] + q[3]);
;     s += __shfl_xor(s, 16); s += __shfl_xor(s, 32); return rsqrtf(s * (1.0f / 1024.0f) + EPS);
; }
;     __device__ __forceinline__ void operator()(const f32x4 (&acc)[2][2][4][2], const Unit& u, int wr, int wc, int fr, int fq) const {
;         EPI_ROWCOL();
;         EPI_FOR_ROWS() {
;             const int row = row0 + ai * 128 + m * 16; const float rs = row_rstd(ssq, row, fq);
; #pragma unroll
;             for (int bj = 0; bj < 2; ++bj) { const int col = col0 + bj * 128; f32x4 v0 = acc[ai][bj][m][0] * rs, v1 = acc[ai][bj][m][1] * rs;
;                 if (u.pn >= 2) {
; #pragma unroll
;                     for (int e = 0; e < 4; ++e) { v0[e] = gelu_t(v0[e]); v1[e] = gelu_t(v1[e]); } }
;                 u32x4 w; w.x = cvt_pk_bf16(v0[0], v0[1]); w.y = cvt_pk_bf16(v0[2], v0[3]); w.z = cvt_pk_bf16(v1[0], v1[1]); w.w = cvt_pk_bf16(v1[2], v1[3]);
;                 *(u32x4*)(proj + (size_t)row * 1536 + col) = w; }
.LBB0_248:
	v_cvt_pk_bf16_f32 v84, v84, v85
	v_cvt_pk_bf16_f32 v85, v86, v87
	v_cvt_pk_bf16_f32 v86, v80, v81
	v_or_b32_e32 v80, 48, v130
	v_ashrrev_i32_e32 v81, 31, v80
	v_cvt_pk_bf16_f32 v87, v82, v83
	v_lshlrev_b64 v[82:83], 6, v[80:81]
	global_store_dwordx4 v[88:89], v[84:87], off offset:256
	v_lshl_add_u64 v[82:83], v[128:129], 0, v[82:83]
	v_mov_b32_e32 v82, v182
	v_mov_b32_e32 v83, v183
	v_mov_b32_e32 v84, v184
	v_mov_b32_e32 v85, v185
	s_and_b64 vcc, exec, s[8:9]
	v_mov_b32_e32 v86, v83
	v_mov_b32_e32 v87, v84
	v_mov_b32_e32 v83, v85
	v_pk_add_f32 v[82:83], v[86:87], v[82:83]
	s_nop 0
	v_add_f32_e32 v81, v82, v83
	v_mov_b32_e32 v82, v81
	v_mov_b32_e32 v158, v81
	s_nop 1
	v_permlane16_swap_b32_e32 v82, v158
	s_waitcnt lgkmcnt(0)
	v_add_f32_e32 v81, v82, v158
	v_mov_b32_e32 v82, v81
	v_mov_b32_e32 v158, v81
	s_nop 1
	v_permlane32_swap_b32_e32 v82, v158
	s_waitcnt lgkmcnt(0)
	v_add_f32_e32 v81, v82, v158
	v_fmamk_f32 v81, v81, 0x3a800000, v208
	v_mul_f32_e32 v82, 0x4b800000, v81
	v_cmp_gt_f32_e64 s[10:11], s44, v81
	s_nop 1
	v_cndmask_b32_e64 v81, v81, v82, s[10:11]
	v_rsq_f32_e32 v81, v81
	s_nop 0
	v_mul_f32_e32 v82, 0x45800000, v81
	v_cndmask_b32_e64 v82, v81, v82, s[10:11]
	v_pk_mul_f32 v[78:79], v[78:79], v[82:83] op_sel_hi:[1,0]
	v_pk_mul_f32 v[76:77], v[76:77], v[82:83] op_sel_hi:[1,0]
	v_pk_mul_f32 v[74:75], v[74:75], v[82:83] op_sel_hi:[1,0]
	v_pk_mul_f32 v[72:73], v[72:73], v[82:83] op_sel_hi:[1,0]
	s_cbranch_vccnz .LBB0_250
	v_mul_f32_e32 v81, 0x3d372713, v76
	v_mul_f32_e32 v81, v76, v81
	v_fma_f32 v81, v76, v81, v76
	v_mul_f32_e32 v81, 0x3fcc422a, v81
	v_mul_f32_e32 v81, 0xbfb8aa3b, v81
	v_exp_f32_e32 v81, v81
	v_mov_b32_e32 v83, v77
	v_add_f32_e32 v81, 1.0, v81
	v_rcp_f32_e32 v84, v81
	v_mul_f32_e32 v81, 0x3d372713, v72
	v_mul_f32_e32 v81, v72, v81
	v_fma_f32 v81, v72, v81, v72
	v_mul_f32_e32 v81, 0x3fcc422a, v81
	v_mul_f32_e32 v81, 0xbfb8aa3b, v81
	v_exp_f32_e32 v81, v81
	s_nop 0
	v_add_f32_e32 v81, 1.0, v81
	v_rcp_f32_e32 v86, v81
	v_mul_f32_e32 v81, 0x3d372713, v77
	v_mul_f32_e32 v81, v77, v81
	v_fmac_f32_e32 v83, v83, v81
	v_mul_f32_e32 v81, 0x3fcc422a, v83
	v_mul_f32_e32 v81, 0xbfb8aa3b, v81
	v_exp_f32_e32 v81, v81
	v_mov_b32_e32 v83, v73
	v_add_f32_e32 v81, 1.0, v81
	v_rcp_f32_e32 v85, v81
	v_mul_f32_e32 v81, 0x3d372713, v73
	v_mul_f32_e32 v81, v73, v81
	v_fmac_f32_e32 v83, v83, v81
	v_mul_f32_e32 v81, 0x3fcc422a, v83
	v_mul_f32_e32 v81, 0xbfb8aa3b, v81
	v_exp_f32_e32 v81, v81
	v_pk_mul_f32 v[76:77], v[76:77], v[84:85]
	v_add_f32_e32 v81, 1.0, v81
	v_rcp_f32_e32 v87, v81
	v_mul_f32_e32 v81, 0x3d372713, v78
	v_mul_f32_e32 v81, v78, v81
	v_fma_f32 v81, v78, v81, v78
	v_mul_f32_e32 v81, 0x3fcc422a, v81
	v_mul_f32_e32 v81, 0xbfb8aa3b, v81
	v_exp_f32_e32 v81, v81
	v_pk_mul_f32 v[72:73], v[72:73], v[86:87]
	v_add_f32_e32 v81, 1.0, v81
	v_rcp_f32_e32 v88, v81
	v_mul_f32_e32 v81, 0x3d372713, v74
	v_mul_f32_e32 v81, v74, v81
	v_fma_f32 v81, v74, v81, v74
	v_mul_f32_e32 v81, 0x3fcc422a, v81
	v_mul_f32_e32 v81, 0xbfb8aa3b, v81
	v_exp_f32_e32 v81, v81
	s_nop 0
	v_add_f32_e32 v81, 1.0, v81
	v_rcp_f32_e32 v90, v81
	v_mul_f32_e32 v81, 0x3d372713, v79
	v_mul_f32_e32 v81, v79, v81
	v_fma_f32 v81, v79, v81, v79
	v_mul_f32_e32 v81, 0x3fcc422a, v81
	v_mul_f32_e32 v81, 0xbfb8aa3b, v81
	v_exp_f32_e32 v81, v81
	s_nop 0
	v_add_f32_e32 v81, 1.0, v81
	v_rcp_f32_e32 v89, v81
	v_mul_f32_e32 v81, 0x3d372713, v75
	v_mul_f32_e32 v81, v75, v81
	v_fma_f32 v81, v75, v81, v75
	v_mul_f32_e32 v81, 0x3fcc422a, v81
	v_mul_f32_e32 v81, 0xbfb8aa3b, v81
	v_exp_f32_e32 v81, v81
	v_pk_mul_f32 v[78:79], v[78:79], v[88:89]
	v_add_f32_e32 v81, 1.0, v81
	v_rcp_f32_e32 v91, v81
	s_nop 0
	v_pk_mul_f32 v[74:75], v[74:75], v[90:91]

; __device__ __forceinline__ unsigned cvt_pk_bf16(float lo, float hi) { unsigned r; asm volatile("v_cvt_pk_bf16_f32 %0, %1, %2" : "=v"(r) : "v"(lo), "v"(hi)); return r; }
; __device__ __forceinline__ float gelu_t(float x) { const float z = 1.5957691216f * (x + 0.044715f * x * x * x); return x * sigm(z); }
; #define EPI_FOR_ROWS() _Pragma("unroll") for (int ai = 0; ai < 2; ++ai) _Pragma("unroll") for (int m = 0; m < 4; ++m)
; __device__ __forceinline__ float row_rstd(const float* ssq, int row, int fq) {
;     const f32x4 q = *(const f32x4*)(ssq + (size_t)row * 16 + 4 * fq); float s = (q[0] + q[1]) + (q[2] + q[3]);
;     s += __shfl_xor(s, 16); s += __shfl_xor(s, 32); return rsqrtf(s * (1.0f / 1024.0f) + EPS);
; }
;     __device__ __forceinline__ void operator()(const f32x4 (&acc)[2][2][4][2], const Unit& u, int wr, int wc, int fr, int fq) const {
;         EPI_ROWCOL();
;         EPI_FOR_ROWS() {
;             const int row = row0 + ai * 128 + m * 16; const float rs = row_rstd(ssq, row, fq);
; #pragma unroll
;             for (int bj = 0; bj < 2; ++bj) { const int col = col0 + bj * 128; f32x4 v0 = acc[ai][bj][m][0] * rs, v1 = acc[ai][bj][m][1] * rs;
;                 if (u.pn >= 2) {
; #pragma unroll
;                     for (int e = 0; e < 4; ++e) { v0[e] = gelu_t(v0[e]); v1[e] = gelu_t(v1[e]); } }
;                 u32x4 w; w.x = cvt_pk_bf16(v0[0], v0[1]); w.y = cvt_pk_bf16(v0[2], v0[3]); w.z = cvt_pk_bf16(v1[0], v1[1]); w.w = cvt_pk_bf16(v1[2], v1[3]);
;                 *(u32x4*)(proj + (size_t)row * 1536 + col) = w; }
.LBB0_252:
	v_cvt_pk_bf16_f32 v68, v68, v69
	v_cvt_pk_bf16_f32 v69, v70, v71
	v_cvt_pk_bf16_f32 v70, v64, v65
	v_add_u32_e32 v64, 0x80, v130
	v_ashrrev_i32_e32 v65, 31, v64
	v_cvt_pk_bf16_f32 v71, v66, v67
	v_lshlrev_b64 v[66:67], 6, v[64:65]
	global_store_dwordx4 v[72:73], v[68:71], off offset:256
	v_lshl_add_u64 v[66:67], v[128:129], 0, v[66:67]
	v_mov_b32_e32 v66, v186
	v_mov_b32_e32 v67, v187
	v_mov_b32_e32 v68, v188
	v_mov_b32_e32 v69, v189
	s_and_b64 vcc, exec, s[8:9]
	v_mov_b32_e32 v70, v67
	v_mov_b32_e32 v71, v68
	v_mov_b32_e32 v67, v69
	v_pk_add_f32 v[66:67], v[70:71], v[66:67]
	s_nop 0
	v_add_f32_e32 v65, v66, v67
	v_mov_b32_e32 v66, v65
	v_mov_b32_e32 v158, v65
	s_nop 1
	v_permlane16_swap_b32_e32 v66, v158
	s_waitcnt lgkmcnt(0)
	v_add_f32_e32 v65, v66, v158
	v_mov_b32_e32 v66, v65
	v_mov_b32_e32 v158, v65
	s_nop 1
	v_permlane32_swap_b32_e32 v66, v158
	s_waitcnt lgkmcnt(0)
	v_add_f32_e32 v65, v66, v158
	v_fmamk_f32 v65, v65, 0x3a800000, v208
	v_mul_f32_e32 v66, 0x4b800000, v65
	v_cmp_gt_f32_e64 s[10:11], s44, v65
	s_nop 1
	v_cndmask_b32_e64 v65, v65, v66, s[10:11]
	v_rsq_f32_e32 v65, v65
	s_nop 0
	v_mul_f32_e32 v66, 0x45800000, v65
	v_cndmask_b32_e64 v66, v65, v66, s[10:11]
	v_pk_mul_f32 v[62:63], v[62:63], v[66:67] op_sel_hi:[1,0]
	v_pk_mul_f32 v[60:61], v[60:61], v[66:67] op_sel_hi:[1,0]
	v_pk_mul_f32 v[58:59], v[58:59], v[66:67] op_sel_hi:[1,0]
	v_pk_mul_f32 v[56:57], v[56:57], v[66:67] op_sel_hi:[1,0]
	s_cbranch_vccnz .LBB0_254
	v_mul_f32_e32 v65, 0x3d372713, v60
	v_mul_f32_e32 v65, v60, v65
	v_fma_f32 v65, v60, v65, v60
	v_mul_f32_e32 v65, 0x3fcc422a, v65
	v_mul_f32_e32 v65, 0xbfb8aa3b, v65
	v_exp_f32_e32 v65, v65
	v_mov_b32_e32 v67, v61
	v_add_f32_e32 v65, 1.0, v65
	v_rcp_f32_e32 v68, v65
	v_mul_f32_e32 v65, 0x3d372713, v56
	v_mul_f32_e32 v65, v56, v65
	v_fma_f32 v65, v56, v65, v56
	v_mul_f32_e32 v65, 0x3fcc422a, v65
	v_mul_f32_e32 v65, 0xbfb8aa3b, v65
	v_exp_f32_e32 v65, v65
	s_nop 0
	v_add_f32_e32 v65, 1.0, v65
	v_rcp_f32_e32 v70, v65
	v_mul_f32_e32 v65, 0x3d372713, v61
	v_mul_f32_e32 v65, v61, v65
	v_fmac_f32_e32 v67, v67, v65
	v_mul_f32_e32 v65, 0x3fcc422a, v67
	v_mul_f32_e32 v65, 0xbfb8aa3b, v65
	v_exp_f32_e32 v65, v65
	v_mov_b32_e32 v67, v57
	v_add_f32_e32 v65, 1.0, v65
	v_rcp_f32_e32 v69, v65
	v_mul_f32_e32 v65, 0x3d372713, v57
	v_mul_f32_e32 v65, v57, v65
	v_fmac_f32_e32 v67, v67, v65
	v_mul_f32_e32 v65, 0x3fcc422a, v67
	v_mul_f32_e32 v65, 0xbfb8aa3b, v65
	v_exp_f32_e32 v65, v65
	v_pk_mul_f32 v[60:61], v[60:61], v[68:69]
	v_add_f32_e32 v65, 1.0, v65
	v_rcp_f32_e32 v71, v65
	v_mul_f32_e32 v65, 0x3d372713, v62
	v_mul_f32_e32 v65, v62, v65
	v_fma_f32 v65, v62, v65, v62
	v_mul_f32_e32 v65, 0x3fcc422a, v65
	v_mul_f32_e32 v65, 0xbfb8aa3b, v65
	v_exp_f32_e32 v65, v65
	v_pk_mul_f32 v[56:57], v[56:57], v[70:71]
	v_add_f32_e32 v65, 1.0, v65
	v_rcp_f32_e32 v72, v65
	v_mul_f32_e32 v65, 0x3d372713, v58
	v_mul_f32_e32 v65, v58, v65
	v_fma_f32 v65, v58, v65, v58
	v_mul_f32_e32 v65, 0x3fcc422a, v65
	v_mul_f32_e32 v65, 0xbfb8aa3b, v65
	v_exp_f32_e32 v65, v65
	s_nop 0
	v_add_f32_e32 v65, 1.0, v65
	v_rcp_f32_e32 v74, v65
	v_mul_f32_e32 v65, 0x3d372713, v63
	v_mul_f32_e32 v65, v63, v65
	v_fma_f32 v65, v63, v65, v63
	v_mul_f32_e32 v65, 0x3fcc422a, v65
	v_mul_f32_e32 v65, 0xbfb8aa3b, v65
	v_exp_f32_e32 v65, v65
	s_nop 0
	v_add_f32_e32 v65, 1.0, v65
	v_rcp_f32_e32 v73, v65
	v_mul_f32_e32 v65, 0x3d372713, v59
	v_mul_f32_e32 v65, v59, v65
	v_fma_f32 v65, v59, v65, v59
	v_mul_f32_e32 v65, 0x3fcc422a, v65
	v_mul_f32_e32 v65, 0xbfb8aa3b, v65
	v_exp_f32_e32 v65, v65
	v_pk_mul_f32 v[62:63], v[62:63], v[72:73]
	v_add_f32_e32 v65, 1.0, v65
	v_rcp_f32_e32 v75, v65
	s_nop 0
	v_pk_mul_f32 v[58:59], v[58:59], v[74:75]

; __device__ __forceinline__ unsigned cvt_pk_bf16(float lo, float hi) { unsigned r; asm volatile("v_cvt_pk_bf16_f32 %0, %1, %2" : "=v"(r) : "v"(lo), "v"(hi)); return r; }
; __device__ __forceinline__ float gelu_t(float x) { const float z = 1.5957691216f * (x + 0.044715f * x * x * x); return x * sigm(z); }
; #define EPI_FOR_ROWS() _Pragma("unroll") for (int ai = 0; ai < 2; ++ai) _Pragma("unroll") for (int m = 0; m < 4; ++m)
; __device__ __forceinline__ float row_rstd(const float* ssq, int row, int fq) {
;     const f32x4 q = *(const f32x4*)(ssq + (size_t)row * 16 + 4 * fq); float s = (q[0] + q[1]) + (q[2] + q[3]);
;     s += __shfl_xor(s, 16); s += __shfl_xor(s, 32); return rsqrtf(s * (1.0f / 1024.0f) + EPS);
; }
;     __device__ __forceinline__ void operator()(const f32x4 (&acc)[2][2][4][2], const Unit& u, int wr, int wc, int fr, int fq) const {
;         EPI_ROWCOL();
;         EPI_FOR_ROWS() {
;             const int row = row0 + ai * 128 + m * 16; const float rs = row_rstd(ssq, row, fq);
; #pragma unroll
;             for (int bj = 0; bj < 2; ++bj) { const int col = col0 + bj * 128; f32x4 v0 = acc[ai][bj][m][0] * rs, v1 = acc[ai][bj][m][1] * rs;
;                 if (u.pn >= 2) {
; #pragma unroll
;                     for (int e = 0; e < 4; ++e) { v0[e] = gelu_t(v0[e]); v1[e] = gelu_t(v1[e]); } }
;                 u32x4 w; w.x = cvt_pk_bf16(v0[0], v0[1]); w.y = cvt_pk_bf16(v0[2], v0[3]); w.z = cvt_pk_bf16(v1[0], v1[1]); w.w = cvt_pk_bf16(v1[2], v1[3]);
;                 *(u32x4*)(proj + (size_t)row * 1536 + col) = w; }
.LBB0_256:
	v_cvt_pk_bf16_f32 v52, v52, v53
	v_cvt_pk_bf16_f32 v53, v54, v55
	v_cvt_pk_bf16_f32 v54, v48, v49
	v_add_u32_e32 v48, 0x90, v130
	v_ashrrev_i32_e32 v49, 31, v48
	v_cvt_pk_bf16_f32 v55, v50, v51
	v_lshlrev_b64 v[50:51], 6, v[48:49]
	global_store_dwordx4 v[56:57], v[52:55], off offset:256
	v_lshl_add_u64 v[50:51], v[128:129], 0, v[50:51]
	v_mov_b32_e32 v50, v190
	v_mov_b32_e32 v51, v191
	v_mov_b32_e32 v52, v192
	v_mov_b32_e32 v53, v193
	s_and_b64 vcc, exec, s[8:9]
	v_mov_b32_e32 v54, v51
	v_mov_b32_e32 v55, v52
	v_mov_b32_e32 v51, v53
	v_pk_add_f32 v[50:51], v[54:55], v[50:51]
	s_nop 0
	v_add_f32_e32 v49, v50, v51
	v_mov_b32_e32 v50, v49
	v_mov_b32_e32 v158, v49
	s_nop 1
	v_permlane16_swap_b32_e32 v50, v158
	s_waitcnt lgkmcnt(0)
	v_add_f32_e32 v49, v50, v158
	v_mov_b32_e32 v50, v49
	v_mov_b32_e32 v158, v49
	s_nop 1
	v_permlane32_swap_b32_e32 v50, v158
	s_waitcnt lgkmcnt(0)
	v_add_f32_e32 v49, v50, v158
	v_fmamk_f32 v49, v49, 0x3a800000, v208
	v_mul_f32_e32 v50, 0x4b800000, v49
	v_cmp_gt_f32_e64 s[10:11], s44, v49
	s_nop 1
	v_cndmask_b32_e64 v49, v49, v50, s[10:11]
	v_rsq_f32_e32 v49, v49
	s_nop 0
	v_mul_f32_e32 v50, 0x45800000, v49
	v_cndmask_b32_e64 v50, v49, v50, s[10:11]
	v_pk_mul_f32 v[46:47], v[46:47], v[50:51] op_sel_hi:[1,0]
	v_pk_mul_f32 v[44:45], v[44:45], v[50:51] op_sel_hi:[1,0]
	v_pk_mul_f32 v[42:43], v[42:43], v[50:51] op_sel_hi:[1,0]
	v_pk_mul_f32 v[40:41], v[40:41], v[50:51] op_sel_hi:[1,0]
	s_cbranch_vccnz .LBB0_258
	v_mul_f32_e32 v49, 0x3d372713, v44
	v_mul_f32_e32 v49, v44, v49
	v_fma_f32 v49, v44, v49, v44
	v_mul_f32_e32 v49, 0x3fcc422a, v49
	v_mul_f32_e32 v49, 0xbfb8aa3b, v49
	v_exp_f32_e32 v49, v49
	v_mov_b32_e32 v51, v45
	v_add_f32_e32 v49, 1.0, v49
	v_rcp_f32_e32 v52, v49
	v_mul_f32_e32 v49, 0x3d372713, v40
	v_mul_f32_e32 v49, v40, v49
	v_fma_f32 v49, v40, v49, v40
	v_mul_f32_e32 v49, 0x3fcc422a, v49
	v_mul_f32_e32 v49, 0xbfb8aa3b, v49
	v_exp_f32_e32 v49, v49
	s_nop 0
	v_add_f32_e32 v49, 1.0, v49
	v_rcp_f32_e32 v54, v49
	v_mul_f32_e32 v49, 0x3d372713, v45
	v_mul_f32_e32 v49, v45, v49
	v_fmac_f32_e32 v51, v51, v49
	v_mul_f32_e32 v49, 0x3fcc422a, v51
	v_mul_f32_e32 v49, 0xbfb8aa3b, v49
	v_exp_f32_e32 v49, v49
	v_mov_b32_e32 v51, v41
	v_add_f32_e32 v49, 1.0, v49
	v_rcp_f32_e32 v53, v49
	v_mul_f32_e32 v49, 0x3d372713, v41
	v_mul_f32_e32 v49, v41, v49
	v_fmac_f32_e32 v51, v51, v49
	v_mul_f32_e32 v49, 0x3fcc422a, v51
	v_mul_f32_e32 v49, 0xbfb8aa3b, v49
	v_exp_f32_e32 v49, v49
	v_pk_mul_f32 v[44:45], v[44:45], v[52:53]
	v_add_f32_e32 v49, 1.0, v49
	v_rcp_f32_e32 v55, v49
	v_mul_f32_e32 v49, 0x3d372713, v46
	v_mul_f32_e32 v49, v46, v49
	v_fma_f32 v49, v46, v49, v46
	v_mul_f32_e32 v49, 0x3fcc422a, v49
	v_mul_f32_e32 v49, 0xbfb8aa3b, v49
	v_exp_f32_e32 v49, v49
	v_pk_mul_f32 v[40:41], v[40:41], v[54:55]
	v_add_f32_e32 v49, 1.0, v49
	v_rcp_f32_e32 v56, v49
	v_mul_f32_e32 v49, 0x3d372713, v42
	v_mul_f32_e32 v49, v42, v49
	v_fma_f32 v49, v42, v49, v42
	v_mul_f32_e32 v49, 0x3fcc422a, v49
	v_mul_f32_e32 v49, 0xbfb8aa3b, v49
	v_exp_f32_e32 v49, v49
	s_nop 0
	v_add_f32_e32 v49, 1.0, v49
	v_rcp_f32_e32 v58, v49
	v_mul_f32_e32 v49, 0x3d372713, v47
	v_mul_f32_e32 v49, v47, v49
	v_fma_f32 v49, v47, v49, v47
	v_mul_f32_e32 v49, 0x3fcc422a, v49
	v_mul_f32_e32 v49, 0xbfb8aa3b, v49
	v_exp_f32_e32 v49, v49
	s_nop 0
	v_add_f32_e32 v49, 1.0, v49
	v_rcp_f32_e32 v57, v49
	v_mul_f32_e32 v49, 0x3d372713, v43
	v_mul_f32_e32 v49, v43, v49
	v_fma_f32 v49, v43, v49, v43
	v_mul_f32_e32 v49, 0x3fcc422a, v49
	v_mul_f32_e32 v49, 0xbfb8aa3b, v49
	v_exp_f32_e32 v49, v49
	v_pk_mul_f32 v[46:47], v[46:47], v[56:57]
	v_add_f32_e32 v49, 1.0, v49
	v_rcp_f32_e32 v59, v49
	s_nop 0
	v_pk_mul_f32 v[42:43], v[42:43], v[58:59]

; __device__ __forceinline__ unsigned cvt_pk_bf16(float lo, float hi) { unsigned r; asm volatile("v_cvt_pk_bf16_f32 %0, %1, %2" : "=v"(r) : "v"(lo), "v"(hi)); return r; }
; __device__ __forceinline__ float gelu_t(float x) { const float z = 1.5957691216f * (x + 0.044715f * x * x * x); return x * sigm(z); }
; #define EPI_FOR_ROWS() _Pragma("unroll") for (int ai = 0; ai < 2; ++ai) _Pragma("unroll") for (int m = 0; m < 4; ++m)
; __device__ __forceinline__ float row_rstd(const float* ssq, int row, int fq) {
;     const f32x4 q = *(const f32x4*)(ssq + (size_t)row * 16 + 4 * fq); float s = (q[0] + q[1]) + (q[2] + q[3]);
;     s += __shfl_xor(s, 16); s += __shfl_xor(s, 32); return rsqrtf(s * (1.0f / 1024.0f) + EPS);
; }
;     __device__ __forceinline__ void operator()(const f32x4 (&acc)[2][2][4][2], const Unit& u, int wr, int wc, int fr, int fq) const {
;         EPI_ROWCOL();
;         EPI_FOR_ROWS() {
;             const int row = row0 + ai * 128 + m * 16; const float rs = row_rstd(ssq, row, fq);
; #pragma unroll
;             for (int bj = 0; bj < 2; ++bj) { const int col = col0 + bj * 128; f32x4 v0 = acc[ai][bj][m][0] * rs, v1 = acc[ai][bj][m][1] * rs;
;                 if (u.pn >= 2) {
; #pragma unroll
;                     for (int e = 0; e < 4; ++e) { v0[e] = gelu_t(v0[e]); v1[e] = gelu_t(v1[e]); } }
;                 u32x4 w; w.x = cvt_pk_bf16(v0[0], v0[1]); w.y = cvt_pk_bf16(v0[2], v0[3]); w.z = cvt_pk_bf16(v1[0], v1[1]); w.w = cvt_pk_bf16(v1[2], v1[3]);
;                 *(u32x4*)(proj + (size_t)row * 1536 + col) = w; }
.LBB0_260:
	v_cvt_pk_bf16_f32 v36, v36, v37
	v_cvt_pk_bf16_f32 v37, v38, v39
	v_cvt_pk_bf16_f32 v38, v32, v33
	v_add_u32_e32 v32, 0xa0, v130
	v_ashrrev_i32_e32 v33, 31, v32
	v_cvt_pk_bf16_f32 v39, v34, v35
	v_lshlrev_b64 v[34:35], 6, v[32:33]
	global_store_dwordx4 v[40:41], v[36:39], off offset:256
	v_lshl_add_u64 v[34:35], v[128:129], 0, v[34:35]
	v_mov_b32_e32 v34, v194
	v_mov_b32_e32 v35, v195
	v_mov_b32_e32 v36, v196
	v_mov_b32_e32 v37, v197
	s_and_b64 vcc, exec, s[8:9]
	v_mov_b32_e32 v38, v35
	v_mov_b32_e32 v39, v36
	v_mov_b32_e32 v35, v37
	v_pk_add_f32 v[34:35], v[38:39], v[34:35]
	s_nop 0
	v_add_f32_e32 v33, v34, v35
	v_mov_b32_e32 v34, v33
	v_mov_b32_e32 v158, v33
	s_nop 1
	v_permlane16_swap_b32_e32 v34, v158
	s_waitcnt lgkmcnt(0)
	v_add_f32_e32 v33, v34, v158
	v_mov_b32_e32 v34, v33
	v_mov_b32_e32 v158, v33
	s_nop 1
	v_permlane32_swap_b32_e32 v34, v158
	s_waitcnt lgkmcnt(0)
	v_add_f32_e32 v33, v34, v158
	v_fmamk_f32 v33, v33, 0x3a800000, v208
	v_mul_f32_e32 v34, 0x4b800000, v33
	v_cmp_gt_f32_e64 s[10:11], s44, v33
	s_nop 1
	v_cndmask_b32_e64 v33, v33, v34, s[10:11]
	v_rsq_f32_e32 v33, v33
	s_nop 0
	v_mul_f32_e32 v34, 0x45800000, v33
	v_cndmask_b32_e64 v34, v33, v34, s[10:11]
	v_pk_mul_f32 v[30:31], v[30:31], v[34:35] op_sel_hi:[1,0]
	v_pk_mul_f32 v[28:29], v[28:29], v[34:35] op_sel_hi:[1,0]
	v_pk_mul_f32 v[26:27], v[26:27], v[34:35] op_sel_hi:[1,0]
	v_pk_mul_f32 v[24:25], v[24:25], v[34:35] op_sel_hi:[1,0]
	s_cbranch_vccnz .LBB0_262
	v_mul_f32_e32 v33, 0x3d372713, v28
	v_mul_f32_e32 v33, v28, v33
	v_fma_f32 v33, v28, v33, v28
	v_mul_f32_e32 v33, 0x3fcc422a, v33
	v_mul_f32_e32 v33, 0xbfb8aa3b, v33
	v_exp_f32_e32 v33, v33
	v_mov_b32_e32 v35, v29
	v_add_f32_e32 v33, 1.0, v33
	v_rcp_f32_e32 v36, v33
	v_mul_f32_e32 v33, 0x3d372713, v24
	v_mul_f32_e32 v33, v24, v33
	v_fma_f32 v33, v24, v33, v24
	v_mul_f32_e32 v33, 0x3fcc422a, v33
	v_mul_f32_e32 v33, 0xbfb8aa3b, v33
	v_exp_f32_e32 v33, v33
	s_nop 0
	v_add_f32_e32 v33, 1.0, v33
	v_rcp_f32_e32 v38, v33
	v_mul_f32_e32 v33, 0x3d372713, v29
	v_mul_f32_e32 v33, v29, v33
	v_fmac_f32_e32 v35, v35, v33
	v_mul_f32_e32 v33, 0x3fcc422a, v35
	v_mul_f32_e32 v33, 0xbfb8aa3b, v33
	v_exp_f32_e32 v33, v33
	v_mov_b32_e32 v35, v25
	v_add_f32_e32 v33, 1.0, v33
	v_rcp_f32_e32 v37, v33
	v_mul_f32_e32 v33, 0x3d372713, v25
	v_mul_f32_e32 v33, v25, v33
	v_fmac_f32_e32 v35, v35, v33
	v_mul_f32_e32 v33, 0x3fcc422a, v35
	v_mul_f32_e32 v33, 0xbfb8aa3b, v33
	v_exp_f32_e32 v33, v33
	v_pk_mul_f32 v[28:29], v[28:29], v[36:37]
	v_add_f32_e32 v33, 1.0, v33
	v_rcp_f32_e32 v39, v33
	v_mul_f32_e32 v33, 0x3d372713, v30
	v_mul_f32_e32 v33, v30, v33
	v_fma_f32 v33, v30, v33, v30
	v_mul_f32_e32 v33, 0x3fcc422a, v33
	v_mul_f32_e32 v33, 0xbfb8aa3b, v33
	v_exp_f32_e32 v33, v33
	v_pk_mul_f32 v[24:25], v[24:25], v[38:39]
	v_add_f32_e32 v33, 1.0, v33
	v_rcp_f32_e32 v40, v33
	v_mul_f32_e32 v33, 0x3d372713, v26
	v_mul_f32_e32 v33, v26, v33
	v_fma_f32 v33, v26, v33, v26
	v_mul_f32_e32 v33, 0x3fcc422a, v33
	v_mul_f32_e32 v33, 0xbfb8aa3b, v33
	v_exp_f32_e32 v33, v33
	s_nop 0
	v_add_f32_e32 v33, 1.0, v33
	v_rcp_f32_e32 v42, v33
	v_mul_f32_e32 v33, 0x3d372713, v31
	v_mul_f32_e32 v33, v31, v33
	v_fma_f32 v33, v31, v33, v31
	v_mul_f32_e32 v33, 0x3fcc422a, v33
	v_mul_f32_e32 v33, 0xbfb8aa3b, v33
	v_exp_f32_e32 v33, v33
	s_nop 0
	v_add_f32_e32 v33, 1.0, v33
	v_rcp_f32_e32 v41, v33
	v_mul_f32_e32 v33, 0x3d372713, v27
	v_mul_f32_e32 v33, v27, v33
	v_fma_f32 v33, v27, v33, v27
	v_mul_f32_e32 v33, 0x3fcc422a, v33
	v_mul_f32_e32 v33, 0xbfb8aa3b, v33
	v_exp_f32_e32 v33, v33
	v_pk_mul_f32 v[30:31], v[30:31], v[40:41]
	v_add_f32_e32 v33, 1.0, v33
	v_rcp_f32_e32 v43, v33
	s_nop 0
	v_pk_mul_f32 v[26:27], v[26:27], v[42:43]

; __device__ __forceinline__ unsigned cvt_pk_bf16(float lo, float hi) { unsigned r; asm volatile("v_cvt_pk_bf16_f32 %0, %1, %2" : "=v"(r) : "v"(lo), "v"(hi)); return r; }
; __device__ __forceinline__ float gelu_t(float x) { const float z = 1.5957691216f * (x + 0.044715f * x * x * x); return x * sigm(z); }
; #define EPI_FOR_ROWS() _Pragma("unroll") for (int ai = 0; ai < 2; ++ai) _Pragma("unroll") for (int m = 0; m < 4; ++m)
; __device__ __forceinline__ float row_rstd(const float* ssq, int row, int fq) {
;     const f32x4 q = *(const f32x4*)(ssq + (size_t)row * 16 + 4 * fq); float s = (q[0] + q[1]) + (q[2] + q[3]);
;     s += __shfl_xor(s, 16); s += __shfl_xor(s, 32); return rsqrtf(s * (1.0f / 1024.0f) + EPS);
; }
;     __device__ __forceinline__ void operator()(const f32x4 (&acc)[2][2][4][2], const Unit& u, int wr, int wc, int fr, int fq) const {
;         EPI_ROWCOL();
;         EPI_FOR_ROWS() {
;             const int row = row0 + ai * 128 + m * 16; const float rs = row_rstd(ssq, row, fq);
; #pragma unroll
;             for (int bj = 0; bj < 2; ++bj) { const int col = col0 + bj * 128; f32x4 v0 = acc[ai][bj][m][0] * rs, v1 = acc[ai][bj][m][1] * rs;
;                 if (u.pn >= 2) {
; #pragma unroll
;                     for (int e = 0; e < 4; ++e) { v0[e] = gelu_t(v0[e]); v1[e] = gelu_t(v1[e]); } }
;                 u32x4 w; w.x = cvt_pk_bf16(v0[0], v0[1]); w.y = cvt_pk_bf16(v0[2], v0[3]); w.z = cvt_pk_bf16(v1[0], v1[1]); w.w = cvt_pk_bf16(v1[2], v1[3]);
;                 *(u32x4*)(proj + (size_t)row * 1536 + col) = w; }
.LBB0_264:
	v_cvt_pk_bf16_f32 v20, v20, v21
	v_cvt_pk_bf16_f32 v21, v22, v23
	v_cvt_pk_bf16_f32 v22, v16, v17
	v_add_u32_e32 v16, 0xb0, v130
	v_ashrrev_i32_e32 v17, 31, v16
	v_cvt_pk_bf16_f32 v23, v18, v19
	v_lshlrev_b64 v[18:19], 6, v[16:17]
	global_store_dwordx4 v[24:25], v[20:23], off offset:256
	v_lshl_add_u64 v[18:19], v[128:129], 0, v[18:19]
	v_mov_b32_e32 v18, v198
	v_mov_b32_e32 v19, v199
	v_mov_b32_e32 v20, v200
	v_mov_b32_e32 v21, v201
	s_and_b64 vcc, exec, s[8:9]
	v_mov_b32_e32 v22, v19
	v_mov_b32_e32 v23, v20
	v_mov_b32_e32 v19, v21
	v_pk_add_f32 v[18:19], v[22:23], v[18:19]
	s_nop 0
	v_add_f32_e32 v17, v18, v19
	v_mov_b32_e32 v18, v17
	v_mov_b32_e32 v158, v17
	s_nop 1
	v_permlane16_swap_b32_e32 v18, v158
	s_waitcnt lgkmcnt(0)
	v_add_f32_e32 v17, v18, v158
	v_mov_b32_e32 v18, v17
	v_mov_b32_e32 v158, v17
	s_nop 1
	v_permlane32_swap_b32_e32 v18, v158
	s_waitcnt lgkmcnt(0)
	v_add_f32_e32 v17, v18, v158
	v_fmamk_f32 v17, v17, 0x3a800000, v208
	v_mul_f32_e32 v18, 0x4b800000, v17
	v_cmp_gt_f32_e64 s[10:11], s44, v17
	s_nop 1
	v_cndmask_b32_e64 v17, v17, v18, s[10:11]
	v_rsq_f32_e32 v17, v17
	s_nop 0
	v_mul_f32_e32 v18, 0x45800000, v17
	v_cndmask_b32_e64 v18, v17, v18, s[10:11]
	v_pk_mul_f32 v[14:15], v[14:15], v[18:19] op_sel_hi:[1,0]
	v_pk_mul_f32 v[12:13], v[12:13], v[18:19] op_sel_hi:[1,0]
	v_pk_mul_f32 v[10:11], v[10:11], v[18:19] op_sel_hi:[1,0]
	v_pk_mul_f32 v[8:9], v[8:9], v[18:19] op_sel_hi:[1,0]
	s_cbranch_vccnz .LBB0_266
	v_mul_f32_e32 v17, 0x3d372713, v12
	v_mul_f32_e32 v17, v12, v17
	v_fma_f32 v17, v12, v17, v12
	v_mul_f32_e32 v17, 0x3fcc422a, v17
	v_mul_f32_e32 v17, 0xbfb8aa3b, v17
	v_exp_f32_e32 v17, v17
	v_mov_b32_e32 v19, v13
	v_add_f32_e32 v17, 1.0, v17
	v_rcp_f32_e32 v20, v17
	v_mul_f32_e32 v17, 0x3d372713, v8
	v_mul_f32_e32 v17, v8, v17
	v_fma_f32 v17, v8, v17, v8
	v_mul_f32_e32 v17, 0x3fcc422a, v17
	v_mul_f32_e32 v17, 0xbfb8aa3b, v17
	v_exp_f32_e32 v17, v17
	s_nop 0
	v_add_f32_e32 v17, 1.0, v17
	v_rcp_f32_e32 v22, v17
	v_mul_f32_e32 v17, 0x3d372713, v13
	v_mul_f32_e32 v17, v13, v17
	v_fmac_f32_e32 v19, v19, v17
	v_mul_f32_e32 v17, 0x3fcc422a, v19
	v_mul_f32_e32 v17, 0xbfb8aa3b, v17
	v_exp_f32_e32 v17, v17
	v_mov_b32_e32 v19, v9
	v_add_f32_e32 v17, 1.0, v17
	v_rcp_f32_e32 v21, v17
	v_mul_f32_e32 v17, 0x3d372713, v9
	v_mul_f32_e32 v17, v9, v17
	v_fmac_f32_e32 v19, v19, v17
	v_mul_f32_e32 v17, 0x3fcc422a, v19
	v_mul_f32_e32 v17, 0xbfb8aa3b, v17
	v_exp_f32_e32 v17, v17
	v_pk_mul_f32 v[12:13], v[12:13], v[20:21]
	v_add_f32_e32 v17, 1.0, v17
	v_rcp_f32_e32 v23, v17
	v_mul_f32_e32 v17, 0x3d372713, v14
	v_mul_f32_e32 v17, v14, v17
	v_fma_f32 v17, v14, v17, v14
	v_mul_f32_e32 v17, 0x3fcc422a, v17
	v_mul_f32_e32 v17, 0xbfb8aa3b, v17
	v_exp_f32_e32 v17, v17
	v_pk_mul_f32 v[8:9], v[8:9], v[22:23]
	v_add_f32_e32 v17, 1.0, v17
	v_rcp_f32_e32 v24, v17
	v_mul_f32_e32 v17, 0x3d372713, v10
	v_mul_f32_e32 v17, v10, v17
	v_fma_f32 v17, v10, v17, v10
	v_mul_f32_e32 v17, 0x3fcc422a, v17
	v_mul_f32_e32 v17, 0xbfb8aa3b, v17
	v_exp_f32_e32 v17, v17
	s_nop 0
	v_add_f32_e32 v17, 1.0, v17
	v_rcp_f32_e32 v26, v17
	v_mul_f32_e32 v17, 0x3d372713, v15
	v_mul_f32_e32 v17, v15, v17
	v_fma_f32 v17, v15, v17, v15
	v_mul_f32_e32 v17, 0x3fcc422a, v17
	v_mul_f32_e32 v17, 0xbfb8aa3b, v17
	v_exp_f32_e32 v17, v17
	s_nop 0
	v_add_f32_e32 v17, 1.0, v17
	v_rcp_f32_e32 v25, v17
	v_mul_f32_e32 v17, 0x3d372713, v11
	v_mul_f32_e32 v17, v11, v17
	v_fma_f32 v17, v11, v17, v11
	v_mul_f32_e32 v17, 0x3fcc422a, v17
	v_mul_f32_e32 v17, 0xbfb8aa3b, v17
	v_exp_f32_e32 v17, v17
	v_pk_mul_f32 v[14:15], v[14:15], v[24:25]
	v_add_f32_e32 v17, 1.0, v17
	v_rcp_f32_e32 v27, v17
	s_nop 0
	v_pk_mul_f32 v[10:11], v[10:11], v[26:27]

; __device__ __forceinline__ unsigned cvt_pk_bf16(float lo, float hi) { unsigned r; asm volatile("v_cvt_pk_bf16_f32 %0, %1, %2" : "=v"(r) : "v"(lo), "v"(hi)); return r; }
; #define EPI_FOR_ROWS() _Pragma("unroll") for (int ai = 0; ai < 2; ++ai) _Pragma("unroll") for (int m = 0; m < 4; ++m)
; __device__ __forceinline__ float row_rstd(const float* ssq, int row, int fq) {
;     const f32x4 q = *(const f32x4*)(ssq + (size_t)row * 16 + 4 * fq); float s = (q[0] + q[1]) + (q[2] + q[3]);
;     s += __shfl_xor(s, 16); s += __shfl_xor(s, 32); return rsqrtf(s * (1.0f / 1024.0f) + EPS);
;     __device__ __forceinline__ void operator()(f32x4 (&acc)[2][2][4][2], const Unit& u, int wr, int wc, int fr, int fq) const {
;     ...
;         const int row0 = u.pm * 256 + wr * 64 + fr, ch = u.pn * 64 + wc * 16 + fq * 4;
;         EPI_FOR_ROWS() { const int row = row0 + ai * 128 + m * 16; const float rs = row_rstd(ssq, row, fq);
;             acc[ai][0][m][0] = (acc[ai][0][m][0] * rs) * (acc[ai][0][m][1] * rs); acc[ai][1][m][0] *= rs;
;             const f32x4 uu = acc[ai][1][m][1] * rs; u32x2 w; w.x = cvt_pk_bf16(uu[0], uu[1]); w.y = cvt_pk_bf16(uu[2], uu[3]);
;             *(u32x2*)(a2 + ((size_t)(ch >> 4) * 2048 + (row >> 4)) * 384 + (row & 15) * 16 + (ch & 15)) = w; }
.LBB0_587:
	s_lshl_b32 s8, s12, 8
	v_mov_b32_e32 v134, v148
	s_add_i32 s8, s8, s54
	v_and_b32_e32 v133, 64, v207
	v_mov_b32_e32 v146, v149
	v_add_u32_e32 v132, s8, v134
	s_lshl_b32 s8, s13, 6
	v_xor_b32_e32 v131, 16, v207
	v_add_u32_e32 v133, 64, v133
	s_or_b32 s8, s8, s62
	v_lshlrev_b32_e32 v128, 2, v146
	v_cmp_lt_i32_e32 vcc, v131, v133
	v_xor_b32_e32 v135, 32, v207
	v_add_u32_e32 v130, s8, v128
	v_cndmask_b32_e32 v131, v207, v131, vcc
	v_cmp_lt_i32_e32 vcc, v135, v133
	v_ashrrev_i32_e32 v136, 4, v130
	v_ashrrev_i32_e32 v137, 31, v136
	v_cndmask_b32_e32 v133, v207, v135, vcc
	v_lshlrev_b32_e32 v135, 2, v133
	v_ashrrev_i32_e32 v133, 31, v132
	v_ashrrev_i32_e32 v129, 31, v128
	v_lshlrev_b64 v[138:139], 11, v[136:137]
	v_lshlrev_b64 v[136:137], 6, v[132:133]
	v_lshl_add_u64 v[136:137], s[20:21], 0, v[136:137]
	v_lshlrev_b64 v[140:141], 2, v[128:129]
	v_lshl_add_u64 v[136:137], v[136:137], 0, v[140:141]
	global_load_dwordx4 v[182:185], v[136:137], off
	global_load_dwordx4 v[186:189], v[136:137], off offset:1024
	global_load_dwordx4 v[190:193], v[136:137], off offset:2048
	global_load_dwordx4 v[194:197], v[136:137], off offset:3072
	v_mov_b32_e32 v200, 0x2000
	v_mov_b32_e32 v201, 0
	v_lshl_add_u64 v[198:199], v[136:137], 0, v[200:201]
	global_load_dwordx4 v[198:201], v[198:199], off
	v_mov_b32_e32 v204, 0x2400
	v_mov_b32_e32 v205, 0
	v_lshl_add_u64 v[202:203], v[136:137], 0, v[204:205]
	global_load_dwordx4 v[202:205], v[202:203], off
	v_mov_b32_e32 v216, 0x2800
	v_mov_b32_e32 v217, 0
	v_lshl_add_u64 v[214:215], v[136:137], 0, v[216:217]
	global_load_dwordx4 v[214:217], v[214:215], off
	v_mov_b32_e32 v220, 0x2c00
	v_mov_b32_e32 v221, 0
	v_lshl_add_u64 v[218:219], v[136:137], 0, v[220:221]
	global_load_dwordx4 v[218:221], v[218:219], off
	s_waitcnt vmcnt(0)
	v_mov_b32_e32 v142, v182
	v_mov_b32_e32 v143, v183
	v_mov_b32_e32 v144, v184
	v_mov_b32_e32 v145, v185
	v_lshlrev_b32_e32 v131, 2, v131
	v_readlane_b32 s8, v252, 40
	v_readlane_b32 s9, v252, 41
	v_mov_b32_e32 v136, v143
	v_mov_b32_e32 v137, v144
	v_mov_b32_e32 v143, v145
	v_pk_add_f32 v[136:137], v[136:137], v[142:143]
	v_mov_b64_e32 v[142:143], s[8:9]
	v_add_f32_e32 v129, v136, v137
	v_mov_b32_e32 v136, v129
	v_mov_b32_e32 v222, v129
	s_nop 1
	v_permlane16_swap_b32_e32 v136, v222
	s_waitcnt lgkmcnt(0)
	v_add_f32_e32 v129, v136, v222
	v_mov_b32_e32 v136, v129
	v_mov_b32_e32 v222, v129
	s_nop 1
	v_permlane32_swap_b32_e32 v136, v222
	s_waitcnt lgkmcnt(0)
	v_add_f32_e32 v129, v136, v222
	v_fmamk_f32 v129, v129, 0x3a800000, v208
	v_cmp_gt_f32_e32 vcc, s44, v129
	v_mul_f32_e32 v136, 0x4b800000, v129
	s_nop 0
	v_cndmask_b32_e32 v129, v129, v136, vcc
	v_rsq_f32_e32 v129, v129
	s_nop 0
	v_mul_f32_e32 v136, 0x45800000, v129
	v_cndmask_b32_e32 v136, v129, v136, vcc
	v_pk_mul_f32 v[126:127], v[126:127], v[136:137] op_sel_hi:[1,0]
	v_pk_mul_f32 v[124:125], v[124:125], v[136:137] op_sel_hi:[1,0]
	v_lshlrev_b32_e32 v129, 3, v146
	v_cvt_pk_bf16_f32 v124, v124, v125
	v_cvt_pk_bf16_f32 v125, v126, v127
	v_ashrrev_i32_e32 v126, 4, v132
	v_ashrrev_i32_e32 v127, 31, v126
	v_lshl_add_u64 v[126:127], v[138:139], 0, v[126:127]
	v_mad_u64_u32 v[144:145], s[8:9], v126, s41, v[142:143]
	v_lshlrev_b32_e32 v126, 5, v134
	v_mad_i32_i24 v145, v127, s41, v145
	v_and_b32_e32 v160, 0x1e0, v126
	v_lshl_add_u64 v[126:127], v[144:145], 0, v[160:161]
	v_and_b32_e32 v144, 24, v129
	v_mov_b32_e32 v145, v161
	v_lshl_add_u64 v[126:127], v[126:127], 0, v[144:145]
	global_store_dwordx2 v[126:127], v[124:125], off
	v_add_u32_e32 v124, 16, v132
	v_ashrrev_i32_e32 v125, 31, v124
	v_lshlrev_b64 v[126:127], 6, v[124:125]
	v_lshl_add_u64 v[126:127], s[20:21], 0, v[126:127]
	v_lshl_add_u64 v[126:127], v[126:127], 0, v[140:141]
	v_mov_b32_e32 v178, v186
	v_mov_b32_e32 v179, v187
	v_mov_b32_e32 v180, v188
	v_mov_b32_e32 v181, v189
	v_mov_b32_e32 v126, v179
	v_mov_b32_e32 v127, v180
	v_mov_b32_e32 v179, v181
	v_pk_add_f32 v[126:127], v[126:127], v[178:179]
	s_nop 0
	v_add_f32_e32 v126, v126, v127
	v_mov_b32_e32 v127, v126
	v_mov_b32_e32 v222, v126
	s_nop 1
	v_permlane16_swap_b32_e32 v127, v222
	s_waitcnt lgkmcnt(0)
	v_add_f32_e32 v126, v127, v222
	v_mov_b32_e32 v127, v126
	v_mov_b32_e32 v222, v126
	s_nop 1
	v_permlane32_swap_b32_e32 v127, v222
	s_waitcnt lgkmcnt(0)
	v_add_f32_e32 v126, v127, v222
	v_fmamk_f32 v126, v126, 0x3a800000, v208
	v_cmp_gt_f32_e32 vcc, s44, v126
	v_mul_f32_e32 v127, 0x4b800000, v126
	s_nop 0
	v_cndmask_b32_e32 v126, v126, v127, vcc
	v_rsq_f32_e32 v126, v126
	s_nop 0
	v_mul_f32_e32 v127, 0x45800000, v126
	v_cndmask_b32_e32 v126, v126, v127, vcc
	v_pk_mul_f32 v[122:123], v[122:123], v[126:127] op_sel_hi:[1,0]
	v_pk_mul_f32 v[120:121], v[120:121], v[126:127] op_sel_hi:[1,0]
	s_nop 0
	v_cvt_pk_bf16_f32 v120, v120, v121
	v_cvt_pk_bf16_f32 v121, v122, v123
	v_ashrrev_i32_e32 v122, 4, v124
	v_ashrrev_i32_e32 v123, 31, v122
	v_lshl_add_u64 v[122:123], v[138:139], 0, v[122:123]
	v_mad_u64_u32 v[146:147], s[8:9], v122, s41, v[142:143]
	v_mad_i32_i24 v147, v123, s41, v147
	v_lshl_add_u64 v[122:123], v[146:147], 0, v[160:161]
	v_lshl_add_u64 v[122:123], v[122:123], 0, v[144:145]
	global_store_dwordx2 v[122:123], v[120:121], off
	v_add_u32_e32 v120, 32, v132
	v_ashrrev_i32_e32 v121, 31, v120
	v_lshlrev_b64 v[122:123], 6, v[120:121]
	v_lshl_add_u64 v[122:123], s[20:21], 0, v[122:123]
	v_lshl_add_u64 v[122:123], v[122:123], 0, v[140:141]
	v_mov_b32_e32 v178, v190
	v_mov_b32_e32 v179, v191
	v_mov_b32_e32 v180, v192
	v_mov_b32_e32 v181, v193
	v_mov_b32_e32 v122, v179
	v_mov_b32_e32 v123, v180
	v_mov_b32_e32 v179, v181
	v_pk_add_f32 v[122:123], v[122:123], v[178:179]
	s_nop 0
	v_add_f32_e32 v122, v122, v123
	v_mov_b32_e32 v123, v122
	v_mov_b32_e32 v222, v122
	s_nop 1
	v_permlane16_swap_b32_e32 v123, v222
	s_waitcnt lgkmcnt(0)
; __device__ __forceinline__ unsigned cvt_pk_bf16(float lo, float hi) { unsigned r; asm volatile("v_cvt_pk_bf16_f32 %0, %1, %2" : "=v"(r) : "v"(lo), "v"(hi)); return r; }
; #define EPI_FOR_ROWS() _Pragma("unroll") for (int ai = 0; ai < 2; ++ai) _Pragma("unroll") for (int m = 0; m < 4; ++m)
; __device__ __forceinline__ float row_rstd(const float* ssq, int row, int fq) {
;     const f32x4 q = *(const f32x4*)(ssq + (size_t)row * 16 + 4 * fq); float s = (q[0] + q[1]) + (q[2] + q[3]);
;     s += __shfl_xor(s, 16); s += __shfl_xor(s, 32); return rsqrtf(s * (1.0f / 1024.0f) + EPS);
;     __device__ __forceinline__ void operator()(f32x4 (&acc)[2][2][4][2], const Unit& u, int wr, int wc, int fr, int fq) const {
;     ...
;         const int row0 = u.pm * 256 + wr * 64 + fr, ch = u.pn * 64 + wc * 16 + fq * 4;
;         EPI_FOR_ROWS() { const int row = row0 + ai * 128 + m * 16; const float rs = row_rstd(ssq, row, fq);
;             acc[ai][0][m][0] = (acc[ai][0][m][0] * rs) * (acc[ai][0][m][1] * rs); acc[ai][1][m][0] *= rs;
;             const f32x4 uu = acc[ai][1][m][1] * rs; u32x2 w; w.x = cvt_pk_bf16(uu[0], uu[1]); w.y = cvt_pk_bf16(uu[2], uu[3]);
;             *(u32x2*)(a2 + ((size_t)(ch >> 4) * 2048 + (row >> 4)) * 384 + (row & 15) * 16 + (ch & 15)) = w; }
	v_add_f32_e32 v122, v123, v222
	v_mov_b32_e32 v123, v122
	v_mov_b32_e32 v222, v122
	s_nop 1
	v_permlane32_swap_b32_e32 v123, v222
	s_waitcnt lgkmcnt(0)
	v_add_f32_e32 v122, v123, v222
	v_fmamk_f32 v122, v122, 0x3a800000, v208
	v_cmp_gt_f32_e32 vcc, s44, v122
	v_mul_f32_e32 v123, 0x4b800000, v122
	s_nop 0
	v_cndmask_b32_e32 v122, v122, v123, vcc
	v_rsq_f32_e32 v122, v122
	s_nop 0
	v_mul_f32_e32 v123, 0x45800000, v122
	v_cndmask_b32_e32 v122, v122, v123, vcc
	v_pk_mul_f32 v[118:119], v[118:119], v[122:123] op_sel_hi:[1,0]
	v_pk_mul_f32 v[116:117], v[116:117], v[122:123] op_sel_hi:[1,0]
	s_nop 0
	v_cvt_pk_bf16_f32 v116, v116, v117
	v_cvt_pk_bf16_f32 v117, v118, v119
	v_ashrrev_i32_e32 v118, 4, v120
	v_ashrrev_i32_e32 v119, 31, v118
	v_lshl_add_u64 v[118:119], v[138:139], 0, v[118:119]
	v_mad_u64_u32 v[146:147], s[8:9], v118, s41, v[142:143]
	v_mad_i32_i24 v147, v119, s41, v147
	v_lshl_add_u64 v[118:119], v[146:147], 0, v[160:161]
	v_lshl_add_u64 v[118:119], v[118:119], 0, v[144:145]
	global_store_dwordx2 v[118:119], v[116:117], off
	v_add_u32_e32 v116, 48, v132
	v_ashrrev_i32_e32 v117, 31, v116
	v_lshlrev_b64 v[118:119], 6, v[116:117]
	v_lshl_add_u64 v[118:119], s[20:21], 0, v[118:119]
	v_lshl_add_u64 v[118:119], v[118:119], 0, v[140:141]
	v_mov_b32_e32 v178, v194
	v_mov_b32_e32 v179, v195
	v_mov_b32_e32 v180, v196
	v_mov_b32_e32 v181, v197
	v_mov_b32_e32 v118, v179
	v_mov_b32_e32 v119, v180
	v_mov_b32_e32 v179, v181
	v_pk_add_f32 v[118:119], v[118:119], v[178:179]
	s_nop 0
	v_add_f32_e32 v118, v118, v119
	v_mov_b32_e32 v119, v118
	v_mov_b32_e32 v222, v118
	s_nop 1
	v_permlane16_swap_b32_e32 v119, v222
	s_waitcnt lgkmcnt(0)
	v_add_f32_e32 v118, v119, v222
	v_mov_b32_e32 v119, v118
	v_mov_b32_e32 v222, v118
	s_nop 1
	v_permlane32_swap_b32_e32 v119, v222
	s_waitcnt lgkmcnt(0)
	v_add_f32_e32 v118, v119, v222
	v_fmamk_f32 v118, v118, 0x3a800000, v208
	v_cmp_gt_f32_e32 vcc, s44, v118
	v_mul_f32_e32 v119, 0x4b800000, v118
	s_nop 0
	v_cndmask_b32_e32 v118, v118, v119, vcc
	v_rsq_f32_e32 v118, v118
	s_nop 0
	v_mul_f32_e32 v119, 0x45800000, v118
	v_cndmask_b32_e32 v118, v118, v119, vcc
	v_pk_mul_f32 v[110:111], v[110:111], v[118:119] op_sel_hi:[1,0]
	v_pk_mul_f32 v[108:109], v[108:109], v[118:119] op_sel_hi:[1,0]
	v_pk_mul_f32 v[112:113], v[112:113], v[118:119] op_sel_hi:[1,0]
	v_cvt_pk_bf16_f32 v108, v108, v109
	v_cvt_pk_bf16_f32 v109, v110, v111
	v_ashrrev_i32_e32 v110, 4, v116
	v_ashrrev_i32_e32 v111, 31, v110
	v_pk_mul_f32 v[104:105], v[104:105], v[118:119] op_sel_hi:[1,0]
	v_lshl_add_u64 v[110:111], v[138:139], 0, v[110:111]
	v_pk_mul_f32 v[104:105], v[112:113], v[104:105]
	v_mad_u64_u32 v[112:113], s[8:9], v110, s41, v[142:143]
	v_mad_i32_i24 v113, v111, s41, v113
	v_lshl_add_u64 v[110:111], v[112:113], 0, v[160:161]
	v_lshl_add_u64 v[110:111], v[110:111], 0, v[144:145]
	global_store_dwordx2 v[110:111], v[108:109], off
	v_add_u32_e32 v108, 0x80, v132
	v_ashrrev_i32_e32 v109, 31, v108
	v_lshlrev_b64 v[110:111], 6, v[108:109]
	v_lshl_add_u64 v[110:111], s[20:21], 0, v[110:111]
	v_lshl_add_u64 v[110:111], v[110:111], 0, v[140:141]
	v_mov_b32_e32 v110, v198
	v_mov_b32_e32 v111, v199
	v_mov_b32_e32 v112, v200
	v_mov_b32_e32 v113, v201
	v_pk_mul_f32 v[114:115], v[114:115], v[118:119] op_sel_hi:[1,0]
	v_pk_mul_f32 v[106:107], v[106:107], v[118:119] op_sel_hi:[1,0]
	s_nop 0
	v_pk_mul_f32 v[106:107], v[114:115], v[106:107]
	v_mov_b32_e32 v114, v111
	v_mov_b32_e32 v115, v112
	v_mov_b32_e32 v111, v113
	v_pk_add_f32 v[110:111], v[114:115], v[110:111]
	s_nop 0
	v_add_f32_e32 v110, v110, v111
	v_mov_b32_e32 v111, v110
	v_mov_b32_e32 v222, v110
	s_nop 1
	v_permlane16_swap_b32_e32 v111, v222
	s_waitcnt lgkmcnt(0)
	v_add_f32_e32 v110, v111, v222
	v_mov_b32_e32 v111, v110
	v_mov_b32_e32 v222, v110
	s_nop 1
	v_permlane32_swap_b32_e32 v111, v222
	s_waitcnt lgkmcnt(0)
	v_add_f32_e32 v110, v111, v222
	v_fmamk_f32 v110, v110, 0x3a800000, v208
	v_cmp_gt_f32_e32 vcc, s44, v110
	v_mul_f32_e32 v111, 0x4b800000, v110
	s_nop 0
	v_cndmask_b32_e32 v110, v110, v111, vcc
	v_rsq_f32_e32 v110, v110
	s_nop 0
	v_mul_f32_e32 v111, 0x45800000, v110
	v_cndmask_b32_e32 v110, v110, v111, vcc
	v_pk_mul_f32 v[102:103], v[102:103], v[110:111] op_sel_hi:[1,0]
	v_pk_mul_f32 v[100:101], v[100:101], v[110:111] op_sel_hi:[1,0]
	s_nop 0
	v_cvt_pk_bf16_f32 v100, v100, v101
	v_cvt_pk_bf16_f32 v101, v102, v103
	v_ashrrev_i32_e32 v102, 4, v108
	v_ashrrev_i32_e32 v103, 31, v102
	v_lshl_add_u64 v[102:103], v[138:139], 0, v[102:103]
	v_mad_u64_u32 v[112:113], s[8:9], v102, s41, v[142:143]
	v_mad_i32_i24 v113, v103, s41, v113
	v_lshl_add_u64 v[102:103], v[112:113], 0, v[160:161]
	v_lshl_add_u64 v[102:103], v[102:103], 0, v[144:145]
	global_store_dwordx2 v[102:103], v[100:101], off
	v_add_u32_e32 v100, 0x90, v132
	v_ashrrev_i32_e32 v101, 31, v100
	v_lshlrev_b64 v[102:103], 6, v[100:101]
	v_lshl_add_u64 v[102:103], s[20:21], 0, v[102:103]
	v_lshl_add_u64 v[102:103], v[102:103], 0, v[140:141]
	v_mov_b32_e32 v112, v202
	v_mov_b32_e32 v113, v203
	v_mov_b32_e32 v114, v204
	v_mov_b32_e32 v115, v205
	v_mov_b32_e32 v102, v113
	v_mov_b32_e32 v103, v114
	v_mov_b32_e32 v113, v115
	v_pk_add_f32 v[102:103], v[102:103], v[112:113]
	s_nop 0
	v_add_f32_e32 v102, v102, v103
	v_mov_b32_e32 v103, v102
	v_mov_b32_e32 v222, v102
	s_nop 1
	v_permlane16_swap_b32_e32 v103, v222
	s_waitcnt lgkmcnt(0)
; #define LAS __attribute__((address_space(3)))
; __device__ __forceinline__ unsigned cvt_pk_bf16(float lo, float hi) { unsigned r; asm volatile("v_cvt_pk_bf16_f32 %0, %1, %2" : "=v"(r) : "v"(lo), "v"(hi)); return r; }
; #define EPI_FOR_ROWS() _Pragma("unroll") for (int ai = 0; ai < 2; ++ai) _Pragma("unroll") for (int m = 0; m < 4; ++m)
;     __device__ __forceinline__ void operator()(f32x4 (&acc)[2][2][4][2], const Unit& u, int wr, int wc, int fr, int fq) const {
;     ...
;         EPI_FOR_ROWS() { const int row = row0 + ai * 128 + m * 16; const float rs = row_rstd(ssq, row, fq);
;             acc[ai][0][m][0] = (acc[ai][0][m][0] * rs) * (acc[ai][0][m][1] * rs); acc[ai][1][m][0] *= rs;
;             const f32x4 uu = acc[ai][1][m][1] * rs; u32x2 w; w.x = cvt_pk_bf16(uu[0], uu[1]); w.y = cvt_pk_bf16(uu[2], uu[3]);
;             *(u32x2*)(a2 + ((size_t)(ch >> 4) * 2048 + (row >> 4)) * 384 + (row & 15) * 16 + (ch & 15)) = w; }
;         if (fr >= 14) {
; #pragma unroll
;             for (int ai = 0; ai < 2; ++ai) *(LAS f32x4*)(hl + ((((ai * 2 + wr) * 4 + wc) * 2 + (fr - 14)) * 16 + fq * 4)) = acc[ai][0][3][0];
;             if (wr == 1) *(f32x4*)(tail + ((size_t)u.pm * 2 + (fr - 14)) * 512 + ch) = acc[1][0][3][0]; }
	v_add_f32_e32 v102, v103, v222
	v_mov_b32_e32 v103, v102
	v_mov_b32_e32 v222, v102
	s_nop 1
	v_permlane32_swap_b32_e32 v103, v222
	s_waitcnt lgkmcnt(0)
	v_add_f32_e32 v102, v103, v222
	v_fmamk_f32 v102, v102, 0x3a800000, v208
	v_cmp_gt_f32_e32 vcc, s44, v102
	v_mul_f32_e32 v103, 0x4b800000, v102
	s_nop 0
	v_cndmask_b32_e32 v102, v102, v103, vcc
	v_rsq_f32_e32 v102, v102
	s_nop 0
	v_mul_f32_e32 v103, 0x45800000, v102
	v_cndmask_b32_e32 v112, v102, v103, vcc
	v_pk_mul_f32 v[98:99], v[98:99], v[112:113] op_sel_hi:[1,0]
	v_pk_mul_f32 v[96:97], v[96:97], v[112:113] op_sel_hi:[1,0]
	s_nop 0
	v_cvt_pk_bf16_f32 v96, v96, v97
	v_cvt_pk_bf16_f32 v97, v98, v99
	v_ashrrev_i32_e32 v98, 4, v100
	v_ashrrev_i32_e32 v99, 31, v98
	v_lshl_add_u64 v[98:99], v[138:139], 0, v[98:99]
	v_mad_u64_u32 v[102:103], s[8:9], v98, s41, v[142:143]
	v_mad_i32_i24 v103, v99, s41, v103
	v_lshl_add_u64 v[98:99], v[102:103], 0, v[160:161]
	v_add_u32_e32 v102, 0xa0, v132
	v_lshl_add_u64 v[98:99], v[98:99], 0, v[144:145]
	v_ashrrev_i32_e32 v103, 31, v102
	global_store_dwordx2 v[98:99], v[96:97], off
	v_lshlrev_b64 v[96:97], 6, v[102:103]
	v_lshl_add_u64 v[96:97], s[20:21], 0, v[96:97]
	v_lshl_add_u64 v[96:97], v[96:97], 0, v[140:141]
	v_mov_b32_e32 v96, v214
	v_mov_b32_e32 v97, v215
	v_mov_b32_e32 v98, v216
	v_mov_b32_e32 v99, v217
	v_mov_b32_e32 v114, v97
	v_mov_b32_e32 v115, v98
	v_mov_b32_e32 v97, v99
	v_pk_add_f32 v[96:97], v[114:115], v[96:97]
	v_add_u32_e32 v114, 0xb0, v132
	v_add_f32_e32 v96, v96, v97
	v_mov_b32_e32 v97, v96
	v_mov_b32_e32 v222, v96
	s_nop 1
	v_permlane16_swap_b32_e32 v97, v222
	v_ashrrev_i32_e32 v115, 31, v114
	s_waitcnt lgkmcnt(0)
	v_add_f32_e32 v96, v97, v222
	v_mov_b32_e32 v97, v96
	v_mov_b32_e32 v222, v96
	s_nop 1
	v_permlane32_swap_b32_e32 v97, v222
	s_waitcnt lgkmcnt(0)
	v_add_f32_e32 v96, v97, v222
	v_fmamk_f32 v96, v96, 0x3a800000, v208
	v_cmp_gt_f32_e32 vcc, s44, v96
	v_mul_f32_e32 v97, 0x4b800000, v96
	s_nop 0
	v_cndmask_b32_e32 v96, v96, v97, vcc
	v_rsq_f32_e32 v96, v96
	s_nop 0
	v_mul_f32_e32 v97, 0x45800000, v96
	v_cndmask_b32_e32 v146, v96, v97, vcc
	v_pk_mul_f32 v[94:95], v[94:95], v[146:147] op_sel_hi:[1,0]
	v_pk_mul_f32 v[92:93], v[92:93], v[146:147] op_sel_hi:[1,0]
	s_nop 0
	v_cvt_pk_bf16_f32 v92, v92, v93
	v_cvt_pk_bf16_f32 v93, v94, v95
	v_ashrrev_i32_e32 v94, 4, v102
	v_ashrrev_i32_e32 v95, 31, v94
	v_lshl_add_u64 v[94:95], v[138:139], 0, v[94:95]
	v_mad_u64_u32 v[96:97], s[8:9], v94, s41, v[142:143]
	v_mad_i32_i24 v97, v95, s41, v97
	v_lshl_add_u64 v[94:95], v[96:97], 0, v[160:161]
	v_lshl_add_u64 v[94:95], v[94:95], 0, v[144:145]
	global_store_dwordx2 v[94:95], v[92:93], off
	v_lshlrev_b64 v[92:93], 6, v[114:115]
	v_lshl_add_u64 v[92:93], s[20:21], 0, v[92:93]
	v_lshl_add_u64 v[92:93], v[92:93], 0, v[140:141]
	v_mov_b32_e32 v92, v218
	v_mov_b32_e32 v93, v219
	v_mov_b32_e32 v94, v220
	v_mov_b32_e32 v95, v221
	v_mov_b32_e32 v96, v93
	v_mov_b32_e32 v97, v94
	v_mov_b32_e32 v93, v95
	v_pk_add_f32 v[92:93], v[96:97], v[92:93]
	s_nop 0
	v_add_f32_e32 v92, v92, v93
	v_mov_b32_e32 v93, v92
	v_mov_b32_e32 v222, v92
	s_nop 1
	v_permlane16_swap_b32_e32 v93, v222
	s_waitcnt lgkmcnt(0)
	v_add_f32_e32 v92, v93, v222
	v_mov_b32_e32 v93, v92
	v_mov_b32_e32 v222, v92
	s_nop 1
	v_permlane32_swap_b32_e32 v93, v222
	s_waitcnt lgkmcnt(0)
	v_add_f32_e32 v92, v93, v222
	v_fmamk_f32 v92, v92, 0x3a800000, v208
	v_cmp_gt_f32_e32 vcc, s44, v92
	v_mul_f32_e32 v93, 0x4b800000, v92
	s_nop 0
	v_cndmask_b32_e32 v92, v92, v93, vcc
	v_rsq_f32_e32 v92, v92
	s_nop 0
	v_mul_f32_e32 v93, 0x45800000, v92
	v_cndmask_b32_e32 v140, v92, v93, vcc
	v_pk_mul_f32 v[82:83], v[82:83], v[140:141] op_sel_hi:[1,0]
	v_pk_mul_f32 v[80:81], v[80:81], v[140:141] op_sel_hi:[1,0]
	v_pk_mul_f32 v[88:89], v[88:89], v[140:141] op_sel_hi:[1,0]
	v_cvt_pk_bf16_f32 v80, v80, v81
	v_cvt_pk_bf16_f32 v81, v82, v83
	v_ashrrev_i32_e32 v82, 4, v114
	v_ashrrev_i32_e32 v83, 31, v82
	v_pk_mul_f32 v[84:85], v[84:85], v[140:141] op_sel_hi:[1,0]
	v_lshl_add_u64 v[82:83], v[138:139], 0, v[82:83]
	v_pk_mul_f32 v[84:85], v[88:89], v[84:85]
	v_mad_u64_u32 v[88:89], s[8:9], v82, s41, v[142:143]
	v_mad_i32_i24 v89, v83, s41, v89
	v_lshl_add_u64 v[82:83], v[88:89], 0, v[160:161]
	v_lshl_add_u64 v[82:83], v[82:83], 0, v[144:145]
	v_pk_mul_f32 v[90:91], v[90:91], v[140:141] op_sel_hi:[1,0]
	v_pk_mul_f32 v[86:87], v[86:87], v[140:141] op_sel_hi:[1,0]
	global_store_dwordx2 v[82:83], v[80:81], off
	v_cndmask_b32_e64 v80, 0, 1, s[0:1]
	v_pk_mul_f32 v[86:87], v[90:91], v[86:87]
	v_cmp_lt_i32_e32 vcc, 13, v134
	v_cmp_ne_u32_e64 s[8:9], 1, v80
	s_and_saveexec_b64 s[10:11], vcc
	s_cbranch_execz .LBB0_590
	v_lshlrev_b32_e32 v80, 6, v134
	v_lshlrev_b32_e32 v81, 2, v128
	v_add3_u32 v80, s65, v80, v81
	v_add_u32_e32 v81, 0xfffffc80, v80
	s_and_b64 vcc, exec, s[8:9]
	ds_write_b128 v81, v[104:107]
	ds_write_b128 v80, v[84:87] offset:128
	s_cbranch_vccnz .LBB0_590
	s_ashr_i32 s13, s12, 31
	s_lshl_b64 s[68:69], s[12:13], 12
	v_readlane_b32 s84, v252, 23
	v_add_u32_e32 v160, -14, v134
	v_readlane_b32 s85, v252, 24
	s_add_u32 s68, s84, s68
	s_addc_u32 s69, s85, s69
	v_lshlrev_b64 v[80:81], 11, v[160:161]
	v_lshl_add_u64 v[80:81], s[68:69], 0, v[80:81]
	v_ashrrev_i32_e32 v131, 31, v130
	v_lshl_add_u64 v[80:81], v[130:131], 2, v[80:81]
	global_store_dwordx4 v[80:81], v[84:87], off

; __device__ __forceinline__ unsigned cvt_pk_bf16(float lo, float hi) { unsigned r; asm volatile("v_cvt_pk_bf16_f32 %0, %1, %2" : "=v"(r) : "v"(lo), "v"(hi)); return r; }
; __device__ __forceinline__ void UNPACK8(const u32x4 q, float (&f)[8]) { f[0] = bflo(q.x); f[1] = bfhi(q.x); f[2] = bflo(q.y); f[3] = bfhi(q.y); f[4] = bflo(q.z); f[5] = bfhi(q.z); f[6] = bflo(q.w); f[7] = bfhi(q.w); }
; #define EPI_FOR_ROWS() _Pragma("unroll") for (int ai = 0; ai < 2; ++ai) _Pragma("unroll") for (int m = 0; m < 4; ++m)
;     __device__ __forceinline__ void operator()(const f32x4 (&acc)[2][2][4][2], const Unit& u, int wr, int wc, int fr, int fq) const {
;         EPI_ROWCOL();
;         EPI_FOR_ROWS() {
;             const int row = row0 + ai * 128 + m * 16; float ss = 0.f;
; #pragma unroll
;             for (int bj = 0; bj < 2; ++bj) { const int col = col0 + bj * 128; const size_t off = (size_t)row * 1024 + col;
;                 const u32x4 xw = *(const u32x4*)(xb + off); float xo[8]; UNPACK8(xw, xo);
;                 const f32x4 x0 = (f32x4){xo[0], xo[1], xo[2], xo[3]} + acc[ai][bj][m][0], x1 = (f32x4){xo[4], xo[5], xo[6], xo[7]} + acc[ai][bj][m][1];
;                 ss += (x0[0] * x0[0] + x0[1] * x0[1]) + (x0[2] * x0[2] + x0[3] * x0[3]) + (x1[0] * x1[0] + x1[1] * x1[1]) + (x1[2] * x1[2] + x1[3] * x1[3]);
;                 u32x4 w; w.x = cvt_pk_bf16(x0[0], x0[1]); w.y = cvt_pk_bf16(x0[2], x0[3]); w.z = cvt_pk_bf16(x1[0], x1[1]); w.w = cvt_pk_bf16(x1[2], x1[3]);
;                 *(u32x4*)(xb + off) = w; }
;             ss += __shfl_xor(ss, 16); ss += __shfl_xor(ss, 32);
;             if (fq == 0) ssq[(size_t)row * 16 + u.pn * 4 + wc] = ss;
;         }
.LBB0_946:
	v_lshl_add_u32 v130, s65, 8, v136
	v_ashrrev_i32_e32 v131, 31, v130
	v_lshl_or_b32 v128, s64, 8, v137
	v_lshlrev_b64 v[144:145], 11, v[130:131]
	v_ashrrev_i32_e32 v129, 31, v128
	v_lshl_add_u64 v[144:145], s[22:23], 0, v[144:145]
	v_lshl_add_u64 v[148:149], v[128:129], 1, v[144:145]
	global_load_dwordx4 v[156:159], v[148:149], off
	global_load_dwordx4 v[166:169], v[148:149], off offset:256
	s_mov_b32 s38, 0x8000
	s_mov_b32 s39, 0
	v_lshl_add_u64 v[182:183], v[148:149], 0, s[38:39]
	global_load_dwordx4 v[178:181], v[182:183], off
	global_load_dwordx4 v[182:185], v[182:183], off offset:256
	s_mov_b32 s38, 0x10000
	s_mov_b32 s39, 0
	v_lshl_add_u64 v[190:191], v[148:149], 0, s[38:39]
	global_load_dwordx4 v[186:189], v[190:191], off
	global_load_dwordx4 v[190:193], v[190:191], off offset:256
	s_mov_b32 s38, 0x18000
	s_mov_b32 s39, 0
	v_lshl_add_u64 v[198:199], v[148:149], 0, s[38:39]
	global_load_dwordx4 v[194:197], v[198:199], off
	global_load_dwordx4 v[198:201], v[198:199], off offset:256
	s_mov_b32 s38, 0x40000
	s_mov_b32 s39, 0
	v_lshl_add_u64 v[214:215], v[148:149], 0, s[38:39]
	global_load_dwordx4 v[202:205], v[214:215], off
	global_load_dwordx4 v[214:217], v[214:215], off offset:256
	s_mov_b32 s38, 0x48000
	s_mov_b32 s39, 0
	v_lshl_add_u64 v[222:223], v[148:149], 0, s[38:39]
	global_load_dwordx4 v[218:221], v[222:223], off
	global_load_dwordx4 v[222:225], v[222:223], off offset:256
	s_mov_b32 s38, 0x50000
	s_mov_b32 s39, 0
	v_lshl_add_u64 v[230:231], v[148:149], 0, s[38:39]
	global_load_dwordx4 v[226:229], v[230:231], off
	global_load_dwordx4 v[230:233], v[230:231], off offset:256
	s_mov_b32 s38, 0x58000
	s_mov_b32 s39, 0
	v_lshl_add_u64 v[238:239], v[148:149], 0, s[38:39]
	global_load_dwordx4 v[234:237], v[238:239], off
	global_load_dwordx4 v[238:241], v[238:239], off offset:256
	s_waitcnt vmcnt(0)
	v_mov_b32_e32 v144, v156
	v_mov_b32_e32 v145, v157
	v_mov_b32_e32 v146, v158
	v_mov_b32_e32 v147, v159
	s_lshl_b32 s38, s64, 2
	s_ashr_i32 s39, s38, 31
	v_lshlrev_b32_e32 v150, 16, v144
	v_and_b32_e32 v151, 0xffff0000, v144
	v_lshlrev_b32_e32 v144, 16, v145
	v_and_b32_e32 v145, 0xffff0000, v145
	v_lshlrev_b32_e32 v152, 16, v146
	v_and_b32_e32 v153, 0xffff0000, v146
	v_lshlrev_b32_e32 v146, 16, v147
	v_and_b32_e32 v147, 0xffff0000, v147
	v_pk_add_f32 v[126:127], v[126:127], v[144:145]
	v_pk_add_f32 v[124:125], v[124:125], v[150:151]
	v_pk_add_f32 v[144:145], v[122:123], v[146:147]
	v_pk_add_f32 v[122:123], v[120:121], v[152:153]
	v_mul_f32_e32 v120, v125, v125
	v_mul_f32_e32 v121, v127, v127
	v_fmac_f32_e32 v120, v124, v124
	v_fmac_f32_e32 v121, v126, v126
	v_add_f32_e32 v120, v120, v121
	v_mul_f32_e32 v121, v123, v123
	v_fmac_f32_e32 v121, v122, v122
	v_add_f32_e32 v120, v121, v120
	v_mul_f32_e32 v121, v145, v145
	v_fmac_f32_e32 v121, v144, v144
	v_add_f32_e32 v143, v121, v120
	v_cvt_pk_bf16_f32 v120, v124, v125
	v_cvt_pk_bf16_f32 v121, v126, v127
	v_cvt_pk_bf16_f32 v122, v122, v123
	v_cvt_pk_bf16_f32 v123, v144, v145
	global_store_dwordx4 v[148:149], v[120:123], off
	s_nop 1
	v_mov_b32_e32 v120, v166
	v_mov_b32_e32 v121, v167
	v_mov_b32_e32 v122, v168
	v_mov_b32_e32 v123, v169
	v_lshlrev_b32_e32 v124, 16, v120
	v_and_b32_e32 v125, 0xffff0000, v120
	v_lshlrev_b32_e32 v120, 16, v121
	v_and_b32_e32 v121, 0xffff0000, v121
	v_lshlrev_b32_e32 v126, 16, v122
	v_and_b32_e32 v127, 0xffff0000, v122
	v_lshlrev_b32_e32 v122, 16, v123
	v_and_b32_e32 v123, 0xffff0000, v123
	v_pk_add_f32 v[118:119], v[118:119], v[120:121]
	v_pk_add_f32 v[116:117], v[116:117], v[124:125]
	v_pk_add_f32 v[120:121], v[114:115], v[122:123]
	v_pk_add_f32 v[114:115], v[112:113], v[126:127]
	v_mul_f32_e32 v112, v117, v117
	v_mul_f32_e32 v113, v119, v119
	v_fmac_f32_e32 v112, v116, v116
	v_fmac_f32_e32 v113, v118, v118
	v_add_f32_e32 v112, v112, v113
	v_mul_f32_e32 v113, v115, v115
	v_fmac_f32_e32 v113, v114, v114
	v_add_f32_e32 v112, v113, v112
	v_mul_f32_e32 v113, v121, v121
	v_fmac_f32_e32 v113, v120, v120
	v_add_f32_e32 v112, v113, v112
	v_add_f32_e32 v122, v143, v112
	v_cvt_pk_bf16_f32 v112, v116, v117
	v_cvt_pk_bf16_f32 v113, v118, v119
	v_cvt_pk_bf16_f32 v114, v114, v115
	v_cvt_pk_bf16_f32 v115, v120, v121
	global_store_dwordx4 v[148:149], v[112:115], off offset:256
	s_nop 1
	v_and_b32_e32 v113, 64, v207
	v_xor_b32_e32 v112, 16, v207
	v_add_u32_e32 v113, 64, v113
	v_cmp_lt_i32_e32 vcc, v112, v113
	v_xor_b32_e32 v115, 32, v207
	s_nop 0
	v_cndmask_b32_e32 v112, v207, v112, vcc
	v_lshlrev_b32_e32 v114, 2, v112
	v_mov_b32_e32 v112, v122
	v_mov_b32_e32 v154, v122
	s_nop 1
	v_permlane16_swap_b32_e32 v112, v154
	v_cmp_lt_i32_e32 vcc, v115, v113
	s_waitcnt lgkmcnt(0)
	v_add_f32_e32 v112, v112, v154
	v_cndmask_b32_e32 v113, v207, v115, vcc
	v_lshlrev_b32_e32 v115, 2, v113
	v_mov_b32_e32 v113, v112
	v_mov_b32_e32 v154, v112
	s_nop 1
	v_permlane32_swap_b32_e32 v113, v154
	s_and_saveexec_b64 s[6:7], s[8:9]
	s_cbranch_execz .LBB0_948
	v_lshlrev_b64 v[116:117], 6, v[130:131]
	v_lshl_add_u64 v[116:117], s[18:19], 0, v[116:117]
	v_lshl_add_u64 v[116:117], s[38:39], 2, v[116:117]
	s_lshl_b32 s42, s28, 2
	s_mov_b32 s43, s36
	v_lshl_add_u64 v[116:117], v[116:117], 0, s[42:43]
	s_waitcnt lgkmcnt(0)
	v_add_f32_e32 v112, v113, v154
	global_store_dword v[116:117], v112, off
; __device__ __forceinline__ unsigned cvt_pk_bf16(float lo, float hi) { unsigned r; asm volatile("v_cvt_pk_bf16_f32 %0, %1, %2" : "=v"(r) : "v"(lo), "v"(hi)); return r; }
; __device__ __forceinline__ void UNPACK8(const u32x4 q, float (&f)[8]) { f[0] = bflo(q.x); f[1] = bfhi(q.x); f[2] = bflo(q.y); f[3] = bfhi(q.y); f[4] = bflo(q.z); f[5] = bfhi(q.z); f[6] = bflo(q.w); f[7] = bfhi(q.w); }
; #define EPI_FOR_ROWS() _Pragma("unroll") for (int ai = 0; ai < 2; ++ai) _Pragma("unroll") for (int m = 0; m < 4; ++m)
;     __device__ __forceinline__ void operator()(const f32x4 (&acc)[2][2][4][2], const Unit& u, int wr, int wc, int fr, int fq) const {
;         EPI_ROWCOL();
;         EPI_FOR_ROWS() {
;             const int row = row0 + ai * 128 + m * 16; float ss = 0.f;
; #pragma unroll
;             for (int bj = 0; bj < 2; ++bj) { const int col = col0 + bj * 128; const size_t off = (size_t)row * 1024 + col;
;                 const u32x4 xw = *(const u32x4*)(xb + off); float xo[8]; UNPACK8(xw, xo);
;                 const f32x4 x0 = (f32x4){xo[0], xo[1], xo[2], xo[3]} + acc[ai][bj][m][0], x1 = (f32x4){xo[4], xo[5], xo[6], xo[7]} + acc[ai][bj][m][1];
;                 ss += (x0[0] * x0[0] + x0[1] * x0[1]) + (x0[2] * x0[2] + x0[3] * x0[3]) + (x1[0] * x1[0] + x1[1] * x1[1]) + (x1[2] * x1[2] + x1[3] * x1[3]);
;                 u32x4 w; w.x = cvt_pk_bf16(x0[0], x0[1]); w.y = cvt_pk_bf16(x0[2], x0[3]); w.z = cvt_pk_bf16(x1[0], x1[1]); w.w = cvt_pk_bf16(x1[2], x1[3]);
;                 *(u32x4*)(xb + off) = w; }
;             ss += __shfl_xor(ss, 16); ss += __shfl_xor(ss, 32);
;             if (fq == 0) ssq[(size_t)row * 16 + u.pn * 4 + wc] = ss;
;         }
.LBB0_948:
	s_or_b64 exec, exec, s[6:7]
	v_or_b32_e32 v112, 16, v130
	s_waitcnt lgkmcnt(0)
	v_ashrrev_i32_e32 v113, 31, v112
	v_lshlrev_b64 v[116:117], 11, v[112:113]
	v_lshl_add_u64 v[116:117], s[22:23], 0, v[116:117]
	v_lshl_add_u64 v[120:121], v[128:129], 1, v[116:117]
	v_mov_b32_e32 v116, v178
	v_mov_b32_e32 v117, v179
	v_mov_b32_e32 v118, v180
	v_mov_b32_e32 v119, v181
	v_lshlrev_b32_e32 v122, 16, v116
	v_and_b32_e32 v123, 0xffff0000, v116
	v_lshlrev_b32_e32 v116, 16, v117
	v_and_b32_e32 v117, 0xffff0000, v117
	v_lshlrev_b32_e32 v124, 16, v118
	v_and_b32_e32 v125, 0xffff0000, v118
	v_lshlrev_b32_e32 v118, 16, v119
	v_and_b32_e32 v119, 0xffff0000, v119
	v_pk_add_f32 v[116:117], v[110:111], v[116:117]
	v_pk_add_f32 v[122:123], v[108:109], v[122:123]
	v_pk_add_f32 v[118:119], v[106:107], v[118:119]
	v_pk_add_f32 v[124:125], v[104:105], v[124:125]
	v_cvt_pk_bf16_f32 v104, v122, v123
	v_cvt_pk_bf16_f32 v105, v116, v117
	v_mul_f32_e32 v123, v123, v123
	v_cvt_pk_bf16_f32 v106, v124, v125
	v_cvt_pk_bf16_f32 v107, v118, v119
	v_mov_b32_e32 v108, v182
	v_mov_b32_e32 v109, v183
	v_mov_b32_e32 v110, v184
	v_mov_b32_e32 v111, v185
	v_mul_f32_e32 v117, v117, v117
	v_mul_f32_e32 v125, v125, v125
	v_fmac_f32_e32 v123, v122, v122
	v_fmac_f32_e32 v117, v116, v116
	v_mul_f32_e32 v119, v119, v119
	v_fmac_f32_e32 v125, v124, v124
	v_add_f32_e32 v116, v123, v117
	v_fmac_f32_e32 v119, v118, v118
	v_add_f32_e32 v116, v125, v116
	v_add_f32_e32 v122, v119, v116
	global_store_dwordx4 v[120:121], v[104:107], off
	v_lshlrev_b32_e32 v116, 16, v108
	v_and_b32_e32 v117, 0xffff0000, v108
	v_lshlrev_b32_e32 v108, 16, v109
	v_and_b32_e32 v109, 0xffff0000, v109
	v_lshlrev_b32_e32 v118, 16, v110
	v_and_b32_e32 v119, 0xffff0000, v110
	v_lshlrev_b32_e32 v110, 16, v111
	v_and_b32_e32 v111, 0xffff0000, v111
	v_pk_add_f32 v[102:103], v[102:103], v[108:109]
	v_pk_add_f32 v[100:101], v[100:101], v[116:117]
	v_pk_add_f32 v[108:109], v[98:99], v[110:111]
	v_pk_add_f32 v[110:111], v[96:97], v[118:119]
	v_mul_f32_e32 v96, v101, v101
	v_mul_f32_e32 v97, v103, v103
	v_mul_f32_e32 v98, v111, v111
	v_fmac_f32_e32 v96, v100, v100
	v_fmac_f32_e32 v97, v102, v102
	v_mul_f32_e32 v99, v109, v109
	v_fmac_f32_e32 v98, v110, v110
	v_add_f32_e32 v96, v96, v97
	v_add_f32_e32 v96, v98, v96
	v_fmac_f32_e32 v99, v108, v108
	v_add_f32_e32 v96, v99, v96
	v_add_f32_e32 v96, v122, v96
	v_mov_b32_e32 v97, v96
	v_mov_b32_e32 v154, v96
	s_nop 1
	v_permlane16_swap_b32_e32 v97, v154
	v_cvt_pk_bf16_f32 v98, v100, v101
	v_cvt_pk_bf16_f32 v99, v102, v103
	v_cvt_pk_bf16_f32 v100, v110, v111
	v_cvt_pk_bf16_f32 v101, v108, v109
	s_waitcnt lgkmcnt(0)
	v_add_f32_e32 v96, v97, v154
	v_mov_b32_e32 v97, v96
	v_mov_b32_e32 v154, v96
	s_nop 1
	v_permlane32_swap_b32_e32 v97, v154
	global_store_dwordx4 v[120:121], v[98:101], off offset:256
	s_and_saveexec_b64 s[6:7], s[8:9]
	s_cbranch_execz .LBB0_950
	v_lshlrev_b64 v[98:99], 6, v[112:113]
	v_lshl_add_u64 v[98:99], s[18:19], 0, v[98:99]
	v_lshl_add_u64 v[98:99], s[38:39], 2, v[98:99]
	s_lshl_b32 s42, s28, 2
	s_mov_b32 s43, s36
	v_lshl_add_u64 v[98:99], v[98:99], 0, s[42:43]
	s_waitcnt lgkmcnt(0)
	v_add_f32_e32 v96, v97, v154
	global_store_dword v[98:99], v96, off
.LBB0_950:
	s_or_b64 exec, exec, s[6:7]
	v_or_b32_e32 v96, 32, v130
	s_waitcnt lgkmcnt(0)
	v_ashrrev_i32_e32 v97, 31, v96
	v_lshlrev_b64 v[98:99], 11, v[96:97]
	v_lshl_add_u64 v[98:99], s[22:23], 0, v[98:99]
	v_lshl_add_u64 v[102:103], v[128:129], 1, v[98:99]
	v_mov_b32_e32 v98, v186
	v_mov_b32_e32 v99, v187
	v_mov_b32_e32 v100, v188
	v_mov_b32_e32 v101, v189
	v_lshlrev_b32_e32 v104, 16, v98
	v_and_b32_e32 v105, 0xffff0000, v98
	v_lshlrev_b32_e32 v98, 16, v99
	v_and_b32_e32 v99, 0xffff0000, v99
	v_lshlrev_b32_e32 v106, 16, v100
	v_and_b32_e32 v107, 0xffff0000, v100
	v_lshlrev_b32_e32 v100, 16, v101
	v_and_b32_e32 v101, 0xffff0000, v101
	v_pk_add_f32 v[98:99], v[94:95], v[98:99]
	v_pk_add_f32 v[104:105], v[92:93], v[104:105]
	v_pk_add_f32 v[100:101], v[90:91], v[100:101]
	v_pk_add_f32 v[106:107], v[88:89], v[106:107]
	v_cvt_pk_bf16_f32 v88, v104, v105
	v_cvt_pk_bf16_f32 v89, v98, v99
	v_mul_f32_e32 v105, v105, v105
	v_cvt_pk_bf16_f32 v90, v106, v107
	v_cvt_pk_bf16_f32 v91, v100, v101
	v_mov_b32_e32 v92, v190
	v_mov_b32_e32 v93, v191
	v_mov_b32_e32 v94, v192
	v_mov_b32_e32 v95, v193
	v_mul_f32_e32 v99, v99, v99
	v_mul_f32_e32 v107, v107, v107
	v_fmac_f32_e32 v105, v104, v104
	v_fmac_f32_e32 v99, v98, v98
	v_mul_f32_e32 v101, v101, v101
	v_fmac_f32_e32 v107, v106, v106
	v_add_f32_e32 v98, v105, v99
	v_fmac_f32_e32 v101, v100, v100
	v_add_f32_e32 v98, v107, v98
	v_add_f32_e32 v104, v101, v98
	global_store_dwordx4 v[102:103], v[88:91], off
	v_lshlrev_b32_e32 v98, 16, v92
	v_and_b32_e32 v99, 0xffff0000, v92
	v_lshlrev_b32_e32 v92, 16, v93
	v_and_b32_e32 v93, 0xffff0000, v93
	v_lshlrev_b32_e32 v100, 16, v94
	v_and_b32_e32 v101, 0xffff0000, v94
	v_lshlrev_b32_e32 v94, 16, v95
	v_and_b32_e32 v95, 0xffff0000, v95
	v_pk_add_f32 v[86:87], v[86:87], v[92:93]
	v_pk_add_f32 v[84:85], v[84:85], v[98:99]
	v_pk_add_f32 v[92:93], v[82:83], v[94:95]
	v_pk_add_f32 v[94:95], v[80:81], v[100:101]
	v_mul_f32_e32 v80, v85, v85
	v_mul_f32_e32 v81, v87, v87
	v_mul_f32_e32 v82, v95, v95
	v_fmac_f32_e32 v80, v84, v84
	v_fmac_f32_e32 v81, v86, v86
	v_mul_f32_e32 v83, v93, v93
	v_fmac_f32_e32 v82, v94, v94
	v_add_f32_e32 v80, v80, v81
	v_add_f32_e32 v80, v82, v80
	v_fmac_f32_e32 v83, v92, v92
	v_add_f32_e32 v80, v83, v80
	v_add_f32_e32 v80, v104, v80
	v_mov_b32_e32 v81, v80
	v_mov_b32_e32 v154, v80
	s_nop 1
	v_permlane16_swap_b32_e32 v81, v154
	v_cvt_pk_bf16_f32 v82, v84, v85
	v_cvt_pk_bf16_f32 v83, v86, v87
	v_cvt_pk_bf16_f32 v84, v94, v95
	v_cvt_pk_bf16_f32 v85, v92, v93
	s_waitcnt lgkmcnt(0)
	v_add_f32_e32 v80, v81, v154
	v_mov_b32_e32 v81, v80
	v_mov_b32_e32 v154, v80
	s_nop 1
	v_permlane32_swap_b32_e32 v81, v154
	global_store_dwordx4 v[102:103], v[82:85], off offset:256
	s_and_saveexec_b64 s[6:7], s[8:9]
	s_cbranch_execz .LBB0_952
	v_lshlrev_b64 v[82:83], 6, v[96:97]
	v_lshl_add_u64 v[82:83], s[18:19], 0, v[82:83]
	v_lshl_add_u64 v[82:83], s[38:39], 2, v[82:83]
	s_lshl_b32 s42, s28, 2
	s_mov_b32 s43, s36
	v_lshl_add_u64 v[82:83], v[82:83], 0, s[42:43]
	s_waitcnt lgkmcnt(0)
	v_add_f32_e32 v80, v81, v154
	global_store_dword v[82:83], v80, off
; __device__ __forceinline__ unsigned cvt_pk_bf16(float lo, float hi) { unsigned r; asm volatile("v_cvt_pk_bf16_f32 %0, %1, %2" : "=v"(r) : "v"(lo), "v"(hi)); return r; }
; __device__ __forceinline__ void UNPACK8(const u32x4 q, float (&f)[8]) { f[0] = bflo(q.x); f[1] = bfhi(q.x); f[2] = bflo(q.y); f[3] = bfhi(q.y); f[4] = bflo(q.z); f[5] = bfhi(q.z); f[6] = bflo(q.w); f[7] = bfhi(q.w); }
; #define EPI_FOR_ROWS() _Pragma("unroll") for (int ai = 0; ai < 2; ++ai) _Pragma("unroll") for (int m = 0; m < 4; ++m)
;     __device__ __forceinline__ void operator()(const f32x4 (&acc)[2][2][4][2], const Unit& u, int wr, int wc, int fr, int fq) const {
;         EPI_ROWCOL();
;         EPI_FOR_ROWS() {
;             const int row = row0 + ai * 128 + m * 16; float ss = 0.f;
; #pragma unroll
;             for (int bj = 0; bj < 2; ++bj) { const int col = col0 + bj * 128; const size_t off = (size_t)row * 1024 + col;
;                 const u32x4 xw = *(const u32x4*)(xb + off); float xo[8]; UNPACK8(xw, xo);
;                 const f32x4 x0 = (f32x4){xo[0], xo[1], xo[2], xo[3]} + acc[ai][bj][m][0], x1 = (f32x4){xo[4], xo[5], xo[6], xo[7]} + acc[ai][bj][m][1];
;                 ss += (x0[0] * x0[0] + x0[1] * x0[1]) + (x0[2] * x0[2] + x0[3] * x0[3]) + (x1[0] * x1[0] + x1[1] * x1[1]) + (x1[2] * x1[2] + x1[3] * x1[3]);
;                 u32x4 w; w.x = cvt_pk_bf16(x0[0], x0[1]); w.y = cvt_pk_bf16(x0[2], x0[3]); w.z = cvt_pk_bf16(x1[0], x1[1]); w.w = cvt_pk_bf16(x1[2], x1[3]);
;                 *(u32x4*)(xb + off) = w; }
;             ss += __shfl_xor(ss, 16); ss += __shfl_xor(ss, 32);
;             if (fq == 0) ssq[(size_t)row * 16 + u.pn * 4 + wc] = ss;
;         }
.LBB0_952:
	s_or_b64 exec, exec, s[6:7]
	v_or_b32_e32 v80, 48, v130
	s_waitcnt lgkmcnt(0)
	v_ashrrev_i32_e32 v81, 31, v80
	v_lshlrev_b64 v[82:83], 11, v[80:81]
	v_lshl_add_u64 v[82:83], s[22:23], 0, v[82:83]
	v_lshl_add_u64 v[86:87], v[128:129], 1, v[82:83]
	v_mov_b32_e32 v82, v194
	v_mov_b32_e32 v83, v195
	v_mov_b32_e32 v84, v196
	v_mov_b32_e32 v85, v197
	v_lshlrev_b32_e32 v88, 16, v82
	v_and_b32_e32 v89, 0xffff0000, v82
	v_lshlrev_b32_e32 v82, 16, v83
	v_and_b32_e32 v83, 0xffff0000, v83
	v_lshlrev_b32_e32 v90, 16, v84
	v_and_b32_e32 v91, 0xffff0000, v84
	v_lshlrev_b32_e32 v84, 16, v85
	v_and_b32_e32 v85, 0xffff0000, v85
	v_pk_add_f32 v[82:83], v[78:79], v[82:83]
	v_pk_add_f32 v[88:89], v[76:77], v[88:89]
	v_pk_add_f32 v[84:85], v[74:75], v[84:85]
	v_pk_add_f32 v[90:91], v[72:73], v[90:91]
	v_cvt_pk_bf16_f32 v72, v88, v89
	v_cvt_pk_bf16_f32 v73, v82, v83
	v_mul_f32_e32 v89, v89, v89
	v_cvt_pk_bf16_f32 v74, v90, v91
	v_cvt_pk_bf16_f32 v75, v84, v85
	v_mov_b32_e32 v76, v198
	v_mov_b32_e32 v77, v199
	v_mov_b32_e32 v78, v200
	v_mov_b32_e32 v79, v201
	v_mul_f32_e32 v83, v83, v83
	v_mul_f32_e32 v91, v91, v91
	v_fmac_f32_e32 v89, v88, v88
	v_fmac_f32_e32 v83, v82, v82
	v_mul_f32_e32 v85, v85, v85
	v_fmac_f32_e32 v91, v90, v90
	v_add_f32_e32 v82, v89, v83
	v_fmac_f32_e32 v85, v84, v84
	v_add_f32_e32 v82, v91, v82
	v_add_f32_e32 v88, v85, v82
	global_store_dwordx4 v[86:87], v[72:75], off
	v_lshlrev_b32_e32 v82, 16, v76
	v_and_b32_e32 v83, 0xffff0000, v76
	v_lshlrev_b32_e32 v76, 16, v77
	v_and_b32_e32 v77, 0xffff0000, v77
	v_lshlrev_b32_e32 v84, 16, v78
	v_and_b32_e32 v85, 0xffff0000, v78
	v_lshlrev_b32_e32 v78, 16, v79
	v_and_b32_e32 v79, 0xffff0000, v79
	v_pk_add_f32 v[70:71], v[70:71], v[76:77]
	v_pk_add_f32 v[68:69], v[68:69], v[82:83]
	v_pk_add_f32 v[76:77], v[66:67], v[78:79]
	v_pk_add_f32 v[78:79], v[64:65], v[84:85]
	v_mul_f32_e32 v64, v69, v69
	v_mul_f32_e32 v65, v71, v71
	v_mul_f32_e32 v66, v79, v79
	v_fmac_f32_e32 v64, v68, v68
	v_fmac_f32_e32 v65, v70, v70
	v_mul_f32_e32 v67, v77, v77
	v_fmac_f32_e32 v66, v78, v78
	v_add_f32_e32 v64, v64, v65
	v_add_f32_e32 v64, v66, v64
	v_fmac_f32_e32 v67, v76, v76
	v_add_f32_e32 v64, v67, v64
	v_add_f32_e32 v64, v88, v64
	v_mov_b32_e32 v65, v64
	v_mov_b32_e32 v154, v64
	s_nop 1
	v_permlane16_swap_b32_e32 v65, v154
	v_cvt_pk_bf16_f32 v66, v68, v69
	v_cvt_pk_bf16_f32 v67, v70, v71
	v_cvt_pk_bf16_f32 v68, v78, v79
	v_cvt_pk_bf16_f32 v69, v76, v77
	s_waitcnt lgkmcnt(0)
	v_add_f32_e32 v64, v65, v154
	v_mov_b32_e32 v65, v64
	v_mov_b32_e32 v154, v64
	s_nop 1
	v_permlane32_swap_b32_e32 v65, v154
	global_store_dwordx4 v[86:87], v[66:69], off offset:256
	s_and_saveexec_b64 s[6:7], s[8:9]
	s_cbranch_execz .LBB0_954
	v_lshlrev_b64 v[66:67], 6, v[80:81]
	v_lshl_add_u64 v[66:67], s[18:19], 0, v[66:67]
	v_lshl_add_u64 v[66:67], s[38:39], 2, v[66:67]
	s_lshl_b32 s42, s28, 2
	s_mov_b32 s43, s36
	v_lshl_add_u64 v[66:67], v[66:67], 0, s[42:43]
	s_waitcnt lgkmcnt(0)
	v_add_f32_e32 v64, v65, v154
	global_store_dword v[66:67], v64, off
.LBB0_954:
	s_or_b64 exec, exec, s[6:7]
	v_add_u32_e32 v64, 0x80, v130
	s_waitcnt lgkmcnt(0)
	v_ashrrev_i32_e32 v65, 31, v64
	v_lshlrev_b64 v[66:67], 11, v[64:65]
	v_lshl_add_u64 v[66:67], s[22:23], 0, v[66:67]
	v_lshl_add_u64 v[70:71], v[128:129], 1, v[66:67]
	v_mov_b32_e32 v66, v202
	v_mov_b32_e32 v67, v203
	v_mov_b32_e32 v68, v204
	v_mov_b32_e32 v69, v205
	v_lshlrev_b32_e32 v72, 16, v66
	v_and_b32_e32 v73, 0xffff0000, v66
	v_lshlrev_b32_e32 v66, 16, v67
	v_and_b32_e32 v67, 0xffff0000, v67
	v_lshlrev_b32_e32 v74, 16, v68
	v_and_b32_e32 v75, 0xffff0000, v68
	v_lshlrev_b32_e32 v68, 16, v69
	v_and_b32_e32 v69, 0xffff0000, v69
	v_pk_add_f32 v[66:67], v[62:63], v[66:67]
	v_pk_add_f32 v[72:73], v[60:61], v[72:73]
	v_pk_add_f32 v[68:69], v[58:59], v[68:69]
	v_pk_add_f32 v[74:75], v[56:57], v[74:75]
	v_cvt_pk_bf16_f32 v56, v72, v73
	v_cvt_pk_bf16_f32 v57, v66, v67
	v_mul_f32_e32 v73, v73, v73
	v_cvt_pk_bf16_f32 v58, v74, v75
	v_cvt_pk_bf16_f32 v59, v68, v69
	v_mov_b32_e32 v60, v214
	v_mov_b32_e32 v61, v215
	v_mov_b32_e32 v62, v216
	v_mov_b32_e32 v63, v217
	v_mul_f32_e32 v67, v67, v67
	v_mul_f32_e32 v75, v75, v75
	v_fmac_f32_e32 v73, v72, v72
	v_fmac_f32_e32 v67, v66, v66
	v_mul_f32_e32 v69, v69, v69
	v_fmac_f32_e32 v75, v74, v74
	v_add_f32_e32 v66, v73, v67
	v_fmac_f32_e32 v69, v68, v68
	v_add_f32_e32 v66, v75, v66
	v_add_f32_e32 v72, v69, v66
	global_store_dwordx4 v[70:71], v[56:59], off
	v_lshlrev_b32_e32 v66, 16, v60
	v_and_b32_e32 v67, 0xffff0000, v60
	v_lshlrev_b32_e32 v60, 16, v61
	v_and_b32_e32 v61, 0xffff0000, v61
	v_lshlrev_b32_e32 v68, 16, v62
	v_and_b32_e32 v69, 0xffff0000, v62
	v_lshlrev_b32_e32 v62, 16, v63
	v_and_b32_e32 v63, 0xffff0000, v63
	v_pk_add_f32 v[54:55], v[54:55], v[60:61]
	v_pk_add_f32 v[52:53], v[52:53], v[66:67]
	v_pk_add_f32 v[60:61], v[50:51], v[62:63]
	v_pk_add_f32 v[62:63], v[48:49], v[68:69]
	v_mul_f32_e32 v48, v53, v53
	v_mul_f32_e32 v49, v55, v55
	v_mul_f32_e32 v50, v63, v63
	v_fmac_f32_e32 v48, v52, v52
	v_fmac_f32_e32 v49, v54, v54
	v_mul_f32_e32 v51, v61, v61
	v_fmac_f32_e32 v50, v62, v62
	v_add_f32_e32 v48, v48, v49
	v_add_f32_e32 v48, v50, v48
	v_fmac_f32_e32 v51, v60, v60
	v_add_f32_e32 v48, v51, v48
	v_add_f32_e32 v48, v72, v48
	v_mov_b32_e32 v49, v48
	v_mov_b32_e32 v154, v48
	s_nop 1
	v_permlane16_swap_b32_e32 v49, v154
	v_cvt_pk_bf16_f32 v50, v52, v53
	v_cvt_pk_bf16_f32 v51, v54, v55
	v_cvt_pk_bf16_f32 v52, v62, v63
	v_cvt_pk_bf16_f32 v53, v60, v61
	s_waitcnt lgkmcnt(0)
	v_add_f32_e32 v48, v49, v154
	v_mov_b32_e32 v49, v48
	v_mov_b32_e32 v154, v48
	s_nop 1
	v_permlane32_swap_b32_e32 v49, v154
	global_store_dwordx4 v[70:71], v[50:53], off offset:256
	s_and_saveexec_b64 s[6:7], s[8:9]
	s_cbranch_execz .LBB0_956
	v_lshlrev_b64 v[50:51], 6, v[64:65]
	v_lshl_add_u64 v[50:51], s[18:19], 0, v[50:51]
	v_lshl_add_u64 v[50:51], s[38:39], 2, v[50:51]
	s_lshl_b32 s42, s28, 2
	s_mov_b32 s43, s36
	v_lshl_add_u64 v[50:51], v[50:51], 0, s[42:43]
	s_waitcnt lgkmcnt(0)
	v_add_f32_e32 v48, v49, v154
	global_store_dword v[50:51], v48, off
; __device__ __forceinline__ unsigned cvt_pk_bf16(float lo, float hi) { unsigned r; asm volatile("v_cvt_pk_bf16_f32 %0, %1, %2" : "=v"(r) : "v"(lo), "v"(hi)); return r; }
; __device__ __forceinline__ void UNPACK8(const u32x4 q, float (&f)[8]) { f[0] = bflo(q.x); f[1] = bfhi(q.x); f[2] = bflo(q.y); f[3] = bfhi(q.y); f[4] = bflo(q.z); f[5] = bfhi(q.z); f[6] = bflo(q.w); f[7] = bfhi(q.w); }
; #define EPI_FOR_ROWS() _Pragma("unroll") for (int ai = 0; ai < 2; ++ai) _Pragma("unroll") for (int m = 0; m < 4; ++m)
;     __device__ __forceinline__ void operator()(const f32x4 (&acc)[2][2][4][2], const Unit& u, int wr, int wc, int fr, int fq) const {
;         EPI_ROWCOL();
;         EPI_FOR_ROWS() {
;             const int row = row0 + ai * 128 + m * 16; float ss = 0.f;
; #pragma unroll
;             for (int bj = 0; bj < 2; ++bj) { const int col = col0 + bj * 128; const size_t off = (size_t)row * 1024 + col;
;                 const u32x4 xw = *(const u32x4*)(xb + off); float xo[8]; UNPACK8(xw, xo);
;                 const f32x4 x0 = (f32x4){xo[0], xo[1], xo[2], xo[3]} + acc[ai][bj][m][0], x1 = (f32x4){xo[4], xo[5], xo[6], xo[7]} + acc[ai][bj][m][1];
;                 ss += (x0[0] * x0[0] + x0[1] * x0[1]) + (x0[2] * x0[2] + x0[3] * x0[3]) + (x1[0] * x1[0] + x1[1] * x1[1]) + (x1[2] * x1[2] + x1[3] * x1[3]);
;                 u32x4 w; w.x = cvt_pk_bf16(x0[0], x0[1]); w.y = cvt_pk_bf16(x0[2], x0[3]); w.z = cvt_pk_bf16(x1[0], x1[1]); w.w = cvt_pk_bf16(x1[2], x1[3]);
;                 *(u32x4*)(xb + off) = w; }
;             ss += __shfl_xor(ss, 16); ss += __shfl_xor(ss, 32);
;             if (fq == 0) ssq[(size_t)row * 16 + u.pn * 4 + wc] = ss;
;         }
.LBB0_956:
	s_or_b64 exec, exec, s[6:7]
	v_add_u32_e32 v48, 0x90, v130
	s_waitcnt lgkmcnt(0)
	v_ashrrev_i32_e32 v49, 31, v48
	v_lshlrev_b64 v[50:51], 11, v[48:49]
	v_lshl_add_u64 v[50:51], s[22:23], 0, v[50:51]
	v_lshl_add_u64 v[54:55], v[128:129], 1, v[50:51]
	v_mov_b32_e32 v50, v218
	v_mov_b32_e32 v51, v219
	v_mov_b32_e32 v52, v220
	v_mov_b32_e32 v53, v221
	v_lshlrev_b32_e32 v56, 16, v50
	v_and_b32_e32 v57, 0xffff0000, v50
	v_lshlrev_b32_e32 v50, 16, v51
	v_and_b32_e32 v51, 0xffff0000, v51
	v_lshlrev_b32_e32 v58, 16, v52
	v_and_b32_e32 v59, 0xffff0000, v52
	v_lshlrev_b32_e32 v52, 16, v53
	v_and_b32_e32 v53, 0xffff0000, v53
	v_pk_add_f32 v[50:51], v[46:47], v[50:51]
	v_pk_add_f32 v[56:57], v[44:45], v[56:57]
	v_pk_add_f32 v[52:53], v[42:43], v[52:53]
	v_pk_add_f32 v[58:59], v[40:41], v[58:59]
	v_cvt_pk_bf16_f32 v40, v56, v57
	v_cvt_pk_bf16_f32 v41, v50, v51
	v_mul_f32_e32 v57, v57, v57
	v_cvt_pk_bf16_f32 v42, v58, v59
	v_cvt_pk_bf16_f32 v43, v52, v53
	v_mov_b32_e32 v44, v222
	v_mov_b32_e32 v45, v223
	v_mov_b32_e32 v46, v224
	v_mov_b32_e32 v47, v225
	v_mul_f32_e32 v51, v51, v51
	v_mul_f32_e32 v59, v59, v59
	v_fmac_f32_e32 v57, v56, v56
	v_fmac_f32_e32 v51, v50, v50
	v_mul_f32_e32 v53, v53, v53
	v_fmac_f32_e32 v59, v58, v58
	v_add_f32_e32 v50, v57, v51
	v_fmac_f32_e32 v53, v52, v52
	v_add_f32_e32 v50, v59, v50
	v_add_f32_e32 v56, v53, v50
	global_store_dwordx4 v[54:55], v[40:43], off
	v_lshlrev_b32_e32 v50, 16, v44
	v_and_b32_e32 v51, 0xffff0000, v44
	v_lshlrev_b32_e32 v44, 16, v45
	v_and_b32_e32 v45, 0xffff0000, v45
	v_lshlrev_b32_e32 v52, 16, v46
	v_and_b32_e32 v53, 0xffff0000, v46
	v_lshlrev_b32_e32 v46, 16, v47
	v_and_b32_e32 v47, 0xffff0000, v47
	v_pk_add_f32 v[38:39], v[38:39], v[44:45]
	v_pk_add_f32 v[36:37], v[36:37], v[50:51]
	v_pk_add_f32 v[44:45], v[34:35], v[46:47]
	v_pk_add_f32 v[46:47], v[32:33], v[52:53]
	v_mul_f32_e32 v32, v37, v37
	v_mul_f32_e32 v33, v39, v39
	v_mul_f32_e32 v34, v47, v47
	v_fmac_f32_e32 v32, v36, v36
	v_fmac_f32_e32 v33, v38, v38
	v_mul_f32_e32 v35, v45, v45
	v_fmac_f32_e32 v34, v46, v46
	v_add_f32_e32 v32, v32, v33
	v_add_f32_e32 v32, v34, v32
	v_fmac_f32_e32 v35, v44, v44
	v_add_f32_e32 v32, v35, v32
	v_add_f32_e32 v32, v56, v32
	v_mov_b32_e32 v33, v32
	v_mov_b32_e32 v154, v32
	s_nop 1
	v_permlane16_swap_b32_e32 v33, v154
	v_cvt_pk_bf16_f32 v34, v36, v37
	v_cvt_pk_bf16_f32 v35, v38, v39
	v_cvt_pk_bf16_f32 v36, v46, v47
	v_cvt_pk_bf16_f32 v37, v44, v45
	s_waitcnt lgkmcnt(0)
	v_add_f32_e32 v32, v33, v154
	v_mov_b32_e32 v33, v32
	v_mov_b32_e32 v154, v32
	s_nop 1
	v_permlane32_swap_b32_e32 v33, v154
	global_store_dwordx4 v[54:55], v[34:37], off offset:256
	s_and_saveexec_b64 s[6:7], s[8:9]
	s_cbranch_execz .LBB0_958
	v_lshlrev_b64 v[34:35], 6, v[48:49]
	v_lshl_add_u64 v[34:35], s[18:19], 0, v[34:35]
	v_lshl_add_u64 v[34:35], s[38:39], 2, v[34:35]
	s_lshl_b32 s42, s28, 2
	s_mov_b32 s43, s36
	v_lshl_add_u64 v[34:35], v[34:35], 0, s[42:43]
	s_waitcnt lgkmcnt(0)
	v_add_f32_e32 v32, v33, v154
	global_store_dword v[34:35], v32, off
; __device__ __forceinline__ unsigned cvt_pk_bf16(float lo, float hi) { unsigned r; asm volatile("v_cvt_pk_bf16_f32 %0, %1, %2" : "=v"(r) : "v"(lo), "v"(hi)); return r; }
; __device__ __forceinline__ void UNPACK8(const u32x4 q, float (&f)[8]) { f[0] = bflo(q.x); f[1] = bfhi(q.x); f[2] = bflo(q.y); f[3] = bfhi(q.y); f[4] = bflo(q.z); f[5] = bfhi(q.z); f[6] = bflo(q.w); f[7] = bfhi(q.w); }
; #define EPI_FOR_ROWS() _Pragma("unroll") for (int ai = 0; ai < 2; ++ai) _Pragma("unroll") for (int m = 0; m < 4; ++m)
;     __device__ __forceinline__ void operator()(const f32x4 (&acc)[2][2][4][2], const Unit& u, int wr, int wc, int fr, int fq) const {
;         EPI_ROWCOL();
;         EPI_FOR_ROWS() {
;             const int row = row0 + ai * 128 + m * 16; float ss = 0.f;
; #pragma unroll
;             for (int bj = 0; bj < 2; ++bj) { const int col = col0 + bj * 128; const size_t off = (size_t)row * 1024 + col;
;                 const u32x4 xw = *(const u32x4*)(xb + off); float xo[8]; UNPACK8(xw, xo);
;                 const f32x4 x0 = (f32x4){xo[0], xo[1], xo[2], xo[3]} + acc[ai][bj][m][0], x1 = (f32x4){xo[4], xo[5], xo[6], xo[7]} + acc[ai][bj][m][1];
;                 ss += (x0[0] * x0[0] + x0[1] * x0[1]) + (x0[2] * x0[2] + x0[3] * x0[3]) + (x1[0] * x1[0] + x1[1] * x1[1]) + (x1[2] * x1[2] + x1[3] * x1[3]);
;                 u32x4 w; w.x = cvt_pk_bf16(x0[0], x0[1]); w.y = cvt_pk_bf16(x0[2], x0[3]); w.z = cvt_pk_bf16(x1[0], x1[1]); w.w = cvt_pk_bf16(x1[2], x1[3]);
;                 *(u32x4*)(xb + off) = w; }
;             ss += __shfl_xor(ss, 16); ss += __shfl_xor(ss, 32);
;             if (fq == 0) ssq[(size_t)row * 16 + u.pn * 4 + wc] = ss;
;         }
.LBB0_958:
	s_or_b64 exec, exec, s[6:7]
	v_add_u32_e32 v32, 0xa0, v130
	s_waitcnt lgkmcnt(0)
	v_ashrrev_i32_e32 v33, 31, v32
	v_lshlrev_b64 v[34:35], 11, v[32:33]
	v_lshl_add_u64 v[34:35], s[22:23], 0, v[34:35]
	v_lshl_add_u64 v[38:39], v[128:129], 1, v[34:35]
	v_mov_b32_e32 v34, v226
	v_mov_b32_e32 v35, v227
	v_mov_b32_e32 v36, v228
	v_mov_b32_e32 v37, v229
	v_lshlrev_b32_e32 v40, 16, v34
	v_and_b32_e32 v41, 0xffff0000, v34
	v_lshlrev_b32_e32 v34, 16, v35
	v_and_b32_e32 v35, 0xffff0000, v35
	v_lshlrev_b32_e32 v42, 16, v36
	v_and_b32_e32 v43, 0xffff0000, v36
	v_lshlrev_b32_e32 v36, 16, v37
	v_and_b32_e32 v37, 0xffff0000, v37
	v_pk_add_f32 v[34:35], v[30:31], v[34:35]
	v_pk_add_f32 v[40:41], v[28:29], v[40:41]
	v_pk_add_f32 v[36:37], v[26:27], v[36:37]
	v_pk_add_f32 v[42:43], v[24:25], v[42:43]
	v_cvt_pk_bf16_f32 v24, v40, v41
	v_cvt_pk_bf16_f32 v25, v34, v35
	v_mul_f32_e32 v41, v41, v41
	v_cvt_pk_bf16_f32 v26, v42, v43
	v_cvt_pk_bf16_f32 v27, v36, v37
	v_mov_b32_e32 v28, v230
	v_mov_b32_e32 v29, v231
	v_mov_b32_e32 v30, v232
	v_mov_b32_e32 v31, v233
	v_mul_f32_e32 v35, v35, v35
	v_mul_f32_e32 v43, v43, v43
	v_fmac_f32_e32 v41, v40, v40
	v_fmac_f32_e32 v35, v34, v34
	v_mul_f32_e32 v37, v37, v37
	v_fmac_f32_e32 v43, v42, v42
	v_add_f32_e32 v34, v41, v35
	v_fmac_f32_e32 v37, v36, v36
	v_add_f32_e32 v34, v43, v34
	v_add_f32_e32 v40, v37, v34
	global_store_dwordx4 v[38:39], v[24:27], off
	v_lshlrev_b32_e32 v34, 16, v28
	v_and_b32_e32 v35, 0xffff0000, v28
	v_lshlrev_b32_e32 v28, 16, v29
	v_and_b32_e32 v29, 0xffff0000, v29
	v_lshlrev_b32_e32 v36, 16, v30
	v_and_b32_e32 v37, 0xffff0000, v30
	v_lshlrev_b32_e32 v30, 16, v31
	v_and_b32_e32 v31, 0xffff0000, v31
	v_pk_add_f32 v[22:23], v[22:23], v[28:29]
	v_pk_add_f32 v[20:21], v[20:21], v[34:35]
	v_pk_add_f32 v[28:29], v[18:19], v[30:31]
	v_pk_add_f32 v[30:31], v[16:17], v[36:37]
	v_mul_f32_e32 v16, v21, v21
	v_mul_f32_e32 v17, v23, v23
	v_mul_f32_e32 v18, v31, v31
	v_fmac_f32_e32 v16, v20, v20
	v_fmac_f32_e32 v17, v22, v22
	v_mul_f32_e32 v19, v29, v29
	v_fmac_f32_e32 v18, v30, v30
	v_add_f32_e32 v16, v16, v17
	v_add_f32_e32 v16, v18, v16
	v_fmac_f32_e32 v19, v28, v28
	v_add_f32_e32 v16, v19, v16
	v_add_f32_e32 v16, v40, v16
	v_mov_b32_e32 v17, v16
	v_mov_b32_e32 v154, v16
	s_nop 1
	v_permlane16_swap_b32_e32 v17, v154
	v_cvt_pk_bf16_f32 v18, v20, v21
	v_cvt_pk_bf16_f32 v19, v22, v23
	v_cvt_pk_bf16_f32 v20, v30, v31
	v_cvt_pk_bf16_f32 v21, v28, v29
	s_waitcnt lgkmcnt(0)
	v_add_f32_e32 v16, v17, v154
	v_mov_b32_e32 v17, v16
	v_mov_b32_e32 v154, v16
	s_nop 1
	v_permlane32_swap_b32_e32 v17, v154
	global_store_dwordx4 v[38:39], v[18:21], off offset:256
	s_and_saveexec_b64 s[6:7], s[8:9]
	s_cbranch_execz .LBB0_960
	v_lshlrev_b64 v[18:19], 6, v[32:33]
	v_lshl_add_u64 v[18:19], s[18:19], 0, v[18:19]
	v_lshl_add_u64 v[18:19], s[38:39], 2, v[18:19]
	s_lshl_b32 s42, s28, 2
	s_mov_b32 s43, s36
	v_lshl_add_u64 v[18:19], v[18:19], 0, s[42:43]
	s_waitcnt lgkmcnt(0)
	v_add_f32_e32 v16, v17, v154
	global_store_dword v[18:19], v16, off
.LBB0_960:
	s_or_b64 exec, exec, s[6:7]
	v_add_u32_e32 v16, 0xb0, v130
	s_waitcnt lgkmcnt(0)
	v_ashrrev_i32_e32 v17, 31, v16
	v_lshlrev_b64 v[18:19], 11, v[16:17]
	v_lshl_add_u64 v[18:19], s[22:23], 0, v[18:19]
	v_lshl_add_u64 v[22:23], v[128:129], 1, v[18:19]
	v_mov_b32_e32 v18, v234
	v_mov_b32_e32 v19, v235
	v_mov_b32_e32 v20, v236
	v_mov_b32_e32 v21, v237
	v_lshlrev_b32_e32 v24, 16, v18
	v_and_b32_e32 v25, 0xffff0000, v18
	v_lshlrev_b32_e32 v18, 16, v19
	v_and_b32_e32 v19, 0xffff0000, v19
	v_lshlrev_b32_e32 v26, 16, v20
	v_and_b32_e32 v27, 0xffff0000, v20
	v_lshlrev_b32_e32 v20, 16, v21
	v_and_b32_e32 v21, 0xffff0000, v21
	v_pk_add_f32 v[18:19], v[14:15], v[18:19]
	v_pk_add_f32 v[24:25], v[12:13], v[24:25]
	v_pk_add_f32 v[20:21], v[10:11], v[20:21]
	v_pk_add_f32 v[26:27], v[8:9], v[26:27]
	v_cvt_pk_bf16_f32 v8, v24, v25
	v_cvt_pk_bf16_f32 v9, v18, v19
	v_mul_f32_e32 v25, v25, v25
	v_cvt_pk_bf16_f32 v10, v26, v27
	v_cvt_pk_bf16_f32 v11, v20, v21
	v_mov_b32_e32 v12, v238
	v_mov_b32_e32 v13, v239
	v_mov_b32_e32 v14, v240
	v_mov_b32_e32 v15, v241
	v_mul_f32_e32 v19, v19, v19
	v_mul_f32_e32 v27, v27, v27
	v_fmac_f32_e32 v25, v24, v24
	v_fmac_f32_e32 v19, v18, v18
	v_mul_f32_e32 v21, v21, v21
	v_fmac_f32_e32 v27, v26, v26
	v_add_f32_e32 v18, v25, v19
	v_fmac_f32_e32 v21, v20, v20
	v_add_f32_e32 v18, v27, v18
	v_add_f32_e32 v24, v21, v18
	global_store_dwordx4 v[22:23], v[8:11], off
	v_lshlrev_b32_e32 v18, 16, v12
	v_and_b32_e32 v19, 0xffff0000, v12
	v_lshlrev_b32_e32 v12, 16, v13
	v_and_b32_e32 v13, 0xffff0000, v13
	v_lshlrev_b32_e32 v20, 16, v14
	v_and_b32_e32 v21, 0xffff0000, v14
	v_lshlrev_b32_e32 v14, 16, v15
	v_and_b32_e32 v15, 0xffff0000, v15
	v_pk_add_f32 v[6:7], v[6:7], v[12:13]
	v_pk_add_f32 v[4:5], v[4:5], v[18:19]
	v_pk_add_f32 v[12:13], v[2:3], v[14:15]
	v_pk_add_f32 v[14:15], v[0:1], v[20:21]
	v_mul_f32_e32 v0, v5, v5
	v_mul_f32_e32 v1, v7, v7
	v_mul_f32_e32 v2, v15, v15
	v_fmac_f32_e32 v0, v4, v4
	v_fmac_f32_e32 v1, v6, v6
	v_mul_f32_e32 v3, v13, v13
	v_fmac_f32_e32 v2, v14, v14
	v_add_f32_e32 v0, v0, v1
	v_add_f32_e32 v0, v2, v0
	v_fmac_f32_e32 v3, v12, v12
	v_add_f32_e32 v0, v3, v0
	v_add_f32_e32 v0, v24, v0
	v_mov_b32_e32 v1, v0
	v_mov_b32_e32 v154, v0
	s_nop 1
	v_permlane16_swap_b32_e32 v1, v154
	v_cvt_pk_bf16_f32 v2, v4, v5
	v_cvt_pk_bf16_f32 v3, v6, v7
	v_cvt_pk_bf16_f32 v4, v14, v15
	v_cvt_pk_bf16_f32 v5, v12, v13
	s_waitcnt lgkmcnt(0)
	v_add_f32_e32 v0, v1, v154
	v_mov_b32_e32 v1, v0
	v_mov_b32_e32 v154, v0
	s_nop 1
	v_permlane32_swap_b32_e32 v1, v154
	global_store_dwordx4 v[22:23], v[2:5], off offset:256
	s_and_saveexec_b64 s[6:7], s[8:9]
	s_cbranch_execz .LBB0_962
	v_lshlrev_b64 v[2:3], 6, v[16:17]
	v_lshl_add_u64 v[2:3], s[18:19], 0, v[2:3]
	v_lshl_add_u64 v[2:3], s[38:39], 2, v[2:3]
	s_lshl_b32 s38, s28, 2
	s_mov_b32 s39, s36
	v_lshl_add_u64 v[2:3], v[2:3], 0, s[38:39]
	s_waitcnt lgkmcnt(0)
	v_add_f32_e32 v0, v1, v154
	global_store_dword v[2:3], v0, off

; __device__ __forceinline__ unsigned cvt_pk_bf16(float lo, float hi) { unsigned r; asm volatile("v_cvt_pk_bf16_f32 %0, %1, %2" : "=v"(r) : "v"(lo), "v"(hi)); return r; }
; __device__ __forceinline__ void UNPACK8(const u32x4 q, float (&f)[8]) { f[0] = bflo(q.x); f[1] = bfhi(q.x); f[2] = bflo(q.y); f[3] = bfhi(q.y); f[4] = bflo(q.z); f[5] = bfhi(q.z); f[6] = bflo(q.w); f[7] = bfhi(q.w); }
; #define EPI_FOR_ROWS() _Pragma("unroll") for (int ai = 0; ai < 2; ++ai) _Pragma("unroll") for (int m = 0; m < 4; ++m)
;     __device__ __forceinline__ void operator()(const f32x4 (&acc)[2][2][4][2], const Unit& u, int wr, int wc, int fr, int fq) const {
;         EPI_ROWCOL();
;         EPI_FOR_ROWS() {
;             const int row = row0 + ai * 128 + m * 16; float ss = 0.f;
; #pragma unroll
;             for (int bj = 0; bj < 2; ++bj) { const int col = col0 + bj * 128; const size_t off = (size_t)row * 1024 + col;
;                 const u32x4 xw = *(const u32x4*)(xb + off); float xo[8]; UNPACK8(xw, xo);
;                 const f32x4 x0 = (f32x4){xo[0], xo[1], xo[2], xo[3]} + acc[ai][bj][m][0], x1 = (f32x4){xo[4], xo[5], xo[6], xo[7]} + acc[ai][bj][m][1];
;                 ss += (x0[0] * x0[0] + x0[1] * x0[1]) + (x0[2] * x0[2] + x0[3] * x0[3]) + (x1[0] * x1[0] + x1[1] * x1[1]) + (x1[2] * x1[2] + x1[3] * x1[3]);
;                 u32x4 w; w.x = cvt_pk_bf16(x0[0], x0[1]); w.y = cvt_pk_bf16(x0[2], x0[3]); w.z = cvt_pk_bf16(x1[0], x1[1]); w.w = cvt_pk_bf16(x1[2], x1[3]);
;                 *(u32x4*)(xb + off) = w; }
;             ss += __shfl_xor(ss, 16); ss += __shfl_xor(ss, 32);
;             if (fq == 0) ssq[(size_t)row * 16 + u.pn * 4 + wc] = ss;
;         }
.LBB0_1143:
	v_lshl_add_u32 v130, s67, 8, v136
	v_ashrrev_i32_e32 v131, 31, v130
	v_lshl_or_b32 v128, s66, 8, v137
	v_lshlrev_b64 v[144:145], 11, v[130:131]
	v_ashrrev_i32_e32 v129, 31, v128
	v_lshl_add_u64 v[144:145], s[22:23], 0, v[144:145]
	v_lshl_add_u64 v[148:149], v[128:129], 1, v[144:145]
	global_load_dwordx4 v[156:159], v[148:149], off
	global_load_dwordx4 v[166:169], v[148:149], off offset:256
	s_mov_b32 s12, 0x8000
	s_mov_b32 s13, 0
	v_lshl_add_u64 v[182:183], v[148:149], 0, s[12:13]
	global_load_dwordx4 v[178:181], v[182:183], off
	global_load_dwordx4 v[182:185], v[182:183], off offset:256
	s_mov_b32 s12, 0x10000
	s_mov_b32 s13, 0
	v_lshl_add_u64 v[190:191], v[148:149], 0, s[12:13]
	global_load_dwordx4 v[186:189], v[190:191], off
	global_load_dwordx4 v[190:193], v[190:191], off offset:256
	s_mov_b32 s12, 0x18000
	s_mov_b32 s13, 0
	v_lshl_add_u64 v[198:199], v[148:149], 0, s[12:13]
	global_load_dwordx4 v[194:197], v[198:199], off
	global_load_dwordx4 v[198:201], v[198:199], off offset:256
	s_mov_b32 s12, 0x40000
	s_mov_b32 s13, 0
	v_lshl_add_u64 v[214:215], v[148:149], 0, s[12:13]
	global_load_dwordx4 v[202:205], v[214:215], off
	global_load_dwordx4 v[214:217], v[214:215], off offset:256
	s_mov_b32 s12, 0x48000
	s_mov_b32 s13, 0
	v_lshl_add_u64 v[222:223], v[148:149], 0, s[12:13]
	global_load_dwordx4 v[218:221], v[222:223], off
	global_load_dwordx4 v[222:225], v[222:223], off offset:256
	s_mov_b32 s12, 0x50000
	s_mov_b32 s13, 0
	v_lshl_add_u64 v[230:231], v[148:149], 0, s[12:13]
	global_load_dwordx4 v[226:229], v[230:231], off
	global_load_dwordx4 v[230:233], v[230:231], off offset:256
	s_mov_b32 s12, 0x58000
	s_mov_b32 s13, 0
	v_lshl_add_u64 v[238:239], v[148:149], 0, s[12:13]
	global_load_dwordx4 v[234:237], v[238:239], off
	global_load_dwordx4 v[238:241], v[238:239], off offset:256
	s_waitcnt vmcnt(0)
	v_mov_b32_e32 v144, v156
	v_mov_b32_e32 v145, v157
	v_mov_b32_e32 v146, v158
	v_mov_b32_e32 v147, v159
	s_lshl_b32 s12, s66, 2
	s_ashr_i32 s13, s12, 31
	v_lshlrev_b32_e32 v150, 16, v144
	v_and_b32_e32 v151, 0xffff0000, v144
	v_lshlrev_b32_e32 v144, 16, v145
	v_and_b32_e32 v145, 0xffff0000, v145
	v_lshlrev_b32_e32 v152, 16, v146
	v_and_b32_e32 v153, 0xffff0000, v146
	v_lshlrev_b32_e32 v146, 16, v147
	v_and_b32_e32 v147, 0xffff0000, v147
	v_pk_add_f32 v[126:127], v[126:127], v[144:145]
	v_pk_add_f32 v[124:125], v[124:125], v[150:151]
	v_pk_add_f32 v[144:145], v[122:123], v[146:147]
	v_pk_add_f32 v[122:123], v[120:121], v[152:153]
	v_mul_f32_e32 v120, v125, v125
	v_mul_f32_e32 v121, v127, v127
	v_fmac_f32_e32 v120, v124, v124
	v_fmac_f32_e32 v121, v126, v126
	v_add_f32_e32 v120, v120, v121
	v_mul_f32_e32 v121, v123, v123
	v_fmac_f32_e32 v121, v122, v122
	v_add_f32_e32 v120, v121, v120
	v_mul_f32_e32 v121, v145, v145
	v_fmac_f32_e32 v121, v144, v144
	v_add_f32_e32 v143, v121, v120
	v_cvt_pk_bf16_f32 v120, v124, v125
	v_cvt_pk_bf16_f32 v121, v126, v127
	v_cvt_pk_bf16_f32 v122, v122, v123
	v_cvt_pk_bf16_f32 v123, v144, v145
	global_store_dwordx4 v[148:149], v[120:123], off
	s_nop 1
	v_mov_b32_e32 v120, v166
	v_mov_b32_e32 v121, v167
	v_mov_b32_e32 v122, v168
	v_mov_b32_e32 v123, v169
	v_lshlrev_b32_e32 v124, 16, v120
	v_and_b32_e32 v125, 0xffff0000, v120
	v_lshlrev_b32_e32 v120, 16, v121
	v_and_b32_e32 v121, 0xffff0000, v121
	v_lshlrev_b32_e32 v126, 16, v122
	v_and_b32_e32 v127, 0xffff0000, v122
	v_lshlrev_b32_e32 v122, 16, v123
	v_and_b32_e32 v123, 0xffff0000, v123
	v_pk_add_f32 v[118:119], v[118:119], v[120:121]
	v_pk_add_f32 v[116:117], v[116:117], v[124:125]
	v_pk_add_f32 v[120:121], v[114:115], v[122:123]
	v_pk_add_f32 v[114:115], v[112:113], v[126:127]
	v_mul_f32_e32 v112, v117, v117
	v_mul_f32_e32 v113, v119, v119
	v_fmac_f32_e32 v112, v116, v116
	v_fmac_f32_e32 v113, v118, v118
	v_add_f32_e32 v112, v112, v113
	v_mul_f32_e32 v113, v115, v115
	v_fmac_f32_e32 v113, v114, v114
	v_add_f32_e32 v112, v113, v112
	v_mul_f32_e32 v113, v121, v121
	v_fmac_f32_e32 v113, v120, v120
	v_add_f32_e32 v112, v113, v112
	v_add_f32_e32 v122, v143, v112
	v_cvt_pk_bf16_f32 v112, v116, v117
	v_cvt_pk_bf16_f32 v113, v118, v119
	v_cvt_pk_bf16_f32 v114, v114, v115
	v_cvt_pk_bf16_f32 v115, v120, v121
	global_store_dwordx4 v[148:149], v[112:115], off offset:256
	s_nop 1
	v_and_b32_e32 v113, 64, v207
	v_xor_b32_e32 v112, 16, v207
	v_add_u32_e32 v113, 64, v113
	v_cmp_lt_i32_e32 vcc, v112, v113
	v_xor_b32_e32 v115, 32, v207
	s_nop 0
	v_cndmask_b32_e32 v112, v207, v112, vcc
	v_lshlrev_b32_e32 v114, 2, v112
	v_mov_b32_e32 v112, v122
	v_mov_b32_e32 v154, v122
	s_nop 1
	v_permlane16_swap_b32_e32 v112, v154
	v_cmp_lt_i32_e32 vcc, v115, v113
	s_waitcnt lgkmcnt(0)
	v_add_f32_e32 v112, v112, v154
	v_cndmask_b32_e32 v113, v207, v115, vcc
	v_lshlrev_b32_e32 v115, 2, v113
	v_mov_b32_e32 v113, v112
	v_mov_b32_e32 v154, v112
	s_nop 1
	v_permlane32_swap_b32_e32 v113, v154
	s_and_saveexec_b64 s[14:15], s[6:7]
	s_cbranch_execz .LBB0_1145
	v_lshlrev_b64 v[116:117], 6, v[130:131]
	v_lshl_add_u64 v[116:117], s[20:21], 0, v[116:117]
	v_lshl_add_u64 v[116:117], s[12:13], 2, v[116:117]
	s_lshl_b32 s16, s28, 2
	s_mov_b32 s17, s36
	v_lshl_add_u64 v[116:117], v[116:117], 0, s[16:17]
	s_waitcnt lgkmcnt(0)
	v_add_f32_e32 v112, v113, v154
	global_store_dword v[116:117], v112, off
; __device__ __forceinline__ unsigned cvt_pk_bf16(float lo, float hi) { unsigned r; asm volatile("v_cvt_pk_bf16_f32 %0, %1, %2" : "=v"(r) : "v"(lo), "v"(hi)); return r; }
; __device__ __forceinline__ void UNPACK8(const u32x4 q, float (&f)[8]) { f[0] = bflo(q.x); f[1] = bfhi(q.x); f[2] = bflo(q.y); f[3] = bfhi(q.y); f[4] = bflo(q.z); f[5] = bfhi(q.z); f[6] = bflo(q.w); f[7] = bfhi(q.w); }
; #define EPI_FOR_ROWS() _Pragma("unroll") for (int ai = 0; ai < 2; ++ai) _Pragma("unroll") for (int m = 0; m < 4; ++m)
;     __device__ __forceinline__ void operator()(const f32x4 (&acc)[2][2][4][2], const Unit& u, int wr, int wc, int fr, int fq) const {
;         EPI_ROWCOL();
;         EPI_FOR_ROWS() {
;             const int row = row0 + ai * 128 + m * 16; float ss = 0.f;
; #pragma unroll
;             for (int bj = 0; bj < 2; ++bj) { const int col = col0 + bj * 128; const size_t off = (size_t)row * 1024 + col;
;                 const u32x4 xw = *(const u32x4*)(xb + off); float xo[8]; UNPACK8(xw, xo);
;                 const f32x4 x0 = (f32x4){xo[0], xo[1], xo[2], xo[3]} + acc[ai][bj][m][0], x1 = (f32x4){xo[4], xo[5], xo[6], xo[7]} + acc[ai][bj][m][1];
;                 ss += (x0[0] * x0[0] + x0[1] * x0[1]) + (x0[2] * x0[2] + x0[3] * x0[3]) + (x1[0] * x1[0] + x1[1] * x1[1]) + (x1[2] * x1[2] + x1[3] * x1[3]);
;                 u32x4 w; w.x = cvt_pk_bf16(x0[0], x0[1]); w.y = cvt_pk_bf16(x0[2], x0[3]); w.z = cvt_pk_bf16(x1[0], x1[1]); w.w = cvt_pk_bf16(x1[2], x1[3]);
;                 *(u32x4*)(xb + off) = w; }
;             ss += __shfl_xor(ss, 16); ss += __shfl_xor(ss, 32);
;             if (fq == 0) ssq[(size_t)row * 16 + u.pn * 4 + wc] = ss;
;         }
.LBB0_1145:
	s_or_b64 exec, exec, s[14:15]
	v_or_b32_e32 v112, 16, v130
	s_waitcnt lgkmcnt(0)
	v_ashrrev_i32_e32 v113, 31, v112
	v_lshlrev_b64 v[116:117], 11, v[112:113]
	v_lshl_add_u64 v[116:117], s[22:23], 0, v[116:117]
	v_lshl_add_u64 v[120:121], v[128:129], 1, v[116:117]
	v_mov_b32_e32 v116, v178
	v_mov_b32_e32 v117, v179
	v_mov_b32_e32 v118, v180
	v_mov_b32_e32 v119, v181
	v_lshlrev_b32_e32 v122, 16, v116
	v_and_b32_e32 v123, 0xffff0000, v116
	v_lshlrev_b32_e32 v116, 16, v117
	v_and_b32_e32 v117, 0xffff0000, v117
	v_lshlrev_b32_e32 v124, 16, v118
	v_and_b32_e32 v125, 0xffff0000, v118
	v_lshlrev_b32_e32 v118, 16, v119
	v_and_b32_e32 v119, 0xffff0000, v119
	v_pk_add_f32 v[116:117], v[110:111], v[116:117]
	v_pk_add_f32 v[122:123], v[108:109], v[122:123]
	v_pk_add_f32 v[118:119], v[106:107], v[118:119]
	v_pk_add_f32 v[124:125], v[104:105], v[124:125]
	v_cvt_pk_bf16_f32 v104, v122, v123
	v_cvt_pk_bf16_f32 v105, v116, v117
	v_mul_f32_e32 v123, v123, v123
	v_cvt_pk_bf16_f32 v106, v124, v125
	v_cvt_pk_bf16_f32 v107, v118, v119
	v_mov_b32_e32 v108, v182
	v_mov_b32_e32 v109, v183
	v_mov_b32_e32 v110, v184
	v_mov_b32_e32 v111, v185
	v_mul_f32_e32 v117, v117, v117
	v_mul_f32_e32 v125, v125, v125
	v_fmac_f32_e32 v123, v122, v122
	v_fmac_f32_e32 v117, v116, v116
	v_mul_f32_e32 v119, v119, v119
	v_fmac_f32_e32 v125, v124, v124
	v_add_f32_e32 v116, v123, v117
	v_fmac_f32_e32 v119, v118, v118
	v_add_f32_e32 v116, v125, v116
	v_add_f32_e32 v122, v119, v116
	global_store_dwordx4 v[120:121], v[104:107], off
	v_lshlrev_b32_e32 v116, 16, v108
	v_and_b32_e32 v117, 0xffff0000, v108
	v_lshlrev_b32_e32 v108, 16, v109
	v_and_b32_e32 v109, 0xffff0000, v109
	v_lshlrev_b32_e32 v118, 16, v110
	v_and_b32_e32 v119, 0xffff0000, v110
	v_lshlrev_b32_e32 v110, 16, v111
	v_and_b32_e32 v111, 0xffff0000, v111
	v_pk_add_f32 v[102:103], v[102:103], v[108:109]
	v_pk_add_f32 v[100:101], v[100:101], v[116:117]
	v_pk_add_f32 v[108:109], v[98:99], v[110:111]
	v_pk_add_f32 v[110:111], v[96:97], v[118:119]
	v_mul_f32_e32 v96, v101, v101
	v_mul_f32_e32 v97, v103, v103
	v_mul_f32_e32 v98, v111, v111
	v_fmac_f32_e32 v96, v100, v100
	v_fmac_f32_e32 v97, v102, v102
	v_mul_f32_e32 v99, v109, v109
	v_fmac_f32_e32 v98, v110, v110
	v_add_f32_e32 v96, v96, v97
	v_add_f32_e32 v96, v98, v96
	v_fmac_f32_e32 v99, v108, v108
	v_add_f32_e32 v96, v99, v96
	v_add_f32_e32 v96, v122, v96
	v_mov_b32_e32 v97, v96
	v_mov_b32_e32 v154, v96
	s_nop 1
	v_permlane16_swap_b32_e32 v97, v154
	v_cvt_pk_bf16_f32 v98, v100, v101
	v_cvt_pk_bf16_f32 v99, v102, v103
	v_cvt_pk_bf16_f32 v100, v110, v111
	v_cvt_pk_bf16_f32 v101, v108, v109
	s_waitcnt lgkmcnt(0)
	v_add_f32_e32 v96, v97, v154
	v_mov_b32_e32 v97, v96
	v_mov_b32_e32 v154, v96
	s_nop 1
	v_permlane32_swap_b32_e32 v97, v154
	global_store_dwordx4 v[120:121], v[98:101], off offset:256
	s_and_saveexec_b64 s[14:15], s[6:7]
	s_cbranch_execz .LBB0_1147
	v_lshlrev_b64 v[98:99], 6, v[112:113]
	v_lshl_add_u64 v[98:99], s[20:21], 0, v[98:99]
	v_lshl_add_u64 v[98:99], s[12:13], 2, v[98:99]
	s_lshl_b32 s16, s28, 2
	s_mov_b32 s17, s36
	v_lshl_add_u64 v[98:99], v[98:99], 0, s[16:17]
	s_waitcnt lgkmcnt(0)
	v_add_f32_e32 v96, v97, v154
	global_store_dword v[98:99], v96, off
.LBB0_1147:
	s_or_b64 exec, exec, s[14:15]
	v_or_b32_e32 v96, 32, v130
	s_waitcnt lgkmcnt(0)
	v_ashrrev_i32_e32 v97, 31, v96
	v_lshlrev_b64 v[98:99], 11, v[96:97]
	v_lshl_add_u64 v[98:99], s[22:23], 0, v[98:99]
	v_lshl_add_u64 v[102:103], v[128:129], 1, v[98:99]
	v_mov_b32_e32 v98, v186
	v_mov_b32_e32 v99, v187
	v_mov_b32_e32 v100, v188
	v_mov_b32_e32 v101, v189
	v_lshlrev_b32_e32 v104, 16, v98
	v_and_b32_e32 v105, 0xffff0000, v98
	v_lshlrev_b32_e32 v98, 16, v99
	v_and_b32_e32 v99, 0xffff0000, v99
	v_lshlrev_b32_e32 v106, 16, v100
	v_and_b32_e32 v107, 0xffff0000, v100
	v_lshlrev_b32_e32 v100, 16, v101
	v_and_b32_e32 v101, 0xffff0000, v101
	v_pk_add_f32 v[98:99], v[94:95], v[98:99]
	v_pk_add_f32 v[104:105], v[92:93], v[104:105]
	v_pk_add_f32 v[100:101], v[90:91], v[100:101]
	v_pk_add_f32 v[106:107], v[88:89], v[106:107]
	v_cvt_pk_bf16_f32 v88, v104, v105
	v_cvt_pk_bf16_f32 v89, v98, v99
	v_mul_f32_e32 v105, v105, v105
	v_cvt_pk_bf16_f32 v90, v106, v107
	v_cvt_pk_bf16_f32 v91, v100, v101
	v_mov_b32_e32 v92, v190
	v_mov_b32_e32 v93, v191
	v_mov_b32_e32 v94, v192
	v_mov_b32_e32 v95, v193
	v_mul_f32_e32 v99, v99, v99
	v_mul_f32_e32 v107, v107, v107
	v_fmac_f32_e32 v105, v104, v104
	v_fmac_f32_e32 v99, v98, v98
	v_mul_f32_e32 v101, v101, v101
	v_fmac_f32_e32 v107, v106, v106
	v_add_f32_e32 v98, v105, v99
	v_fmac_f32_e32 v101, v100, v100
	v_add_f32_e32 v98, v107, v98
	v_add_f32_e32 v104, v101, v98
	global_store_dwordx4 v[102:103], v[88:91], off
	v_lshlrev_b32_e32 v98, 16, v92
	v_and_b32_e32 v99, 0xffff0000, v92
	v_lshlrev_b32_e32 v92, 16, v93
	v_and_b32_e32 v93, 0xffff0000, v93
	v_lshlrev_b32_e32 v100, 16, v94
	v_and_b32_e32 v101, 0xffff0000, v94
	v_lshlrev_b32_e32 v94, 16, v95
	v_and_b32_e32 v95, 0xffff0000, v95
	v_pk_add_f32 v[86:87], v[86:87], v[92:93]
	v_pk_add_f32 v[84:85], v[84:85], v[98:99]
	v_pk_add_f32 v[92:93], v[82:83], v[94:95]
	v_pk_add_f32 v[94:95], v[80:81], v[100:101]
	v_mul_f32_e32 v80, v85, v85
	v_mul_f32_e32 v81, v87, v87
	v_mul_f32_e32 v82, v95, v95
	v_fmac_f32_e32 v80, v84, v84
	v_fmac_f32_e32 v81, v86, v86
	v_mul_f32_e32 v83, v93, v93
	v_fmac_f32_e32 v82, v94, v94
	v_add_f32_e32 v80, v80, v81
	v_add_f32_e32 v80, v82, v80
	v_fmac_f32_e32 v83, v92, v92
	v_add_f32_e32 v80, v83, v80
	v_add_f32_e32 v80, v104, v80
	v_mov_b32_e32 v81, v80
	v_mov_b32_e32 v154, v80
	s_nop 1
	v_permlane16_swap_b32_e32 v81, v154
	v_cvt_pk_bf16_f32 v82, v84, v85
	v_cvt_pk_bf16_f32 v83, v86, v87
	v_cvt_pk_bf16_f32 v84, v94, v95
	v_cvt_pk_bf16_f32 v85, v92, v93
	s_waitcnt lgkmcnt(0)
	v_add_f32_e32 v80, v81, v154
	v_mov_b32_e32 v81, v80
	v_mov_b32_e32 v154, v80
	s_nop 1
	v_permlane32_swap_b32_e32 v81, v154
	global_store_dwordx4 v[102:103], v[82:85], off offset:256
	s_and_saveexec_b64 s[14:15], s[6:7]
	s_cbranch_execz .LBB0_1149
	v_lshlrev_b64 v[82:83], 6, v[96:97]
	v_lshl_add_u64 v[82:83], s[20:21], 0, v[82:83]
	v_lshl_add_u64 v[82:83], s[12:13], 2, v[82:83]
	s_lshl_b32 s16, s28, 2
	s_mov_b32 s17, s36
	v_lshl_add_u64 v[82:83], v[82:83], 0, s[16:17]
	s_waitcnt lgkmcnt(0)
	v_add_f32_e32 v80, v81, v154
	global_store_dword v[82:83], v80, off
; __device__ __forceinline__ unsigned cvt_pk_bf16(float lo, float hi) { unsigned r; asm volatile("v_cvt_pk_bf16_f32 %0, %1, %2" : "=v"(r) : "v"(lo), "v"(hi)); return r; }
; __device__ __forceinline__ void UNPACK8(const u32x4 q, float (&f)[8]) { f[0] = bflo(q.x); f[1] = bfhi(q.x); f[2] = bflo(q.y); f[3] = bfhi(q.y); f[4] = bflo(q.z); f[5] = bfhi(q.z); f[6] = bflo(q.w); f[7] = bfhi(q.w); }
; #define EPI_FOR_ROWS() _Pragma("unroll") for (int ai = 0; ai < 2; ++ai) _Pragma("unroll") for (int m = 0; m < 4; ++m)
;     __device__ __forceinline__ void operator()(const f32x4 (&acc)[2][2][4][2], const Unit& u, int wr, int wc, int fr, int fq) const {
;     ...
;         EPI_FOR_ROWS() {
;             const int row = row0 + ai * 128 + m * 16; float ss = 0.f;
; #pragma unroll
;             for (int bj = 0; bj < 2; ++bj) { const int col = col0 + bj * 128; const size_t off = (size_t)row * 1024 + col;
;                 const u32x4 xw = *(const u32x4*)(xb + off); float xo[8]; UNPACK8(xw, xo);
;                 const f32x4 x0 = (f32x4){xo[0], xo[1], xo[2], xo[3]} + acc[ai][bj][m][0], x1 = (f32x4){xo[4], xo[5], xo[6], xo[7]} + acc[ai][bj][m][1];
;                 ss += (x0[0] * x0[0] + x0[1] * x0[1]) + (x0[2] * x0[2] + x0[3] * x0[3]) + (x1[0] * x1[0] + x1[1] * x1[1]) + (x1[2] * x1[2] + x1[3] * x1[3]);
;                 u32x4 w; w.x = cvt_pk_bf16(x0[0], x0[1]); w.y = cvt_pk_bf16(x0[2], x0[3]); w.z = cvt_pk_bf16(x1[0], x1[1]); w.w = cvt_pk_bf16(x1[2], x1[3]);
;                 *(u32x4*)(xb + off) = w; }
;             ss += __shfl_xor(ss, 16); ss += __shfl_xor(ss, 32);
;             if (fq == 0) ssq[(size_t)row * 16 + u.pn * 4 + wc] = ss;
;         }
.LBB0_1149:
	s_or_b64 exec, exec, s[14:15]
	v_or_b32_e32 v80, 48, v130
	s_waitcnt lgkmcnt(0)
	v_ashrrev_i32_e32 v81, 31, v80
	v_lshlrev_b64 v[82:83], 11, v[80:81]
	v_lshl_add_u64 v[82:83], s[22:23], 0, v[82:83]
	v_lshl_add_u64 v[86:87], v[128:129], 1, v[82:83]
	v_mov_b32_e32 v82, v194
	v_mov_b32_e32 v83, v195
	v_mov_b32_e32 v84, v196
	v_mov_b32_e32 v85, v197
	v_lshlrev_b32_e32 v88, 16, v82
	v_and_b32_e32 v89, 0xffff0000, v82
	v_lshlrev_b32_e32 v82, 16, v83
	v_and_b32_e32 v83, 0xffff0000, v83
	v_lshlrev_b32_e32 v90, 16, v84
	v_and_b32_e32 v91, 0xffff0000, v84
	v_lshlrev_b32_e32 v84, 16, v85
	v_and_b32_e32 v85, 0xffff0000, v85
	v_pk_add_f32 v[82:83], v[78:79], v[82:83]
	v_pk_add_f32 v[88:89], v[76:77], v[88:89]
	v_pk_add_f32 v[84:85], v[74:75], v[84:85]
	v_pk_add_f32 v[90:91], v[72:73], v[90:91]
	v_cvt_pk_bf16_f32 v72, v88, v89
	v_cvt_pk_bf16_f32 v73, v82, v83
	v_mul_f32_e32 v89, v89, v89
	v_cvt_pk_bf16_f32 v74, v90, v91
	v_cvt_pk_bf16_f32 v75, v84, v85
	v_mov_b32_e32 v76, v198
	v_mov_b32_e32 v77, v199
	v_mov_b32_e32 v78, v200
	v_mov_b32_e32 v79, v201
	v_mul_f32_e32 v83, v83, v83
	v_mul_f32_e32 v91, v91, v91
	v_fmac_f32_e32 v89, v88, v88
	v_fmac_f32_e32 v83, v82, v82
	v_mul_f32_e32 v85, v85, v85
	v_fmac_f32_e32 v91, v90, v90
	v_add_f32_e32 v82, v89, v83
	v_fmac_f32_e32 v85, v84, v84
	v_add_f32_e32 v82, v91, v82
	v_add_f32_e32 v88, v85, v82
	global_store_dwordx4 v[86:87], v[72:75], off
	v_lshlrev_b32_e32 v82, 16, v76
	v_and_b32_e32 v83, 0xffff0000, v76
	v_lshlrev_b32_e32 v76, 16, v77
	v_and_b32_e32 v77, 0xffff0000, v77
	v_lshlrev_b32_e32 v84, 16, v78
	v_and_b32_e32 v85, 0xffff0000, v78
	v_lshlrev_b32_e32 v78, 16, v79
	v_and_b32_e32 v79, 0xffff0000, v79
	v_pk_add_f32 v[70:71], v[70:71], v[76:77]
	v_pk_add_f32 v[68:69], v[68:69], v[82:83]
	v_pk_add_f32 v[76:77], v[66:67], v[78:79]
	v_pk_add_f32 v[78:79], v[64:65], v[84:85]
	v_mul_f32_e32 v64, v69, v69
	v_mul_f32_e32 v65, v71, v71
	v_mul_f32_e32 v66, v79, v79
	v_fmac_f32_e32 v64, v68, v68
	v_fmac_f32_e32 v65, v70, v70
	v_mul_f32_e32 v67, v77, v77
	v_fmac_f32_e32 v66, v78, v78
	v_add_f32_e32 v64, v64, v65
	v_add_f32_e32 v64, v66, v64
	v_fmac_f32_e32 v67, v76, v76
	v_add_f32_e32 v64, v67, v64
	v_add_f32_e32 v64, v88, v64
	v_mov_b32_e32 v65, v64
	v_mov_b32_e32 v154, v64
	s_nop 1
	v_permlane16_swap_b32_e32 v65, v154
	v_cvt_pk_bf16_f32 v66, v68, v69
	v_cvt_pk_bf16_f32 v67, v70, v71
	v_cvt_pk_bf16_f32 v68, v78, v79
	v_cvt_pk_bf16_f32 v69, v76, v77
	s_waitcnt lgkmcnt(0)
	v_add_f32_e32 v64, v65, v154
	v_mov_b32_e32 v65, v64
	v_mov_b32_e32 v154, v64
	s_nop 1
	v_permlane32_swap_b32_e32 v65, v154
	global_store_dwordx4 v[86:87], v[66:69], off offset:256
	s_and_saveexec_b64 s[14:15], s[6:7]
	s_cbranch_execz .LBB0_1151
	v_lshlrev_b64 v[66:67], 6, v[80:81]
	v_lshl_add_u64 v[66:67], s[20:21], 0, v[66:67]
	v_lshl_add_u64 v[66:67], s[12:13], 2, v[66:67]
	s_lshl_b32 s16, s28, 2
	s_mov_b32 s17, s36
	v_lshl_add_u64 v[66:67], v[66:67], 0, s[16:17]
	s_waitcnt lgkmcnt(0)
	v_add_f32_e32 v64, v65, v154
	global_store_dword v[66:67], v64, off
.LBB0_1151:
	s_or_b64 exec, exec, s[14:15]
	v_add_u32_e32 v64, 0x80, v130
	s_waitcnt lgkmcnt(0)
	v_ashrrev_i32_e32 v65, 31, v64
	v_lshlrev_b64 v[66:67], 11, v[64:65]
	v_lshl_add_u64 v[66:67], s[22:23], 0, v[66:67]
	v_lshl_add_u64 v[70:71], v[128:129], 1, v[66:67]
	v_mov_b32_e32 v66, v202
	v_mov_b32_e32 v67, v203
	v_mov_b32_e32 v68, v204
	v_mov_b32_e32 v69, v205
	v_lshlrev_b32_e32 v72, 16, v66
	v_and_b32_e32 v73, 0xffff0000, v66
	v_lshlrev_b32_e32 v66, 16, v67
	v_and_b32_e32 v67, 0xffff0000, v67
	v_lshlrev_b32_e32 v74, 16, v68
	v_and_b32_e32 v75, 0xffff0000, v68
	v_lshlrev_b32_e32 v68, 16, v69
	v_and_b32_e32 v69, 0xffff0000, v69
	v_pk_add_f32 v[66:67], v[62:63], v[66:67]
	v_pk_add_f32 v[72:73], v[60:61], v[72:73]
	v_pk_add_f32 v[68:69], v[58:59], v[68:69]
	v_pk_add_f32 v[74:75], v[56:57], v[74:75]
	v_cvt_pk_bf16_f32 v56, v72, v73
	v_cvt_pk_bf16_f32 v57, v66, v67
	v_mul_f32_e32 v73, v73, v73
	v_cvt_pk_bf16_f32 v58, v74, v75
	v_cvt_pk_bf16_f32 v59, v68, v69
	v_mov_b32_e32 v60, v214
	v_mov_b32_e32 v61, v215
	v_mov_b32_e32 v62, v216
	v_mov_b32_e32 v63, v217
	v_mul_f32_e32 v67, v67, v67
	v_mul_f32_e32 v75, v75, v75
	v_fmac_f32_e32 v73, v72, v72
	v_fmac_f32_e32 v67, v66, v66
	v_mul_f32_e32 v69, v69, v69
	v_fmac_f32_e32 v75, v74, v74
	v_add_f32_e32 v66, v73, v67
	v_fmac_f32_e32 v69, v68, v68
	v_add_f32_e32 v66, v75, v66
	v_add_f32_e32 v72, v69, v66
	global_store_dwordx4 v[70:71], v[56:59], off
	v_lshlrev_b32_e32 v66, 16, v60
	v_and_b32_e32 v67, 0xffff0000, v60
	v_lshlrev_b32_e32 v60, 16, v61
	v_and_b32_e32 v61, 0xffff0000, v61
	v_lshlrev_b32_e32 v68, 16, v62
	v_and_b32_e32 v69, 0xffff0000, v62
	v_lshlrev_b32_e32 v62, 16, v63
	v_and_b32_e32 v63, 0xffff0000, v63
	v_pk_add_f32 v[54:55], v[54:55], v[60:61]
	v_pk_add_f32 v[52:53], v[52:53], v[66:67]
	v_pk_add_f32 v[60:61], v[50:51], v[62:63]
	v_pk_add_f32 v[62:63], v[48:49], v[68:69]
	v_mul_f32_e32 v48, v53, v53
	v_mul_f32_e32 v49, v55, v55
	v_mul_f32_e32 v50, v63, v63
	v_fmac_f32_e32 v48, v52, v52
	v_fmac_f32_e32 v49, v54, v54
	v_mul_f32_e32 v51, v61, v61
	v_fmac_f32_e32 v50, v62, v62
	v_add_f32_e32 v48, v48, v49
	v_add_f32_e32 v48, v50, v48
	v_fmac_f32_e32 v51, v60, v60
	v_add_f32_e32 v48, v51, v48
	v_add_f32_e32 v48, v72, v48
	v_mov_b32_e32 v49, v48
	v_mov_b32_e32 v154, v48
	s_nop 1
	v_permlane16_swap_b32_e32 v49, v154
	v_cvt_pk_bf16_f32 v50, v52, v53
	v_cvt_pk_bf16_f32 v51, v54, v55
	v_cvt_pk_bf16_f32 v52, v62, v63
	v_cvt_pk_bf16_f32 v53, v60, v61
	s_waitcnt lgkmcnt(0)
	v_add_f32_e32 v48, v49, v154
	v_mov_b32_e32 v49, v48
	v_mov_b32_e32 v154, v48
	s_nop 1
	v_permlane32_swap_b32_e32 v49, v154
	global_store_dwordx4 v[70:71], v[50:53], off offset:256
	s_and_saveexec_b64 s[14:15], s[6:7]
	s_cbranch_execz .LBB0_1153
	v_lshlrev_b64 v[50:51], 6, v[64:65]
	v_lshl_add_u64 v[50:51], s[20:21], 0, v[50:51]
	v_lshl_add_u64 v[50:51], s[12:13], 2, v[50:51]
	s_lshl_b32 s16, s28, 2
	s_mov_b32 s17, s36
	v_lshl_add_u64 v[50:51], v[50:51], 0, s[16:17]
	s_waitcnt lgkmcnt(0)
	v_add_f32_e32 v48, v49, v154
	global_store_dword v[50:51], v48, off
; __device__ __forceinline__ unsigned cvt_pk_bf16(float lo, float hi) { unsigned r; asm volatile("v_cvt_pk_bf16_f32 %0, %1, %2" : "=v"(r) : "v"(lo), "v"(hi)); return r; }
; __device__ __forceinline__ void UNPACK8(const u32x4 q, float (&f)[8]) { f[0] = bflo(q.x); f[1] = bfhi(q.x); f[2] = bflo(q.y); f[3] = bfhi(q.y); f[4] = bflo(q.z); f[5] = bfhi(q.z); f[6] = bflo(q.w); f[7] = bfhi(q.w); }
; #define EPI_FOR_ROWS() _Pragma("unroll") for (int ai = 0; ai < 2; ++ai) _Pragma("unroll") for (int m = 0; m < 4; ++m)
;     __device__ __forceinline__ void operator()(const f32x4 (&acc)[2][2][4][2], const Unit& u, int wr, int wc, int fr, int fq) const {
;     ...
;         EPI_FOR_ROWS() {
;             const int row = row0 + ai * 128 + m * 16; float ss = 0.f;
; #pragma unroll
;             for (int bj = 0; bj < 2; ++bj) { const int col = col0 + bj * 128; const size_t off = (size_t)row * 1024 + col;
;                 const u32x4 xw = *(const u32x4*)(xb + off); float xo[8]; UNPACK8(xw, xo);
;                 const f32x4 x0 = (f32x4){xo[0], xo[1], xo[2], xo[3]} + acc[ai][bj][m][0], x1 = (f32x4){xo[4], xo[5], xo[6], xo[7]} + acc[ai][bj][m][1];
;                 ss += (x0[0] * x0[0] + x0[1] * x0[1]) + (x0[2] * x0[2] + x0[3] * x0[3]) + (x1[0] * x1[0] + x1[1] * x1[1]) + (x1[2] * x1[2] + x1[3] * x1[3]);
;                 u32x4 w; w.x = cvt_pk_bf16(x0[0], x0[1]); w.y = cvt_pk_bf16(x0[2], x0[3]); w.z = cvt_pk_bf16(x1[0], x1[1]); w.w = cvt_pk_bf16(x1[2], x1[3]);
;                 *(u32x4*)(xb + off) = w; }
;             ss += __shfl_xor(ss, 16); ss += __shfl_xor(ss, 32);
;             if (fq == 0) ssq[(size_t)row * 16 + u.pn * 4 + wc] = ss;
;         }
.LBB0_1153:
	s_or_b64 exec, exec, s[14:15]
	v_add_u32_e32 v48, 0x90, v130
	s_waitcnt lgkmcnt(0)
	v_ashrrev_i32_e32 v49, 31, v48
	v_lshlrev_b64 v[50:51], 11, v[48:49]
	v_lshl_add_u64 v[50:51], s[22:23], 0, v[50:51]
	v_lshl_add_u64 v[54:55], v[128:129], 1, v[50:51]
	v_mov_b32_e32 v50, v218
	v_mov_b32_e32 v51, v219
	v_mov_b32_e32 v52, v220
	v_mov_b32_e32 v53, v221
	v_lshlrev_b32_e32 v56, 16, v50
	v_and_b32_e32 v57, 0xffff0000, v50
	v_lshlrev_b32_e32 v50, 16, v51
	v_and_b32_e32 v51, 0xffff0000, v51
	v_lshlrev_b32_e32 v58, 16, v52
	v_and_b32_e32 v59, 0xffff0000, v52
	v_lshlrev_b32_e32 v52, 16, v53
	v_and_b32_e32 v53, 0xffff0000, v53
	v_pk_add_f32 v[50:51], v[46:47], v[50:51]
	v_pk_add_f32 v[56:57], v[44:45], v[56:57]
	v_pk_add_f32 v[52:53], v[42:43], v[52:53]
	v_pk_add_f32 v[58:59], v[40:41], v[58:59]
	v_cvt_pk_bf16_f32 v40, v56, v57
	v_cvt_pk_bf16_f32 v41, v50, v51
	v_mul_f32_e32 v57, v57, v57
	v_cvt_pk_bf16_f32 v42, v58, v59
	v_cvt_pk_bf16_f32 v43, v52, v53
	v_mov_b32_e32 v44, v222
	v_mov_b32_e32 v45, v223
	v_mov_b32_e32 v46, v224
	v_mov_b32_e32 v47, v225
	v_mul_f32_e32 v51, v51, v51
	v_mul_f32_e32 v59, v59, v59
	v_fmac_f32_e32 v57, v56, v56
	v_fmac_f32_e32 v51, v50, v50
	v_mul_f32_e32 v53, v53, v53
	v_fmac_f32_e32 v59, v58, v58
	v_add_f32_e32 v50, v57, v51
	v_fmac_f32_e32 v53, v52, v52
	v_add_f32_e32 v50, v59, v50
	v_add_f32_e32 v56, v53, v50
	global_store_dwordx4 v[54:55], v[40:43], off
	v_lshlrev_b32_e32 v50, 16, v44
	v_and_b32_e32 v51, 0xffff0000, v44
	v_lshlrev_b32_e32 v44, 16, v45
	v_and_b32_e32 v45, 0xffff0000, v45
	v_lshlrev_b32_e32 v52, 16, v46
	v_and_b32_e32 v53, 0xffff0000, v46
	v_lshlrev_b32_e32 v46, 16, v47
	v_and_b32_e32 v47, 0xffff0000, v47
	v_pk_add_f32 v[38:39], v[38:39], v[44:45]
	v_pk_add_f32 v[36:37], v[36:37], v[50:51]
	v_pk_add_f32 v[44:45], v[34:35], v[46:47]
	v_pk_add_f32 v[46:47], v[32:33], v[52:53]
	v_mul_f32_e32 v32, v37, v37
	v_mul_f32_e32 v33, v39, v39
	v_mul_f32_e32 v34, v47, v47
	v_fmac_f32_e32 v32, v36, v36
	v_fmac_f32_e32 v33, v38, v38
	v_mul_f32_e32 v35, v45, v45
	v_fmac_f32_e32 v34, v46, v46
	v_add_f32_e32 v32, v32, v33
	v_add_f32_e32 v32, v34, v32
	v_fmac_f32_e32 v35, v44, v44
	v_add_f32_e32 v32, v35, v32
	v_add_f32_e32 v32, v56, v32
	v_mov_b32_e32 v33, v32
	v_mov_b32_e32 v154, v32
	s_nop 1
	v_permlane16_swap_b32_e32 v33, v154
	v_cvt_pk_bf16_f32 v34, v36, v37
	v_cvt_pk_bf16_f32 v35, v38, v39
	v_cvt_pk_bf16_f32 v36, v46, v47
	v_cvt_pk_bf16_f32 v37, v44, v45
	s_waitcnt lgkmcnt(0)
	v_add_f32_e32 v32, v33, v154
	v_mov_b32_e32 v33, v32
	v_mov_b32_e32 v154, v32
	s_nop 1
	v_permlane32_swap_b32_e32 v33, v154
	global_store_dwordx4 v[54:55], v[34:37], off offset:256
	s_and_saveexec_b64 s[14:15], s[6:7]
	s_cbranch_execz .LBB0_1155
	v_lshlrev_b64 v[34:35], 6, v[48:49]
	v_lshl_add_u64 v[34:35], s[20:21], 0, v[34:35]
	v_lshl_add_u64 v[34:35], s[12:13], 2, v[34:35]
	s_lshl_b32 s16, s28, 2
	s_mov_b32 s17, s36
	v_lshl_add_u64 v[34:35], v[34:35], 0, s[16:17]
	s_waitcnt lgkmcnt(0)
	v_add_f32_e32 v32, v33, v154
	global_store_dword v[34:35], v32, off
; __device__ __forceinline__ unsigned cvt_pk_bf16(float lo, float hi) { unsigned r; asm volatile("v_cvt_pk_bf16_f32 %0, %1, %2" : "=v"(r) : "v"(lo), "v"(hi)); return r; }
; __device__ __forceinline__ void UNPACK8(const u32x4 q, float (&f)[8]) { f[0] = bflo(q.x); f[1] = bfhi(q.x); f[2] = bflo(q.y); f[3] = bfhi(q.y); f[4] = bflo(q.z); f[5] = bfhi(q.z); f[6] = bflo(q.w); f[7] = bfhi(q.w); }
; #define EPI_FOR_ROWS() _Pragma("unroll") for (int ai = 0; ai < 2; ++ai) _Pragma("unroll") for (int m = 0; m < 4; ++m)
;     __device__ __forceinline__ void operator()(const f32x4 (&acc)[2][2][4][2], const Unit& u, int wr, int wc, int fr, int fq) const {
;     ...
;         EPI_FOR_ROWS() {
;             const int row = row0 + ai * 128 + m * 16; float ss = 0.f;
; #pragma unroll
;             for (int bj = 0; bj < 2; ++bj) { const int col = col0 + bj * 128; const size_t off = (size_t)row * 1024 + col;
;                 const u32x4 xw = *(const u32x4*)(xb + off); float xo[8]; UNPACK8(xw, xo);
;                 const f32x4 x0 = (f32x4){xo[0], xo[1], xo[2], xo[3]} + acc[ai][bj][m][0], x1 = (f32x4){xo[4], xo[5], xo[6], xo[7]} + acc[ai][bj][m][1];
;                 ss += (x0[0] * x0[0] + x0[1] * x0[1]) + (x0[2] * x0[2] + x0[3] * x0[3]) + (x1[0] * x1[0] + x1[1] * x1[1]) + (x1[2] * x1[2] + x1[3] * x1[3]);
;                 u32x4 w; w.x = cvt_pk_bf16(x0[0], x0[1]); w.y = cvt_pk_bf16(x0[2], x0[3]); w.z = cvt_pk_bf16(x1[0], x1[1]); w.w = cvt_pk_bf16(x1[2], x1[3]);
;                 *(u32x4*)(xb + off) = w; }
;             ss += __shfl_xor(ss, 16); ss += __shfl_xor(ss, 32);
;             if (fq == 0) ssq[(size_t)row * 16 + u.pn * 4 + wc] = ss;
;         }
.LBB0_1155:
	s_or_b64 exec, exec, s[14:15]
	v_add_u32_e32 v32, 0xa0, v130
	s_waitcnt lgkmcnt(0)
	v_ashrrev_i32_e32 v33, 31, v32
	v_lshlrev_b64 v[34:35], 11, v[32:33]
	v_lshl_add_u64 v[34:35], s[22:23], 0, v[34:35]
	v_lshl_add_u64 v[38:39], v[128:129], 1, v[34:35]
	v_mov_b32_e32 v34, v226
	v_mov_b32_e32 v35, v227
	v_mov_b32_e32 v36, v228
	v_mov_b32_e32 v37, v229
	v_lshlrev_b32_e32 v40, 16, v34
	v_and_b32_e32 v41, 0xffff0000, v34
	v_lshlrev_b32_e32 v34, 16, v35
	v_and_b32_e32 v35, 0xffff0000, v35
	v_lshlrev_b32_e32 v42, 16, v36
	v_and_b32_e32 v43, 0xffff0000, v36
	v_lshlrev_b32_e32 v36, 16, v37
	v_and_b32_e32 v37, 0xffff0000, v37
	v_pk_add_f32 v[34:35], v[30:31], v[34:35]
	v_pk_add_f32 v[40:41], v[28:29], v[40:41]
	v_pk_add_f32 v[36:37], v[26:27], v[36:37]
	v_pk_add_f32 v[42:43], v[24:25], v[42:43]
	v_cvt_pk_bf16_f32 v24, v40, v41
	v_cvt_pk_bf16_f32 v25, v34, v35
	v_mul_f32_e32 v41, v41, v41
	v_cvt_pk_bf16_f32 v26, v42, v43
	v_cvt_pk_bf16_f32 v27, v36, v37
	v_mov_b32_e32 v28, v230
	v_mov_b32_e32 v29, v231
	v_mov_b32_e32 v30, v232
	v_mov_b32_e32 v31, v233
	v_mul_f32_e32 v35, v35, v35
	v_mul_f32_e32 v43, v43, v43
	v_fmac_f32_e32 v41, v40, v40
	v_fmac_f32_e32 v35, v34, v34
	v_mul_f32_e32 v37, v37, v37
	v_fmac_f32_e32 v43, v42, v42
	v_add_f32_e32 v34, v41, v35
	v_fmac_f32_e32 v37, v36, v36
	v_add_f32_e32 v34, v43, v34
	v_add_f32_e32 v40, v37, v34
	global_store_dwordx4 v[38:39], v[24:27], off
	v_lshlrev_b32_e32 v34, 16, v28
	v_and_b32_e32 v35, 0xffff0000, v28
	v_lshlrev_b32_e32 v28, 16, v29
	v_and_b32_e32 v29, 0xffff0000, v29
	v_lshlrev_b32_e32 v36, 16, v30
	v_and_b32_e32 v37, 0xffff0000, v30
	v_lshlrev_b32_e32 v30, 16, v31
	v_and_b32_e32 v31, 0xffff0000, v31
	v_pk_add_f32 v[22:23], v[22:23], v[28:29]
	v_pk_add_f32 v[20:21], v[20:21], v[34:35]
	v_pk_add_f32 v[28:29], v[18:19], v[30:31]
	v_pk_add_f32 v[30:31], v[16:17], v[36:37]
	v_mul_f32_e32 v16, v21, v21
	v_mul_f32_e32 v17, v23, v23
	v_mul_f32_e32 v18, v31, v31
	v_fmac_f32_e32 v16, v20, v20
	v_fmac_f32_e32 v17, v22, v22
	v_mul_f32_e32 v19, v29, v29
	v_fmac_f32_e32 v18, v30, v30
	v_add_f32_e32 v16, v16, v17
	v_add_f32_e32 v16, v18, v16
	v_fmac_f32_e32 v19, v28, v28
	v_add_f32_e32 v16, v19, v16
	v_add_f32_e32 v16, v40, v16
	v_mov_b32_e32 v17, v16
	v_mov_b32_e32 v154, v16
	s_nop 1
	v_permlane16_swap_b32_e32 v17, v154
	v_cvt_pk_bf16_f32 v18, v20, v21
	v_cvt_pk_bf16_f32 v19, v22, v23
	v_cvt_pk_bf16_f32 v20, v30, v31
	v_cvt_pk_bf16_f32 v21, v28, v29
	s_waitcnt lgkmcnt(0)
	v_add_f32_e32 v16, v17, v154
	v_mov_b32_e32 v17, v16
	v_mov_b32_e32 v154, v16
	s_nop 1
	v_permlane32_swap_b32_e32 v17, v154
	global_store_dwordx4 v[38:39], v[18:21], off offset:256
	s_and_saveexec_b64 s[14:15], s[6:7]
	s_cbranch_execz .LBB0_1157
	v_lshlrev_b64 v[18:19], 6, v[32:33]
	v_lshl_add_u64 v[18:19], s[20:21], 0, v[18:19]
	v_lshl_add_u64 v[18:19], s[12:13], 2, v[18:19]
	s_lshl_b32 s16, s28, 2
	s_mov_b32 s17, s36
	v_lshl_add_u64 v[18:19], v[18:19], 0, s[16:17]
	s_waitcnt lgkmcnt(0)
	v_add_f32_e32 v16, v17, v154
	global_store_dword v[18:19], v16, off
.LBB0_1157:
	s_or_b64 exec, exec, s[14:15]
	v_add_u32_e32 v16, 0xb0, v130
	s_waitcnt lgkmcnt(0)
	v_ashrrev_i32_e32 v17, 31, v16
	v_lshlrev_b64 v[18:19], 11, v[16:17]
	v_lshl_add_u64 v[18:19], s[22:23], 0, v[18:19]
	v_lshl_add_u64 v[22:23], v[128:129], 1, v[18:19]
	v_mov_b32_e32 v18, v234
	v_mov_b32_e32 v19, v235
	v_mov_b32_e32 v20, v236
	v_mov_b32_e32 v21, v237
	v_lshlrev_b32_e32 v24, 16, v18
	v_and_b32_e32 v25, 0xffff0000, v18
	v_lshlrev_b32_e32 v18, 16, v19
	v_and_b32_e32 v19, 0xffff0000, v19
	v_lshlrev_b32_e32 v26, 16, v20
	v_and_b32_e32 v27, 0xffff0000, v20
	v_lshlrev_b32_e32 v20, 16, v21
	v_and_b32_e32 v21, 0xffff0000, v21
	v_pk_add_f32 v[18:19], v[14:15], v[18:19]
	v_pk_add_f32 v[24:25], v[12:13], v[24:25]
	v_pk_add_f32 v[20:21], v[10:11], v[20:21]
	v_pk_add_f32 v[26:27], v[8:9], v[26:27]
	v_cvt_pk_bf16_f32 v8, v24, v25
	v_cvt_pk_bf16_f32 v9, v18, v19
	v_mul_f32_e32 v25, v25, v25
	v_cvt_pk_bf16_f32 v10, v26, v27
	v_cvt_pk_bf16_f32 v11, v20, v21
	v_mov_b32_e32 v12, v238
	v_mov_b32_e32 v13, v239
	v_mov_b32_e32 v14, v240
	v_mov_b32_e32 v15, v241
	v_mul_f32_e32 v19, v19, v19
	v_mul_f32_e32 v27, v27, v27
	v_fmac_f32_e32 v25, v24, v24
	v_fmac_f32_e32 v19, v18, v18
	v_mul_f32_e32 v21, v21, v21
	v_fmac_f32_e32 v27, v26, v26
	v_add_f32_e32 v18, v25, v19
	v_fmac_f32_e32 v21, v20, v20
	v_add_f32_e32 v18, v27, v18
	v_add_f32_e32 v24, v21, v18
	global_store_dwordx4 v[22:23], v[8:11], off
	v_lshlrev_b32_e32 v18, 16, v12
	v_and_b32_e32 v19, 0xffff0000, v12
	v_lshlrev_b32_e32 v12, 16, v13
	v_and_b32_e32 v13, 0xffff0000, v13
	v_lshlrev_b32_e32 v20, 16, v14
	v_and_b32_e32 v21, 0xffff0000, v14
	v_lshlrev_b32_e32 v14, 16, v15
	v_and_b32_e32 v15, 0xffff0000, v15
	v_pk_add_f32 v[6:7], v[6:7], v[12:13]
	v_pk_add_f32 v[4:5], v[4:5], v[18:19]
	v_pk_add_f32 v[12:13], v[2:3], v[14:15]
	v_pk_add_f32 v[14:15], v[0:1], v[20:21]
	v_mul_f32_e32 v0, v5, v5
	v_mul_f32_e32 v1, v7, v7
	v_mul_f32_e32 v2, v15, v15
	v_fmac_f32_e32 v0, v4, v4
	v_fmac_f32_e32 v1, v6, v6
	v_mul_f32_e32 v3, v13, v13
	v_fmac_f32_e32 v2, v14, v14
	v_add_f32_e32 v0, v0, v1
	v_add_f32_e32 v0, v2, v0
	v_fmac_f32_e32 v3, v12, v12
	v_add_f32_e32 v0, v3, v0
	v_add_f32_e32 v0, v24, v0
	v_mov_b32_e32 v1, v0
	v_mov_b32_e32 v154, v0
	s_nop 1
	v_permlane16_swap_b32_e32 v1, v154
	v_cvt_pk_bf16_f32 v2, v4, v5
	v_cvt_pk_bf16_f32 v3, v6, v7
	v_cvt_pk_bf16_f32 v4, v14, v15
	v_cvt_pk_bf16_f32 v5, v12, v13
	s_waitcnt lgkmcnt(0)
	v_add_f32_e32 v0, v1, v154
	v_mov_b32_e32 v1, v0
	v_mov_b32_e32 v154, v0
	s_nop 1
	v_permlane32_swap_b32_e32 v1, v154
	global_store_dwordx4 v[22:23], v[2:5], off offset:256
	s_and_saveexec_b64 s[14:15], s[6:7]
	s_cbranch_execz .LBB0_1159
	v_lshlrev_b64 v[2:3], 6, v[16:17]
	v_lshl_add_u64 v[2:3], s[20:21], 0, v[2:3]
	v_lshl_add_u64 v[2:3], s[12:13], 2, v[2:3]
	s_lshl_b32 s12, s28, 2
	s_mov_b32 s13, s36
	v_lshl_add_u64 v[2:3], v[2:3], 0, s[12:13]
	s_waitcnt lgkmcnt(0)
	v_add_f32_e32 v0, v1, v154
	global_store_dword v[2:3], v0, off
